# XG (normalised GEMM A operand of the w_in and gate_up phases) stored as contiguous 1-KiB 16x32 fragments: A-tile LDS-DMA reads 1 KiB contiguous per instruction; writers xg_pass + out/down-proj epilogu
# speedup vs baseline: 1.0288x; 1.0021x over previous
; __device__ __forceinline__ int opaque_tid(int wave_s) { int l; asm volatile("v_mbcnt_lo_u32_b32 %0, -1, 0\n\tv_mbcnt_hi_u32_b32 %0, -1, %0" : "=v"(l)); return (wave_s << 6) | l; }
; __device__ __forceinline__ unsigned cvtpk(float lo, float hi) { unsigned r; asm volatile("v_cvt_pk_bf16_f32 %0, %1, %2" : "=v"(r) : "v"(lo), "v"(hi)); return r; }
; __device__ __forceinline__ void xg_pass(const float* x, const float* nw, const float* sc, bf16_t* XGp, bf16_t* X16p, unsigned long long* ssq, int vcu, int ngw, const int wave_s) {
;     const int tid_ = opaque_tid(wave_s), lane = tid_ & 63, gw = vcu * NWAVES + (tid_ >> 6);
;     f32x4 wv[4];
; #pragma unroll
;     for (int j = 0; j < 4; ++j) wv[j] = *(const f32x4*)(nw + 4 * lane + 256 * j);
;     for (int m0 = 2 * gw; m0 < MTOK; m0 += 2 * ngw) {
;         const int b = m0 >> 12;
;         f32x4 v[2][4], scv[4];
; #pragma unroll
;         for (int i = 0; i < 2; ++i)
; #pragma unroll
;             for (int j = 0; j < 4; ++j) v[i][j] = ((const f32x4*)(x + (size_t)(m0 + i) * DM) + lane)[64 * j];
; #pragma unroll
;         for (int j = 0; j < 4; ++j) scv[j] = *(const f32x4*)(sc + (size_t)b * NMOD + 4 * lane + 256 * j);
; #pragma unroll
;         for (int i = 0; i < 2; ++i) {
;             const int m = m0 + i; float s = 0.f;
; #pragma unroll
;             for (int j = 0; j < 4; ++j) s += (v[i][j].x * v[i][j].x + v[i][j].y * v[i][j].y) + (v[i][j].z * v[i][j].z + v[i][j].w * v[i][j].w);
;             s = wave_sum(s, lane);
;             if (lane == 0) ssq[m] = (unsigned long long)(s * 16777216.0f);
;             unsigned long long* o8 = (unsigned long long*)(XGp + (size_t)m * DM) + lane;
;             unsigned long long* x8 = (unsigned long long*)(X16p + (size_t)m * DM) + lane;
; #pragma unroll
;             for (int j = 0; j < 4; ++j) {
;                 const f32x4 h = v[i][j] * wv[j] * (scv[j] + 1.0f);
;                 o8[64 * j] = (unsigned long long)cvtpk(h.x, h.y) | ((unsigned long long)cvtpk(h.z, h.w) << 32);
;                 x8[64 * j] = (unsigned long long)cvtpk(v[i][j].x, v[i][j].y) | ((unsigned long long)cvtpk(v[i][j].z, v[i][j].w) << 32);
;             }
;         }
;     }
; }
.LBB0_348:
	v_mbcnt_lo_u32_b32 v0, -1, 0
	v_mbcnt_hi_u32_b32 v0, -1, v0
	s_nop 0
	v_or_b32_e32 v1, s40, v0
	v_ashrrev_i32_e32 v1, 5, v1
	v_and_b32_e32 v1, -2, v1
	v_lshl_add_u32 v64, s8, 4, v1
	s_mov_b32 s8, 0x10000
	v_cmp_gt_i32_e32 vcc, s8, v64
	s_and_saveexec_b64 s[8:9], vcc
	s_cbranch_execz .LBB0_355
	v_and_b32_e32 v20, 63, v0
	v_lshlrev_b32_e32 v16, 4, v20
	s_waitcnt lgkmcnt(0)
	global_load_dwordx4 v[0:3], v16, s[10:11]
	global_load_dwordx4 v[4:7], v16, s[10:11] offset:1024
	global_load_dwordx4 v[8:11], v16, s[10:11] offset:2048
	global_load_dwordx4 v[12:15], v16, s[10:11] offset:3072
	v_mov_b32_e32 v17, 0
	v_lshl_add_u64 v[18:19], s[2:3], 0, v[16:17]
	s_mov_b64 s[2:3], 0x6001000
	v_ashrrev_i32_e32 v65, 31, v64
	v_lshl_add_u64 v[66:67], v[18:19], 0, s[2:3]
	v_lshl_add_u64 v[18:19], v[64:65], 3, s[12:13]
	s_mov_b64 s[2:3], 0x3d000008
	v_lshl_add_u64 v[68:69], v[18:19], 0, s[2:3]
	v_lshlrev_b64 v[18:19], 11, v[64:65]
	v_lshl_add_u64 v[72:73], s[14:15], 0, v[18:19]
	v_lshl_add_u64 v[74:75], s[6:7], 0, v[18:19]
	v_lshlrev_b64 v[18:19], 12, v[64:65]
	s_lshl_b32 s10, s38, 4
	v_or_b32_e32 v18, v18, v16
	v_lshlrev_b32_e32 v21, 2, v20
	s_ashr_i32 s11, s10, 31
	v_mov_b32_e32 v71, v17
	v_lshl_add_u64 v[16:17], s[4:5], 0, v[18:19]
	s_mov_b64 s[2:3], 0x1000
	v_xor_b32_e32 v80, 4, v21
	v_xor_b32_e32 v81, 8, v21
	v_xor_b32_e32 v82, 16, v21
	v_xor_b32_e32 v83, 32, v21
	v_xor_b32_e32 v84, 64, v21
	v_xor_b32_e32 v85, 0x80, v21
	v_cmp_eq_u32_e32 vcc, 0, v20
	s_lshl_b64 s[12:13], s[10:11], 3
	v_lshlrev_b32_e32 v70, 3, v20
	s_lshl_b64 s[14:15], s[10:11], 11
	v_lshl_add_u64 v[76:77], v[16:17], 0, s[2:3]
	s_lshl_b64 s[16:17], s[10:11], 12
	s_mov_b64 s[18:19], 0
	s_mov_b32 s4, 0x35000000
	s_brev_b32 s5, 16
	s_mov_b32 s11, 0xffff
	v_and_b32_e32 v94, 15, v64
	v_mul_u32_u24_e32 v94, 0x7c0, v94
	v_bfe_u32 v95, v20, 3, 2
	v_lshlrev_b32_e32 v95, 1, v95
	v_lshrrev_b32_e32 v96, 5, v20
	v_add_u32_e32 v95, v95, v96
	v_lshlrev_b32_e32 v95, 10, v95
	v_and_b32_e32 v96, 7, v20
	v_lshl_or_b32 v95, v96, 3, v95
	v_sub_u32_e32 v94, v95, v94
	v_ashrrev_i32_e32 v95, 31, v94
	v_mov_b32_e32 v104, 0x2000
	v_mov_b32_e32 v105, 0x4000
	v_mov_b32_e32 v106, 0x6000
	v_lshrrev_b32_e32 v108, 3, v20
	v_lshlrev_b32_e32 v108, 10, v108
	v_and_b32_e32 v109, 7, v20
	v_lshl_or_b32 v108, v109, 3, v108
	v_and_b32_e32 v109, 15, v64
	v_mul_u32_u24_e32 v109, 0x7c0, v109
	v_sub_u32_e32 v108, v108, v109
	v_ashrrev_i32_e32 v109, 31, v108
	v_mov_b32_e32 v118, 0x2000
	v_mov_b32_e32 v119, 0
	v_mov_b32_e32 v120, 0x4000
	v_mov_b32_e32 v121, 0
	v_mov_b32_e32 v122, 0x6000
	v_mov_b32_e32 v123, 0
	v_mov_b32_e32 v124, 0x35000000
	v_mov_b32_e32 v125, 0
	s_branch .LBB0_351
.LBB0_350:
	s_or_b64 exec, exec, s[2:3]
	v_pk_mul_f32 v[34:35], v[0:1], v[28:29]
	v_pk_mul_f32 v[32:33], v[2:3], v[30:31]
	v_pk_mul_f32 v[34:35], v[34:35], v[78:79]
	v_pk_mul_f32 v[32:33], v[32:33], v[62:63]
	v_cvt_pk_bf16_f32 v34, v34, v35
	v_add_u32_e32 v64, s10, v64
	v_cvt_pk_bf16_f32 v35, v32, v33
	global_store_dwordx2 v[110:111], v[34:35], off offset:64
	v_cvt_pk_bf16_f32 v28, v28, v29
	v_cvt_pk_bf16_f32 v29, v30, v31
	v_pk_mul_f32 v[30:31], v[4:5], v[24:25]
	global_store_dwordx2 v[56:57], v[28:29], off offset:64
	v_pk_mul_f32 v[28:29], v[6:7], v[26:27]
	v_pk_mul_f32 v[30:31], v[30:31], v[52:53]
	v_pk_mul_f32 v[28:29], v[28:29], v[54:55]
	v_cvt_pk_bf16_f32 v30, v30, v31
	v_cmp_lt_i32_e64 s[6:7], s11, v64
	v_cvt_pk_bf16_f32 v31, v28, v29
	global_store_dwordx2 v[112:113], v[30:31], off offset:64
	v_cvt_pk_bf16_f32 v24, v24, v25
	v_cvt_pk_bf16_f32 v25, v26, v27
	v_pk_mul_f32 v[26:27], v[8:9], v[20:21]
	global_store_dwordx2 v[98:99], v[24:25], off offset:64
	v_pk_mul_f32 v[24:25], v[10:11], v[22:23]
	v_pk_mul_f32 v[26:27], v[26:27], v[44:45]
	v_pk_mul_f32 v[24:25], v[24:25], v[46:47]
	v_cvt_pk_bf16_f32 v26, v26, v27
	v_lshl_add_u64 v[68:69], v[68:69], 0, s[12:13]
	v_cvt_pk_bf16_f32 v27, v24, v25
	global_store_dwordx2 v[114:115], v[26:27], off offset:64
	v_cvt_pk_bf16_f32 v20, v20, v21
	v_cvt_pk_bf16_f32 v21, v22, v23
	v_pk_mul_f32 v[22:23], v[12:13], v[16:17]
	global_store_dwordx2 v[100:101], v[20:21], off offset:64
	v_pk_mul_f32 v[20:21], v[14:15], v[18:19]
	v_pk_mul_f32 v[22:23], v[22:23], v[38:39]
	v_lshl_add_u64 v[72:73], v[72:73], 0, s[14:15]
	v_lshl_add_u64 v[74:75], v[74:75], 0, s[14:15]
	s_or_b64 s[18:19], s[6:7], s[18:19]
	v_lshl_add_u64 v[76:77], v[76:77], 0, s[16:17]
	v_pk_mul_f32 v[20:21], v[20:21], v[36:37]
	v_cvt_pk_bf16_f32 v22, v22, v23
	s_nop 0
	v_cvt_pk_bf16_f32 v23, v20, v21
	global_store_dwordx2 v[116:117], v[22:23], off offset:64
	v_cvt_pk_bf16_f32 v16, v16, v17
	v_cvt_pk_bf16_f32 v17, v18, v19
	global_store_dwordx2 v[102:103], v[16:17], off offset:64
	s_andn2_b64 exec, exec, s[18:19]
	s_cbranch_execz .LBB0_355

; __device__ __forceinline__ unsigned cvtpk(float lo, float hi) { unsigned r; asm volatile("v_cvt_pk_bf16_f32 %0, %1, %2" : "=v"(r) : "v"(lo), "v"(hi)); return r; }
; __device__ __forceinline__ void xg_pass(const float* x, const float* nw, const float* sc, bf16_t* XGp, bf16_t* X16p, unsigned long long* ssq, int vcu, int ngw, const int wave_s) {
;     ...
;         for (int i = 0; i < 2; ++i) {
;             const int m = m0 + i; float s = 0.f;
; #pragma unroll
;             for (int j = 0; j < 4; ++j) s += (v[i][j].x * v[i][j].x + v[i][j].y * v[i][j].y) + (v[i][j].z * v[i][j].z + v[i][j].w * v[i][j].w);
;             s = wave_sum(s, lane);
;             if (lane == 0) ssq[m] = (unsigned long long)(s * 16777216.0f);
;             unsigned long long* o8 = (unsigned long long*)(XGp + (size_t)m * DM) + lane;
;             unsigned long long* x8 = (unsigned long long*)(X16p + (size_t)m * DM) + lane;
; #pragma unroll
;             for (int j = 0; j < 4; ++j) {
;                 const f32x4 h = v[i][j] * wv[j] * (scv[j] + 1.0f);
;                 o8[64 * j] = (unsigned long long)cvtpk(h.x, h.y) | ((unsigned long long)cvtpk(h.z, h.w) << 32);
;                 x8[64 * j] = (unsigned long long)cvtpk(v[i][j].x, v[i][j].y) | ((unsigned long long)cvtpk(v[i][j].z, v[i][j].w) << 32);
;             }
;         }
.LBB0_353:
	s_or_b64 exec, exec, s[2:3]
	v_pk_mul_f32 v[90:91], v[2:3], v[58:59]
	v_pk_mul_f32 v[92:93], v[0:1], v[56:57]
	v_pk_add_f32 v[62:63], v[62:63], 1.0 op_sel_hi:[1,0]
	s_waitcnt lgkmcnt(0)
	v_pk_add_f32 v[78:79], v[60:61], 1.0 op_sel_hi:[1,0]
	v_lshl_add_u64 v[86:87], v[74:75], 0, v[70:71]
	v_lshl_add_u64 v[110:111], v[74:75], 0, v[108:109]
	v_lshl_add_u64 v[110:111], v[110:111], 0, v[124:125]
	v_lshl_add_u64 v[112:113], v[110:111], 0, v[118:119]
	v_lshl_add_u64 v[114:115], v[110:111], 0, v[120:121]
	v_lshl_add_u64 v[116:117], v[110:111], 0, v[122:123]
	v_pk_mul_f32 v[60:61], v[90:91], v[62:63]
	v_pk_mul_f32 v[90:91], v[92:93], v[78:79]
	v_lshl_add_u64 v[88:89], v[72:73], 0, v[70:71]
	v_lshl_add_u64 v[96:97], v[72:73], 0, v[94:95]
	v_cvt_pk_bf16_f32 v90, v90, v91
	v_cvt_pk_bf16_f32 v91, v60, v61
	v_add_co_u32_e64 v60, s[6:7], s4, v86
	v_pk_add_f32 v[52:53], v[52:53], 1.0 op_sel_hi:[1,0]
	s_nop 0
	v_addc_co_u32_e64 v61, s[6:7], 0, v87, s[6:7]
	global_store_dwordx2 v[110:111], v[90:91], off
	v_cvt_pk_bf16_f32 v86, v56, v57
	v_add_co_u32_e64 v56, s[6:7], s5, v96
	v_cvt_pk_bf16_f32 v87, v58, v59
	v_pk_mul_f32 v[58:59], v[6:7], v[50:51]
	s_nop 0
	v_addc_co_u32_e64 v57, s[6:7], 0, v97, s[6:7]
	v_add_co_u32_e64 v98, s[6:7], v104, v56
	s_nop 1
	v_addc_co_u32_e64 v99, s[6:7], 0, v57, s[6:7]
	v_add_co_u32_e64 v100, s[6:7], v105, v56
	s_nop 1
	v_addc_co_u32_e64 v101, s[6:7], 0, v57, s[6:7]
	v_add_co_u32_e64 v102, s[6:7], v106, v56
	s_nop 1
	v_addc_co_u32_e64 v103, s[6:7], 0, v57, s[6:7]
	global_store_dwordx2 v[56:57], v[86:87], off
	v_pk_mul_f32 v[86:87], v[4:5], v[48:49]
	v_pk_add_f32 v[54:55], v[54:55], 1.0 op_sel_hi:[1,0]
	v_pk_mul_f32 v[86:87], v[86:87], v[52:53]
	v_pk_mul_f32 v[58:59], v[58:59], v[54:55]
	v_cvt_pk_bf16_f32 v86, v86, v87
	v_pk_add_f32 v[46:47], v[46:47], 1.0 op_sel_hi:[1,0]
	v_cvt_pk_bf16_f32 v87, v58, v59
	global_store_dwordx2 v[112:113], v[86:87], off
	v_cvt_pk_bf16_f32 v48, v48, v49
	v_cvt_pk_bf16_f32 v49, v50, v51
	global_store_dwordx2 v[98:99], v[48:49], off
	v_mul_f32_e32 v48, v29, v29
	v_mul_f32_e32 v49, v31, v31
	v_fmac_f32_e32 v48, v28, v28
	v_fmac_f32_e32 v49, v30, v30
	v_add_f32_e32 v48, v48, v49
	v_mul_f32_e32 v49, v25, v25
	v_mul_f32_e32 v50, v27, v27
	v_fmac_f32_e32 v49, v24, v24
	v_fmac_f32_e32 v50, v26, v26
	v_add_f32_e32 v49, v49, v50
	v_add_f32_e32 v48, v48, v49
	v_mul_f32_e32 v49, v21, v21
	v_mul_f32_e32 v50, v23, v23
	v_fmac_f32_e32 v49, v20, v20
	v_fmac_f32_e32 v50, v22, v22
	v_add_f32_e32 v49, v49, v50
	v_add_f32_e32 v48, v48, v49
	v_mul_f32_e32 v49, v17, v17
	v_mul_f32_e32 v50, v19, v19
	v_fmac_f32_e32 v49, v16, v16
	v_fmac_f32_e32 v50, v18, v18
	v_add_f32_e32 v49, v49, v50
	v_add_f32_e32 v58, v48, v49
	ds_bpermute_b32 v59, v80, v58
	v_pk_mul_f32 v[48:49], v[10:11], v[38:39]
	v_pk_mul_f32 v[50:51], v[8:9], v[36:37]
	v_pk_add_f32 v[44:45], v[44:45], 1.0 op_sel_hi:[1,0]
	v_pk_mul_f32 v[48:49], v[48:49], v[46:47]
	s_waitcnt lgkmcnt(0)
	v_add_f32_e32 v58, v58, v59
	ds_bpermute_b32 v59, v81, v58
	v_pk_mul_f32 v[50:51], v[50:51], v[44:45]
	s_nop 0
	v_cvt_pk_bf16_f32 v50, v50, v51
	v_cvt_pk_bf16_f32 v51, v48, v49
	s_waitcnt lgkmcnt(0)
	v_add_f32_e32 v48, v58, v59
	ds_bpermute_b32 v49, v82, v48
	global_store_dwordx2 v[114:115], v[50:51], off
	v_cvt_pk_bf16_f32 v36, v36, v37
	v_cvt_pk_bf16_f32 v37, v38, v39
	global_store_dwordx2 v[100:101], v[36:37], off
	s_waitcnt lgkmcnt(0)
	v_add_f32_e32 v58, v48, v49
	ds_bpermute_b32 v59, v83, v58
	v_pk_mul_f32 v[48:49], v[14:15], v[34:35]
	v_pk_mul_f32 v[50:51], v[12:13], v[32:33]
	v_pk_add_f32 v[36:37], v[42:43], 1.0 op_sel_hi:[1,0]
	v_pk_add_f32 v[38:39], v[40:41], 1.0 op_sel_hi:[1,0]
	s_waitcnt lgkmcnt(0)
	v_add_f32_e32 v58, v58, v59
	ds_bpermute_b32 v59, v84, v58
	v_pk_mul_f32 v[40:41], v[48:49], v[36:37]
	v_pk_mul_f32 v[42:43], v[50:51], v[38:39]
	s_nop 0
	v_cvt_pk_bf16_f32 v42, v42, v43
	v_cvt_pk_bf16_f32 v43, v40, v41
	s_waitcnt lgkmcnt(0)
	v_add_f32_e32 v40, v58, v59
	ds_bpermute_b32 v41, v85, v40
	global_store_dwordx2 v[116:117], v[42:43], off
	v_cvt_pk_bf16_f32 v32, v32, v33
	v_cvt_pk_bf16_f32 v33, v34, v35
	global_store_dwordx2 v[102:103], v[32:33], off
	s_and_saveexec_b64 s[2:3], vcc
	s_cbranch_execz .LBB0_350
	s_waitcnt lgkmcnt(0)
	v_add_f32_e32 v32, v40, v41
	v_mul_f32_e32 v32, 0x4b800000, v32
	v_trunc_f32_e32 v32, v32
	v_mul_f32_e32 v33, 0x2f800000, v32
	v_floor_f32_e32 v33, v33
	v_fmac_f32_e32 v32, 0xcf800000, v33
	v_cvt_u32_f32_e32 v32, v32
	v_cvt_u32_f32_e32 v33, v33
	global_store_dwordx2 v[68:69], v[32:33], off
	s_branch .LBB0_350

; __device__ __forceinline__ int opaque_tid(int wave_s) { int l; asm volatile("v_mbcnt_lo_u32_b32 %0, -1, 0\n\tv_mbcnt_hi_u32_b32 %0, -1, %0" : "=v"(l)); return (wave_s << 6) | l; }
; #define PG8_STAGE(bufoff, gbase, voff) do { _Pragma("unroll") for (int _i = 0; _i < 2; ++_i) \
;         __builtin_amdgcn_global_load_lds((const unsigned*)((const char*)(gbase) + (voff)[_i]), (PG8_LAS unsigned*)(lds + (bufoff) + ldsw + _i * 8192), 16, 0, 0); } while (0)
; #define PG8_WAIT_V(n) asm volatile("s_waitcnt vmcnt(" #n ")" ::: "memory")
; #define PG8_BAR __builtin_amdgcn_s_barrier()
; template <class Epi, class Sched, bool ALIGN_EPI = false, bool SP2 = false>
; __device__ __forceinline__ void gemm_phase(PG8_LAS unsigned char* lds, const Gemm g, const Sched& S, const Epi& E, const int wave_s) {
;     const int tid = opaque_tid(wave_s), wid = __builtin_amdgcn_readfirstlane(tid >> 6), lane = tid & 63, wr = wid >> 2, wc = wid & 3, fr = lane & 15, fq = lane >> 4;
;     const int K = g.K, nt = K / BK;
;     unsigned voffA[2], voffB[2];
; #pragma unroll
;     for (int i = 0; i < 2; ++i) { int R, C; stage_rc(tid * 16 + i * 8192, R, C); const int Rb = Epi::PERM ? ((R & ~31) + perm32(R & 31)) : R;
;         voffA[i] = (unsigned)(R * g.lda + C) * 2u; voffB[i] = (unsigned)(Rb * K + C) * 2u; }
;     const size_t kstep = (size_t)(BK * 2);
;     const size_t hstepA = (size_t)HALF * g.lda * 2, hstepB = (size_t)HALF * K * 2;
;     const size_t tstepA = 2 * hstepA, tstepB = 2 * hstepB;
;     const unsigned ldsw = (unsigned)wid * 1024u;
;     const int aoff = lds_byte(wr * 64 + fr, fq * 8), boff = lds_byte(wc * 32 + fr, fq * 8);
;     ...
;     const char* cA = (const char*)g.A + (size_t)cur.pm * tstepA; const char* cB = (const char*)g.Bt + (size_t)cur.pn * tstepB;
;     S.a_ready(cur);
;     if constexpr (SP2) {
;         PG8_STAGE(PG8_SB(0, 0), cB, voffB); PG8_STAGE(PG8_SB(0, 1), cB + hstepB, voffB); PG8_STAGE(PG8_SA(0, 0), cA, voffA); PG8_STAGE(PG8_SA(0, 1), cA + hstepA, voffA);
;         if (wr == 1) PG8_BAR;
;         PG8_WAIT_V(2); PG8_BAR;
;         PG8_STAGE(PG8_SB(1, 0), cB + kstep, voffB); PG8_STAGE(PG8_SA(1, 0), cA + kstep, voffA); PG8_STAGE(PG8_SB(1, 1), cB + hstepB + kstep, voffB);
;         PG8_WAIT_V(6); PG8_BAR;
.LBB0_409:
	s_mov_b32 s2, s28
	s_mul_hi_u32 s29, s28, 0x1e000
	s_mul_i32 s28, s28, 0x1e000
	v_writelane_b32 v255, s28, 16
	s_mov_b32 s3, s53
	s_lshl_b64 s[94:95], s[2:3], 22
	v_writelane_b32 v255, s29, 17
	v_writelane_b32 v255, s2, 18
	s_andn2_b64 vcc, exec, s[20:21]
	s_nop 0
	v_writelane_b32 v255, s3, 19
	s_lshl_b64 s[2:3], s[2:3], 19
	s_or_b32 s54, s2, 0x20000
	s_or_b32 s2, s2, 0x30000
	s_mov_b32 s55, s3
	v_writelane_b32 v255, s2, 20
	s_nop 1
	v_writelane_b32 v255, s3, 21
	s_cbranch_vccnz .LBB0_653
	v_ashrrev_i32_e32 v4, 31, v2
	v_lshrrev_b32_e32 v4, 26, v4
	v_lshlrev_b32_e32 v3, 4, v2
	v_add_u32_e32 v4, v2, v4
	v_bfe_i32 v2, v2, 27, 1
	v_lshrrev_b32_e32 v2, 22, v2
	v_add_u32_e32 v2, v3, v2
	v_and_b32_e32 v2, 0xfffffc00, v2
	v_sub_u32_e32 v2, v3, v2
	v_ashrrev_i32_e32 v10, 6, v4
	v_lshrrev_b32_e32 v4, 4, v2
	v_bitop3_b32 v2, v4, v2, 32 bitop3:0x6c
	v_ashrrev_i32_e32 v5, 31, v2
	v_lshrrev_b32_e32 v5, 26, v5
	v_add_u32_e32 v5, v2, v5
	v_lshlrev_b32_e32 v4, 3, v10
	v_ashrrev_i32_e32 v11, 6, v5
	v_and_b32_e32 v5, 0xc0, v5
	v_and_b32_e32 v4, -16, v4
	v_sub_u32_e32 v2, v2, v5
	v_mov_b32_e32 v8, 1
	v_add_u32_e32 v4, v11, v4
	v_ashrrev_i16_sdwa v2, v8, sext(v2) dst_sel:DWORD dst_unused:UNUSED_PAD src0_sel:DWORD src1_sel:BYTE_0
	v_lshlrev_b32_e32 v6, 5, v10
	v_bfe_i32 v12, v2, 0, 16
	v_lshlrev_b32_e32 v2, 1, v4
	v_lshrrev_b32_e32 v5, 2, v4
	v_and_b32_e32 v7, 3, v11
	s_mov_b32 s3, 0x1fffe0
	v_and_b32_e32 v6, 32, v6
	v_and_b32_e32 v2, 24, v2
	v_and_b32_e32 v5, 4, v5
	v_and_or_b32 v7, v4, s3, v7
	v_or3_b32 v2, v7, v5, v2
	v_add_lshl_u32 v5, v6, v12, 1
	v_lshl_add_u32 v142, v2, 11, v5
	v_add_u32_e32 v2, 0x2000, v3
	v_ashrrev_i32_e32 v3, 31, v2
	v_lshrrev_b32_e32 v3, 22, v3
	v_add_u32_e32 v3, v2, v3
	v_ashrrev_i32_e32 v13, 10, v3
	v_mul_i32_i24_e32 v3, 0x400, v13
	v_sub_u32_e32 v2, v2, v3
	v_lshrrev_b32_e32 v3, 4, v2
	v_bitop3_b32 v2, v3, v2, 32 bitop3:0x6c
	v_lshl_add_u32 v14, v4, 11, v5
	v_and_b32_e32 v250, 0xffff8000, v14
	v_bfe_u32 v251, v14, 11, 4
	v_lshl_or_b32 v250, v251, 6, v250
	v_bfe_u32 v251, v14, 6, 1
	v_lshl_or_b32 v250, v251, 10, v250
	v_and_b32_e32 v251, 63, v14
	v_or_b32_e32 v14, v250, v251
	v_mov_b32_e32 v248, 0x800
	v_mov_b32_e32 v249, 0
	v_ashrrev_i32_e32 v4, 31, v2
	v_lshrrev_b32_e32 v4, 26, v4
	s_add_u32 s44, s14, 0x35000000
	v_lshlrev_b32_e32 v3, 3, v13
	v_add_u32_e32 v4, v2, v4
	s_addc_u32 s45, s15, 0
	v_and_b32_e32 v3, -16, v3
	v_ashrrev_i32_e32 v18, 6, v4
	s_add_u32 s46, s8, s94
	v_add_u32_e32 v3, v18, v3
	v_and_b32_e32 v6, 3, v18
	s_addc_u32 s47, s9, s95
	v_and_b32_e32 v4, 0xc0, v4
	v_and_or_b32 v6, v3, s3, v6
	s_ashr_i32 s3, s30, 6
	s_ashr_i32 s13, s12, 31
	s_ashr_i32 s11, s10, 31
	s_ashr_i32 s2, s30, 8
	v_sub_u32_e32 v2, v2, v4
	s_lshl_b32 s52, s3, 10
	s_lshl_b64 s[14:15], s[12:13], 19
	s_lshl_b64 s[8:9], s[10:11], 19
	v_ashrrev_i16_sdwa v2, v8, sext(v2) dst_sel:DWORD dst_unused:UNUSED_PAD src0_sel:DWORD src1_sel:BYTE_0
	s_add_u32 s8, s46, s8
	v_lshlrev_b32_e32 v5, 5, v13
	v_bfe_i32 v19, v2, 0, 16
	v_lshlrev_b32_e32 v2, 1, v3
	v_lshrrev_b32_e32 v4, 2, v3
	s_addc_u32 s9, s47, s9
	s_add_i32 s90, s52, 0
	v_and_b32_e32 v5, 32, v5
	v_and_b32_e32 v2, 24, v2
	v_and_b32_e32 v4, 4, v4
	s_add_i32 m0, s90, 0x10000
	v_or3_b32 v2, v6, v4, v2
	v_add_lshl_u32 v4, v5, v19, 1
	global_load_lds_dwordx4 v142, s[8:9]
	s_add_i32 m0, s90, 0x12000
	v_lshl_add_u32 v146, v2, 11, v4
	s_add_u32 s20, s8, 0x40000
	global_load_lds_dwordx4 v146, s[8:9]
	s_addc_u32 s21, s9, 0
	s_add_i32 m0, s90, 0x14000
	v_lshl_add_u32 v144, v3, 11, v4
	v_and_b32_e32 v250, 0xffff8000, v144
	v_bfe_u32 v251, v144, 11, 4
	v_lshl_or_b32 v250, v251, 6, v250
	v_bfe_u32 v251, v144, 6, 1
	v_lshl_or_b32 v250, v251, 10, v250
	v_and_b32_e32 v251, 63, v144
	v_or_b32_e32 v144, v250, v251
	global_load_lds_dwordx4 v142, s[20:21]
	s_add_i32 m0, s90, 0x16000
	s_add_u32 s14, s44, s14
	s_addc_u32 s15, s45, s15
	s_add_i32 s91, s90, 0x2000
	global_load_lds_dwordx4 v146, s[20:21]
	s_mov_b32 m0, s90
	s_add_u32 s20, s14, 0x40000
	global_load_lds_dwordx4 v14, s[14:15]
	s_mov_b32 m0, s91
	s_addc_u32 s21, s15, 0
	s_add_i32 s92, s90, 0x4000
	global_load_lds_dwordx4 v144, s[14:15]
	s_mov_b32 m0, s92
	s_add_i32 s93, s90, 0x6000
	global_load_lds_dwordx4 v14, s[20:21]
	s_mov_b32 m0, s93
	v_mov_b32_e32 v143, v1
	global_load_lds_dwordx4 v144, s[20:21]
	v_mov_b32_e32 v147, v1
	v_mov_b32_e32 v15, v1
	v_mov_b32_e32 v145, v1
	s_cmp_eq_u32 s2, 1
	v_lshl_add_u64 v[8:9], s[8:9], 0, v[142:143]
	v_lshl_add_u64 v[6:7], s[8:9], 0, v[146:147]
	v_lshl_add_u64 v[2:3], s[14:15], 0, v[14:15]
	s_cselect_b64 s[56:57], -1, 0
	s_cmp_lg_u32 s2, 1
	v_lshl_add_u64 v[4:5], s[14:15], 0, v[144:145]
	s_cbranch_scc1 .LBB0_412
	s_barrier
; #define PG8_STAGE(bufoff, gbase, voff) do { _Pragma("unroll") for (int _i = 0; _i < 2; ++_i) \
;         __builtin_amdgcn_global_load_lds((const unsigned*)((const char*)(gbase) + (voff)[_i]), (PG8_LAS unsigned*)(lds + (bufoff) + ldsw + _i * 8192), 16, 0, 0); } while (0)
; #define PG8_LDA(dst, b, h) do { _Pragma("unroll") for (int m = 0; m < 4; ++m) _Pragma("unroll") for (int k = 0; k < 2; ++k) dst[m][k] = *(const PG8_LAS bf16x8*)(lds + PG8_SA(b, h) + aoff + m * 2048 + k * 1024); } while (0)
; #define PG8_LDB(dst, b, h) do { _Pragma("unroll") for (int n = 0; n < 2; ++n) _Pragma("unroll") for (int k = 0; k < 2; ++k) dst[n][k] = *(const PG8_LAS bf16x8*)(lds + PG8_SB(b, h) + boff + n * 2048 + k * 1024); } while (0)
; #define PG8_WAIT_V(n) asm volatile("s_waitcnt vmcnt(" #n ")" ::: "memory")
; #define PG8_BAR __builtin_amdgcn_s_barrier()
; #define PG8_SCHED __builtin_amdgcn_sched_barrier(0)
; template <class Epi, class Sched, bool ALIGN_EPI = false, bool SP2 = false>
; __device__ __forceinline__ void gemm_phase(PG8_LAS unsigned char* lds, const Gemm g, const Sched& S, const Epi& E, const int wave_s) {
;     ...
;     const int aoff = lds_byte(wr * 64 + fr, fq * 8), boff = lds_byte(wc * 32 + fr, fq * 8);
;     ...
;         PG8_STAGE(PG8_SB(0, 0), cB, voffB); PG8_STAGE(PG8_SB(0, 1), cB + hstepB, voffB); PG8_STAGE(PG8_SA(0, 0), cA, voffA); PG8_STAGE(PG8_SA(0, 1), cA + hstepA, voffA);
;         if (wr == 1) PG8_BAR;
;         PG8_WAIT_V(2); PG8_BAR;
;         PG8_STAGE(PG8_SB(1, 0), cB + kstep, voffB); PG8_STAGE(PG8_SA(1, 0), cA + kstep, voffA); PG8_STAGE(PG8_SB(1, 1), cB + hstepB + kstep, voffB);
;         PG8_WAIT_V(6); PG8_BAR;
;     ...
;             PG8_LDB(B0, 0, 0); PG8_LDB(B1, 0, 1); PG8_SCHED; PG8_LDA(At, 0, 0); PG8_STAGE(PG8_SA(1, 1), a1 + hstepA, voffA);
.LBB0_412:
	s_add_u32 s22, s22, 0x10000000
	s_addc_u32 s23, s23, 0
	s_add_u32 s24, s24, 0x6200000
	s_addc_u32 s25, s25, 0
	s_add_u32 s26, s26, 0x7200000
	s_addc_u32 s27, s27, 0
	s_add_u32 s11, s18, s94
	s_addc_u32 s13, s19, s95
	v_readlane_b32 s18, v255, 16
	s_add_u32 s28, s11, 0x3d000000
	v_readlane_b32 s19, v255, 17
	s_addc_u32 s29, s13, 0
	s_lshl_b64 s[18:19], s[18:19], 2
	s_add_u32 s11, s16, s18
	s_addc_u32 s13, s17, s19
	s_add_u32 s96, s11, 0x34d00000
	s_addc_u32 s97, s13, 0
	s_lshl_b64 s[16:17], s[54:55], 3
	s_add_u32 s4, s4, s16
	s_addc_u32 s5, s5, s17
	s_add_u32 s73, s4, 0x3d000000
	s_addc_u32 s80, s5, 0
	v_readlane_b32 s4, v255, 20
	v_readlane_b32 s5, v255, 21
	s_lshl_b64 s[4:5], s[4:5], 3
	s_add_u32 s4, s6, s4
	s_addc_u32 s5, s7, s5
	s_add_u32 s81, s4, 0x3d000000
	s_addc_u32 s82, s5, 0
	s_lshl_b32 s83, s2, 6
	s_lshl_b32 s4, s2, 13
	s_lshl_b32 s2, s3, 5
	s_and_b32 s66, s2, 0x60
	s_add_i32 m0, s90, 0x18000
	v_lshl_add_u64 v[8:9], v[8:9], 0, s[58:59]
	s_lshl_b32 s5, s66, 7
	s_waitcnt vmcnt(2)
	s_barrier
	global_load_lds_dwordx4 v[8:9], off
	v_lshl_add_u64 v[6:7], v[6:7], 0, s[58:59]
	s_add_i32 m0, s90, 0x1a000
	s_add_i32 s20, s90, 0x8000
	s_add_i32 s21, s90, 0xa000
	global_load_lds_dwordx4 v[6:7], off
	v_lshl_add_u64 v[2:3], v[2:3], 0, v[248:249]
	s_mov_b32 m0, s20
	s_add_u32 s2, s8, 0x40080
	global_load_lds_dwordx4 v[2:3], off
	v_lshl_add_u64 v[2:3], v[4:5], 0, v[248:249]
	s_mov_b32 m0, s21
	s_addc_u32 s3, s9, 0
	global_load_lds_dwordx4 v[2:3], off
	s_add_i32 m0, s90, 0x1c000
	v_lshl_add_u64 v[2:3], s[2:3], 0, v[142:143]
	global_load_lds_dwordx4 v[2:3], off
	v_lshl_add_u64 v[2:3], s[2:3], 0, v[146:147]
	s_add_i32 m0, s90, 0x1e000
	s_movk_i32 s2, 0x3c0
	global_load_lds_dwordx4 v[2:3], off
	v_and_b32_e32 v2, 48, v0
	v_lshlrev_b32_e32 v3, 6, v0
	v_lshlrev_b32_e32 v0, 2, v0
	v_and_or_b32 v2, v3, s2, v2
	v_and_b32_e32 v0, 32, v0
	v_bitop3_b32 v3, v2, s4, v0 bitop3:0xde
	v_bitop3_b32 v17, s5, v2, v0 bitop3:0xf6
	v_lshlrev_b32_e32 v0, 14, v13
	v_and_b32_e32 v0, 0xffff8000, v0
	v_lshl_add_u32 v0, v18, 11, v0
	v_and_b32_e32 v2, 1, v13
	v_lshl_or_b32 v0, v2, 6, v0
	v_lshl_add_u32 v148, v19, 1, v0
	v_and_b32_e32 v250, 0xffff8000, v148
	v_bfe_u32 v251, v148, 11, 4
	v_lshl_or_b32 v250, v251, 6, v250
	v_bfe_u32 v251, v148, 6, 1
	v_lshl_or_b32 v250, v251, 10, v250
	v_and_b32_e32 v251, 63, v148
	v_or_b32_e32 v148, v250, v251
	v_lshlrev_b32_e32 v0, 14, v10
	v_and_b32_e32 v0, 0xffff8000, v0
	s_waitcnt vmcnt(6)
	v_lshl_add_u32 v0, v11, 11, v0
	v_and_b32_e32 v2, 1, v10
	s_cmpk_lt_u32 s30, 0x100
	v_lshl_or_b32 v0, v2, 6, v0
	s_cselect_b64 s[30:31], -1, 0
	v_mov_b32_e32 v149, v1
	v_lshl_add_u32 v150, v12, 1, v0
	v_and_b32_e32 v250, 0xffff8000, v150
	v_bfe_u32 v251, v150, 11, 4
	v_lshl_or_b32 v250, v251, 6, v250
	v_bfe_u32 v251, v150, 6, 1
	v_lshl_or_b32 v250, v251, 10, v250
	v_and_b32_e32 v251, 63, v150
	v_or_b32_e32 v150, v250, v251
	v_mov_b32_e32 v151, v1
	s_mov_b32 s67, 0
	v_add_u32_e32 v200, 0, v3
	s_barrier
	s_branch .LBB0_415

; __device__ __forceinline__ int opaque_tid(int wave_s) { int l; asm volatile("v_mbcnt_lo_u32_b32 %0, -1, 0\n\tv_mbcnt_hi_u32_b32 %0, -1, %0" : "=v"(l)); return (wave_s << 6) | l; }
; #define PG8_STAGE(bufoff, gbase, voff) do { _Pragma("unroll") for (int _i = 0; _i < 2; ++_i) \
;         __builtin_amdgcn_global_load_lds((const unsigned*)((const char*)(gbase) + (voff)[_i]), (PG8_LAS unsigned*)(lds + (bufoff) + ldsw + _i * 8192), 16, 0, 0); } while (0)
; #define PG8_LDA(dst, b, h) do { _Pragma("unroll") for (int m = 0; m < 4; ++m) _Pragma("unroll") for (int k = 0; k < 2; ++k) dst[m][k] = *(const PG8_LAS bf16x8*)(lds + PG8_SA(b, h) + aoff + m * 2048 + k * 1024); } while (0)
; #define PG8_SCHED __builtin_amdgcn_sched_barrier(0)
; template <class Epi, class Sched, bool ALIGN_EPI = false, bool SP2 = false>
; __device__ __forceinline__ void gemm_phase(PG8_LAS unsigned char* lds, const Gemm g, const Sched& S, const Epi& E, const int wave_s) {
;     ...
;     for (;;) {
;         const bool has_next = S.next(ui + 1, nxt);
;         const char* nA = has_next ? (const char*)g.A + (size_t)nxt.pm * tstepA : cA; const char* nB = has_next ? (const char*)g.Bt + (size_t)nxt.pn * tstepB : cB;
;         for (int t = 0; t < nt; t += 2) {
;             if constexpr (Epi::KHOOK) { if (t == 6 || t == 12) { const int l3_ = opaque_tid(wave_s) & 63; E.khook(acc, t, wr, l3_ & 15, ui & 1, lds); } }
;             const bool last = (t == nt - 2);
;             const char* a1 = cA + (size_t)(t + 1) * kstep;
;             const char* a2 = last ? nA : cA + (size_t)(t + 2) * kstep; const char* b2 = last ? nB : cB + (size_t)(t + 2) * kstep;
;             const char* a3 = a2 + kstep; const char* b3 = b2 + kstep;
;             if (last && has_next) S.a_ready(nxt);
;             if constexpr (SP2) {
;             PG8_LDB(B0, 0, 0); PG8_LDB(B1, 0, 1); PG8_SCHED; PG8_LDA(At, 0, 0); PG8_STAGE(PG8_SA(1, 1), a1 + hstepA, voffA);
;     ...
; #pragma unroll
;         for (int a = 0; a < 2; ++a)
; #pragma unroll
;             for (int b = 0; b < 2; ++b)
; #pragma unroll
;                 for (int m = 0; m < 4; ++m)
; #pragma unroll
;                     for (int n = 0; n < 2; ++n) acc[a][b][m][n] = (f32x4){0.f, 0.f, 0.f, 0.f};
;         cur = nxt; cA = nA; cB = nB; ++ui;
.LBB0_421:
	s_ashr_i32 s35, s34, 31
	s_lshl_b64 s[2:3], s[34:35], 19
	s_add_u32 s48, s44, s2
	s_addc_u32 s49, s45, s3
	s_and_b64 s[2:3], s[6:7], exec
	s_cselect_b32 s2, s49, s15
	s_cselect_b32 s3, s48, s14
	s_ashr_i32 s37, s36, 31
	s_lshl_b64 s[4:5], s[36:37], 19
	s_add_u32 s50, s46, s4
	s_addc_u32 s51, s47, s5
	s_and_b64 s[4:5], s[6:7], exec
	s_cselect_b32 s11, s51, s9
	s_cselect_b32 s13, s50, s8
	s_add_u32 s16, s8, 0x100
	s_addc_u32 s17, s9, 0
	s_add_u32 s8, s14, 0x40800
	v_mov_b32_e32 v2, 0
	s_addc_u32 s9, s15, 0
	s_mov_b32 s18, -2
	v_mov_b32_e32 v3, v2
	v_mov_b32_e32 v4, v2
	v_mov_b32_e32 v5, v2
	v_mov_b32_e32 v6, v2
	v_mov_b32_e32 v7, v2
	v_mov_b32_e32 v8, v2
	v_mov_b32_e32 v9, v2
	v_mov_b32_e32 v10, v2
	v_mov_b32_e32 v11, v2
	v_mov_b32_e32 v12, v2
	v_mov_b32_e32 v13, v2
	v_mov_b32_e32 v18, v2
	v_mov_b32_e32 v19, v2
	v_mov_b32_e32 v20, v2
	v_mov_b32_e32 v21, v2
	v_mov_b32_e32 v22, v2
	v_mov_b32_e32 v23, v2
	v_mov_b32_e32 v24, v2
	v_mov_b32_e32 v25, v2
	v_mov_b32_e32 v26, v2
	v_mov_b32_e32 v27, v2
	v_mov_b32_e32 v28, v2
	v_mov_b32_e32 v29, v2
	v_mov_b32_e32 v30, v2
	v_mov_b32_e32 v31, v2
	v_mov_b32_e32 v32, v2
	v_mov_b32_e32 v33, v2
	v_mov_b32_e32 v34, v2
	v_mov_b32_e32 v35, v2
	v_mov_b32_e32 v36, v2
	v_mov_b32_e32 v37, v2
	v_mov_b32_e32 v70, v2
	v_mov_b32_e32 v71, v2
	v_mov_b32_e32 v72, v2
	v_mov_b32_e32 v73, v2
	v_mov_b32_e32 v74, v2
	v_mov_b32_e32 v75, v2
	v_mov_b32_e32 v76, v2
	v_mov_b32_e32 v77, v2
	v_mov_b32_e32 v78, v2
	v_mov_b32_e32 v79, v2
	v_mov_b32_e32 v80, v2
	v_mov_b32_e32 v81, v2
	v_mov_b32_e32 v82, v2
	v_mov_b32_e32 v83, v2
	v_mov_b32_e32 v84, v2
	v_mov_b32_e32 v85, v2
	v_mov_b32_e32 v94, v2
	v_mov_b32_e32 v95, v2
	v_mov_b32_e32 v96, v2
	v_mov_b32_e32 v97, v2
	v_mov_b32_e32 v98, v2
	v_mov_b32_e32 v99, v2
	v_mov_b32_e32 v100, v2
	v_mov_b32_e32 v101, v2
	v_mov_b32_e32 v102, v2
	v_mov_b32_e32 v103, v2
	v_mov_b32_e32 v104, v2
	v_mov_b32_e32 v105, v2
	v_mov_b32_e32 v106, v2
	v_mov_b32_e32 v107, v2
	v_mov_b32_e32 v108, v2
	v_mov_b32_e32 v109, v2
	v_mov_b32_e32 v38, v2
	v_mov_b32_e32 v39, v2
	v_mov_b32_e32 v40, v2
	v_mov_b32_e32 v41, v2
	v_mov_b32_e32 v42, v2
	v_mov_b32_e32 v43, v2
	v_mov_b32_e32 v44, v2
	v_mov_b32_e32 v45, v2
	v_mov_b32_e32 v46, v2
	v_mov_b32_e32 v47, v2
	v_mov_b32_e32 v48, v2
	v_mov_b32_e32 v49, v2
	v_mov_b32_e32 v50, v2
	v_mov_b32_e32 v51, v2
	v_mov_b32_e32 v52, v2
	v_mov_b32_e32 v53, v2
	v_mov_b32_e32 v54, v2
	v_mov_b32_e32 v55, v2
	v_mov_b32_e32 v56, v2
	v_mov_b32_e32 v57, v2
	v_mov_b32_e32 v58, v2
	v_mov_b32_e32 v59, v2
	v_mov_b32_e32 v60, v2
	v_mov_b32_e32 v61, v2
	v_mov_b32_e32 v62, v2
	v_mov_b32_e32 v63, v2
	v_mov_b32_e32 v64, v2
	v_mov_b32_e32 v65, v2
	v_mov_b32_e32 v66, v2
	v_mov_b32_e32 v67, v2
	v_mov_b32_e32 v68, v2
	v_mov_b32_e32 v69, v2
	v_mov_b32_e32 v110, v2
	v_mov_b32_e32 v111, v2
	v_mov_b32_e32 v112, v2
	v_mov_b32_e32 v113, v2
	v_mov_b32_e32 v114, v2
	v_mov_b32_e32 v115, v2
	v_mov_b32_e32 v116, v2
	v_mov_b32_e32 v117, v2
	v_mov_b32_e32 v118, v2
	v_mov_b32_e32 v119, v2
	v_mov_b32_e32 v120, v2
	v_mov_b32_e32 v121, v2
	v_mov_b32_e32 v122, v2
	v_mov_b32_e32 v123, v2
	v_mov_b32_e32 v124, v2
	v_mov_b32_e32 v125, v2
	v_mov_b32_e32 v126, v2
	v_mov_b32_e32 v127, v2
	v_mov_b32_e32 v128, v2
	v_mov_b32_e32 v129, v2
	v_mov_b32_e32 v130, v2
	v_mov_b32_e32 v131, v2
	v_mov_b32_e32 v132, v2
	v_mov_b32_e32 v133, v2
	v_mov_b32_e32 v134, v2
	v_mov_b32_e32 v135, v2
	v_mov_b32_e32 v136, v2
	v_mov_b32_e32 v137, v2
	v_mov_b32_e32 v138, v2
	v_mov_b32_e32 v139, v2
	v_mov_b32_e32 v140, v2
	v_mov_b32_e32 v141, v2
.LBB0_422:
	s_add_u32 s4, s8, 0xfffc0800
	s_addc_u32 s5, s9, -1
	s_add_i32 s19, 0, 0x10000
	s_cmp_eq_u32 s18, 12
	s_cselect_b32 s15, s2, s5
	s_cselect_b32 s14, s3, s4
	v_add_u32_e32 v0, s19, v17
	s_cselect_b32 s5, s11, s17
	s_cselect_b32 s4, s13, s16
	s_add_i32 s35, 0, 0x14000
	ds_read_b128 v[86:89], v0
	ds_read_b128 v[90:93], v0 offset:1024
	ds_read_b128 v[152:155], v0 offset:2048
	ds_read_b128 v[156:159], v0 offset:3072
	v_add_u32_e32 v0, s35, v17
	ds_read_b128 v[160:163], v0
	ds_read_b128 v[164:167], v0 offset:1024
	ds_read_b128 v[168:171], v0 offset:2048
	ds_read_b128 v[172:175], v0 offset:3072
	v_lshl_add_u64 v[176:177], s[8:9], 0, v[150:151]
	s_add_i32 m0, s90, 0xc000
	ds_read_b128 v[194:197], v200
	ds_read_b128 v[202:205], v200 offset:1024
	ds_read_b128 v[206:209], v200 offset:2048
	ds_read_b128 v[210:213], v200 offset:3072
	ds_read_b128 v[214:217], v200 offset:4096
	ds_read_b128 v[228:231], v200 offset:5120
	ds_read_b128 v[232:235], v200 offset:6144
	ds_read_b128 v[236:239], v200 offset:7168
	global_load_lds_dwordx4 v[176:177], off
	v_lshl_add_u64 v[176:177], s[8:9], 0, v[148:149]
	s_add_i32 m0, s90, 0xe000
	s_nop 0
	global_load_lds_dwordx4 v[176:177], off
	s_waitcnt vmcnt(8)
	s_waitcnt lgkmcnt(0)
	s_barrier
; #define PG8_STAGE(bufoff, gbase, voff) do { _Pragma("unroll") for (int _i = 0; _i < 2; ++_i) \
;         __builtin_amdgcn_global_load_lds((const unsigned*)((const char*)(gbase) + (voff)[_i]), (PG8_LAS unsigned*)(lds + (bufoff) + ldsw + _i * 8192), 16, 0, 0); } while (0)
; #define PG8_LDA(dst, b, h) do { _Pragma("unroll") for (int m = 0; m < 4; ++m) _Pragma("unroll") for (int k = 0; k < 2; ++k) dst[m][k] = *(const PG8_LAS bf16x8*)(lds + PG8_SA(b, h) + aoff + m * 2048 + k * 1024); } while (0)
; #define PG8_LDB(dst, b, h) do { _Pragma("unroll") for (int n = 0; n < 2; ++n) _Pragma("unroll") for (int k = 0; k < 2; ++k) dst[n][k] = *(const PG8_LAS bf16x8*)(lds + PG8_SB(b, h) + boff + n * 2048 + k * 1024); } while (0)
; #define PG8_MMA(ai, bj, At, Bt) do { __builtin_amdgcn_s_setprio(1); _Pragma("unroll") for (int m = 0; m < 4; ++m) _Pragma("unroll") for (int n = 0; n < 2; ++n) _Pragma("unroll") for (int k = 0; k < 2; ++k) \
;         acc[ai][bj][m][n] = __builtin_amdgcn_mfma_f32_16x16x32_bf16(Bt[n][k], At[m][k], acc[ai][bj][m][n], 0, 0, 0); __builtin_amdgcn_s_setprio(0); } while (0)
; #define PG8_WAIT_V(n) asm volatile("s_waitcnt vmcnt(" #n ")" ::: "memory")
; #define PG8_WAIT_L(n) asm volatile("s_waitcnt lgkmcnt(" #n ")" ::: "memory")
; #define PG8_BAR __builtin_amdgcn_s_barrier()
; #define PG8_SCHED __builtin_amdgcn_sched_barrier(0)
; template <class Epi, class Sched, bool ALIGN_EPI = false, bool SP2 = false>
; __device__ __forceinline__ void gemm_phase(PG8_LAS unsigned char* lds, const Gemm g, const Sched& S, const Epi& E, const int wave_s) {
;     ...
;             PG8_LDB(B0, 0, 0); PG8_LDB(B1, 0, 1); PG8_SCHED; PG8_LDA(At, 0, 0); PG8_STAGE(PG8_SA(1, 1), a1 + hstepA, voffA);
;             PG8_WAIT_V(8); PG8_WAIT_L(0); PG8_BAR; PG8_MMA(0, 0, At, B0); PG8_MMA(0, 1, At, B1); PG8_BAR; PG8_SCHED;
;             PG8_LDA(At, 0, 1); PG8_STAGE(PG8_SB(0, 0), b2, voffB); PG8_STAGE(PG8_SB(0, 1), b2 + hstepB, voffB); PG8_STAGE(PG8_SA(0, 0), a2, voffA);
;             PG8_WAIT_V(8); PG8_WAIT_L(0); PG8_BAR; PG8_MMA(1, 0, At, B0); PG8_MMA(1, 1, At, B1); PG8_BAR; PG8_SCHED;
;             PG8_LDB(B0, 1, 0); PG8_LDB(B1, 1, 1); PG8_SCHED; PG8_LDA(At, 1, 0); PG8_STAGE(PG8_SA(0, 1), a2 + hstepA, voffA);
	s_setprio 1
	s_waitcnt lgkmcnt(0)
	v_mfma_f32_16x16x32_bf16 v[138:141], v[86:89], v[194:197], v[138:141]
	v_mfma_f32_16x16x32_bf16 v[134:137], v[152:155], v[194:197], v[134:137]
	v_mfma_f32_16x16x32_bf16 v[130:133], v[86:89], v[206:209], v[130:133]
	v_mfma_f32_16x16x32_bf16 v[126:129], v[152:155], v[206:209], v[126:129]
	v_mfma_f32_16x16x32_bf16 v[122:125], v[86:89], v[214:217], v[122:125]
	v_mfma_f32_16x16x32_bf16 v[118:121], v[152:155], v[214:217], v[118:121]
	v_mfma_f32_16x16x32_bf16 v[114:117], v[86:89], v[232:235], v[114:117]
	v_mfma_f32_16x16x32_bf16 v[110:113], v[152:155], v[232:235], v[110:113]
	v_mfma_f32_16x16x32_bf16 v[138:141], v[90:93], v[202:205], v[138:141]
	v_mfma_f32_16x16x32_bf16 v[134:137], v[156:159], v[202:205], v[134:137]
	v_mfma_f32_16x16x32_bf16 v[130:133], v[90:93], v[210:213], v[130:133]
	v_mfma_f32_16x16x32_bf16 v[126:129], v[156:159], v[210:213], v[126:129]
	v_mfma_f32_16x16x32_bf16 v[122:125], v[90:93], v[228:231], v[122:125]
	v_mfma_f32_16x16x32_bf16 v[118:121], v[156:159], v[228:231], v[118:121]
	v_mfma_f32_16x16x32_bf16 v[114:117], v[90:93], v[236:239], v[114:117]
	v_mfma_f32_16x16x32_bf16 v[110:113], v[156:159], v[236:239], v[110:113]
	s_setprio 0
	s_setprio 1
	v_mfma_f32_16x16x32_bf16 v[66:69], v[160:163], v[194:197], v[66:69]
	v_mfma_f32_16x16x32_bf16 v[62:65], v[168:171], v[194:197], v[62:65]
	v_mfma_f32_16x16x32_bf16 v[58:61], v[160:163], v[206:209], v[58:61]
	v_mfma_f32_16x16x32_bf16 v[54:57], v[168:171], v[206:209], v[54:57]
	v_mfma_f32_16x16x32_bf16 v[50:53], v[160:163], v[214:217], v[50:53]
	v_mfma_f32_16x16x32_bf16 v[46:49], v[168:171], v[214:217], v[46:49]
	v_mfma_f32_16x16x32_bf16 v[42:45], v[160:163], v[232:235], v[42:45]
	v_mfma_f32_16x16x32_bf16 v[38:41], v[168:171], v[232:235], v[38:41]
	v_mfma_f32_16x16x32_bf16 v[66:69], v[164:167], v[202:205], v[66:69]
	v_mfma_f32_16x16x32_bf16 v[62:65], v[172:175], v[202:205], v[62:65]
	v_mfma_f32_16x16x32_bf16 v[58:61], v[164:167], v[210:213], v[58:61]
	v_mfma_f32_16x16x32_bf16 v[54:57], v[172:175], v[210:213], v[54:57]
	v_mfma_f32_16x16x32_bf16 v[50:53], v[164:167], v[228:231], v[50:53]
	v_mfma_f32_16x16x32_bf16 v[46:49], v[172:175], v[228:231], v[46:49]
	v_mfma_f32_16x16x32_bf16 v[42:45], v[164:167], v[236:239], v[42:45]
	v_mfma_f32_16x16x32_bf16 v[38:41], v[172:175], v[236:239], v[38:41]
	s_setprio 0
	s_barrier
	s_add_i32 s19, s19, s52
	v_lshl_add_u64 v[176:177], s[4:5], 0, v[142:143]
	s_mov_b32 m0, s19
	ds_read_b128 v[194:197], v200 offset:16384
	ds_read_b128 v[202:205], v200 offset:17408
	ds_read_b128 v[206:209], v200 offset:18432
	ds_read_b128 v[210:213], v200 offset:19456
	ds_read_b128 v[214:217], v200 offset:20480
	ds_read_b128 v[228:231], v200 offset:21504
	ds_read_b128 v[232:235], v200 offset:22528
	ds_read_b128 v[236:239], v200 offset:23552
	global_load_lds_dwordx4 v[176:177], off
	s_add_i32 m0, s19, 0x2000
	s_add_u32 s40, s4, 0x40000
	v_lshl_add_u64 v[178:179], s[4:5], 0, v[146:147]
	s_addc_u32 s41, s5, 0
	s_add_i32 s19, s35, s52
	global_load_lds_dwordx4 v[178:179], off
	v_lshl_add_u64 v[180:181], s[40:41], 0, v[142:143]
	s_mov_b32 m0, s19
	v_lshl_add_u64 v[182:183], s[14:15], 0, v[144:145]
	global_load_lds_dwordx4 v[180:181], off
	v_lshl_add_u64 v[180:181], s[40:41], 0, v[146:147]
	s_add_i32 m0, s19, 0x2000
	s_nop 0
	global_load_lds_dwordx4 v[180:181], off
	v_lshl_add_u64 v[180:181], s[14:15], 0, v[14:15]
	s_mov_b32 m0, s90
	s_nop 0
	global_load_lds_dwordx4 v[180:181], off
	s_mov_b32 m0, s91
	s_nop 0
	global_load_lds_dwordx4 v[182:183], off
	s_waitcnt vmcnt(8)
	s_waitcnt lgkmcnt(0)
	s_barrier
	s_setprio 1
	s_waitcnt lgkmcnt(0)
	v_mfma_f32_16x16x32_bf16 v[106:109], v[86:89], v[194:197], v[106:109]
	v_mfma_f32_16x16x32_bf16 v[102:105], v[152:155], v[194:197], v[102:105]
	v_mfma_f32_16x16x32_bf16 v[98:101], v[86:89], v[206:209], v[98:101]
	v_mfma_f32_16x16x32_bf16 v[94:97], v[152:155], v[206:209], v[94:97]
	v_mfma_f32_16x16x32_bf16 v[82:85], v[86:89], v[214:217], v[82:85]
	v_mfma_f32_16x16x32_bf16 v[78:81], v[152:155], v[214:217], v[78:81]
	v_mfma_f32_16x16x32_bf16 v[74:77], v[86:89], v[232:235], v[74:77]
	v_mfma_f32_16x16x32_bf16 v[70:73], v[152:155], v[232:235], v[70:73]
	v_mfma_f32_16x16x32_bf16 v[106:109], v[90:93], v[202:205], v[106:109]
	v_mfma_f32_16x16x32_bf16 v[102:105], v[156:159], v[202:205], v[102:105]
	v_mfma_f32_16x16x32_bf16 v[98:101], v[90:93], v[210:213], v[98:101]
	v_mfma_f32_16x16x32_bf16 v[94:97], v[156:159], v[210:213], v[94:97]
	v_mfma_f32_16x16x32_bf16 v[82:85], v[90:93], v[228:231], v[82:85]
	v_mfma_f32_16x16x32_bf16 v[78:81], v[156:159], v[228:231], v[78:81]
	v_mfma_f32_16x16x32_bf16 v[74:77], v[90:93], v[236:239], v[74:77]
	v_mfma_f32_16x16x32_bf16 v[70:73], v[156:159], v[236:239], v[70:73]
	s_setprio 0
	s_setprio 1
	v_mfma_f32_16x16x32_bf16 v[34:37], v[160:163], v[194:197], v[34:37]
	v_mfma_f32_16x16x32_bf16 v[30:33], v[168:171], v[194:197], v[30:33]
	v_mfma_f32_16x16x32_bf16 v[26:29], v[160:163], v[206:209], v[26:29]
	v_mfma_f32_16x16x32_bf16 v[22:25], v[168:171], v[206:209], v[22:25]
	v_mfma_f32_16x16x32_bf16 v[18:21], v[160:163], v[214:217], v[18:21]
	v_mfma_f32_16x16x32_bf16 v[10:13], v[168:171], v[214:217], v[10:13]
	v_mfma_f32_16x16x32_bf16 v[6:9], v[160:163], v[232:235], v[6:9]
	v_mfma_f32_16x16x32_bf16 v[2:5], v[168:171], v[232:235], v[2:5]
	v_mfma_f32_16x16x32_bf16 v[34:37], v[164:167], v[202:205], v[34:37]
	v_mfma_f32_16x16x32_bf16 v[30:33], v[172:175], v[202:205], v[30:33]
	v_mfma_f32_16x16x32_bf16 v[26:29], v[164:167], v[210:213], v[26:29]
	v_mfma_f32_16x16x32_bf16 v[22:25], v[172:175], v[210:213], v[22:25]
	v_mfma_f32_16x16x32_bf16 v[18:21], v[164:167], v[228:231], v[18:21]
	v_mfma_f32_16x16x32_bf16 v[10:13], v[172:175], v[228:231], v[10:13]
	v_mfma_f32_16x16x32_bf16 v[6:9], v[164:167], v[236:239], v[6:9]
	v_mfma_f32_16x16x32_bf16 v[2:5], v[172:175], v[236:239], v[2:5]
	s_setprio 0
	s_barrier
; #define PG8_STAGE(bufoff, gbase, voff) do { _Pragma("unroll") for (int _i = 0; _i < 2; ++_i) \
;         __builtin_amdgcn_global_load_lds((const unsigned*)((const char*)(gbase) + (voff)[_i]), (PG8_LAS unsigned*)(lds + (bufoff) + ldsw + _i * 8192), 16, 0, 0); } while (0)
; #define PG8_LDA(dst, b, h) do { _Pragma("unroll") for (int m = 0; m < 4; ++m) _Pragma("unroll") for (int k = 0; k < 2; ++k) dst[m][k] = *(const PG8_LAS bf16x8*)(lds + PG8_SA(b, h) + aoff + m * 2048 + k * 1024); } while (0)
; #define PG8_LDB(dst, b, h) do { _Pragma("unroll") for (int n = 0; n < 2; ++n) _Pragma("unroll") for (int k = 0; k < 2; ++k) dst[n][k] = *(const PG8_LAS bf16x8*)(lds + PG8_SB(b, h) + boff + n * 2048 + k * 1024); } while (0)
; #define PG8_MMA(ai, bj, At, Bt) do { __builtin_amdgcn_s_setprio(1); _Pragma("unroll") for (int m = 0; m < 4; ++m) _Pragma("unroll") for (int n = 0; n < 2; ++n) _Pragma("unroll") for (int k = 0; k < 2; ++k) \
;         acc[ai][bj][m][n] = __builtin_amdgcn_mfma_f32_16x16x32_bf16(Bt[n][k], At[m][k], acc[ai][bj][m][n], 0, 0, 0); __builtin_amdgcn_s_setprio(0); } while (0)
; #define PG8_WAIT_V(n) asm volatile("s_waitcnt vmcnt(" #n ")" ::: "memory")
; #define PG8_WAIT_L(n) asm volatile("s_waitcnt lgkmcnt(" #n ")" ::: "memory")
; #define PG8_BAR __builtin_amdgcn_s_barrier()
; #define PG8_SCHED __builtin_amdgcn_sched_barrier(0)
; template <class Epi, class Sched, bool ALIGN_EPI = false, bool SP2 = false>
; __device__ __forceinline__ void gemm_phase(PG8_LAS unsigned char* lds, const Gemm g, const Sched& S, const Epi& E, const int wave_s) {
;     ...
;             PG8_LDB(B0, 1, 0); PG8_LDB(B1, 1, 1); PG8_SCHED; PG8_LDA(At, 1, 0); PG8_STAGE(PG8_SA(0, 1), a2 + hstepA, voffA);
;             PG8_WAIT_V(8); PG8_WAIT_L(0); PG8_BAR; PG8_MMA(0, 0, At, B0); PG8_MMA(0, 1, At, B1); PG8_BAR; PG8_SCHED;
	s_add_i32 s19, 0, 0x18000
	v_add_u32_e32 v0, s19, v17
	s_add_i32 s35, 0, 0x1c000
	ds_read_b128 v[86:89], v0
	ds_read_b128 v[90:93], v0 offset:1024
	ds_read_b128 v[152:155], v0 offset:2048
	ds_read_b128 v[156:159], v0 offset:3072
	v_add_u32_e32 v0, s35, v17
	ds_read_b128 v[160:163], v0
	ds_read_b128 v[164:167], v0 offset:1024
	ds_read_b128 v[168:171], v0 offset:2048
	ds_read_b128 v[172:175], v0 offset:3072
	s_add_u32 s14, s14, 0x40000
	s_addc_u32 s15, s15, 0
	s_mov_b32 m0, s92
	v_lshl_add_u64 v[184:185], s[14:15], 0, v[14:15]
	ds_read_b128 v[194:197], v200 offset:32768
	ds_read_b128 v[202:205], v200 offset:33792
	ds_read_b128 v[206:209], v200 offset:34816
	ds_read_b128 v[210:213], v200 offset:35840
	ds_read_b128 v[214:217], v200 offset:36864
	ds_read_b128 v[228:231], v200 offset:37888
	ds_read_b128 v[232:235], v200 offset:38912
	ds_read_b128 v[236:239], v200 offset:39936
	global_load_lds_dwordx4 v[184:185], off
	v_lshl_add_u64 v[184:185], s[14:15], 0, v[144:145]
	s_mov_b32 m0, s93
	s_nop 0
	global_load_lds_dwordx4 v[184:185], off
	s_waitcnt vmcnt(8)
	s_waitcnt lgkmcnt(0)
	s_barrier
	s_setprio 1
	s_waitcnt lgkmcnt(0)
	v_mfma_f32_16x16x32_bf16 v[138:141], v[86:89], v[194:197], v[138:141]
	v_mfma_f32_16x16x32_bf16 v[134:137], v[152:155], v[194:197], v[134:137]
	v_mfma_f32_16x16x32_bf16 v[130:133], v[86:89], v[206:209], v[130:133]
	v_mfma_f32_16x16x32_bf16 v[126:129], v[152:155], v[206:209], v[126:129]
	v_mfma_f32_16x16x32_bf16 v[122:125], v[86:89], v[214:217], v[122:125]
	v_mfma_f32_16x16x32_bf16 v[118:121], v[152:155], v[214:217], v[118:121]
	v_mfma_f32_16x16x32_bf16 v[114:117], v[86:89], v[232:235], v[114:117]
	v_mfma_f32_16x16x32_bf16 v[110:113], v[152:155], v[232:235], v[110:113]
	v_mfma_f32_16x16x32_bf16 v[138:141], v[90:93], v[202:205], v[138:141]
	v_mfma_f32_16x16x32_bf16 v[134:137], v[156:159], v[202:205], v[134:137]
	v_mfma_f32_16x16x32_bf16 v[130:133], v[90:93], v[210:213], v[130:133]
	v_mfma_f32_16x16x32_bf16 v[126:129], v[156:159], v[210:213], v[126:129]
	v_mfma_f32_16x16x32_bf16 v[122:125], v[90:93], v[228:231], v[122:125]
	v_mfma_f32_16x16x32_bf16 v[118:121], v[156:159], v[228:231], v[118:121]
	v_mfma_f32_16x16x32_bf16 v[114:117], v[90:93], v[236:239], v[114:117]
	v_mfma_f32_16x16x32_bf16 v[110:113], v[156:159], v[236:239], v[110:113]
	s_setprio 0
	s_setprio 1
	v_mfma_f32_16x16x32_bf16 v[66:69], v[160:163], v[194:197], v[66:69]
	v_mfma_f32_16x16x32_bf16 v[62:65], v[168:171], v[194:197], v[62:65]
	v_mfma_f32_16x16x32_bf16 v[58:61], v[160:163], v[206:209], v[58:61]
	v_mfma_f32_16x16x32_bf16 v[54:57], v[168:171], v[206:209], v[54:57]
	v_mfma_f32_16x16x32_bf16 v[50:53], v[160:163], v[214:217], v[50:53]
	v_mfma_f32_16x16x32_bf16 v[46:49], v[168:171], v[214:217], v[46:49]
	v_mfma_f32_16x16x32_bf16 v[42:45], v[160:163], v[232:235], v[42:45]
	v_mfma_f32_16x16x32_bf16 v[38:41], v[168:171], v[232:235], v[38:41]
	v_mfma_f32_16x16x32_bf16 v[66:69], v[164:167], v[202:205], v[66:69]
	v_mfma_f32_16x16x32_bf16 v[62:65], v[172:175], v[202:205], v[62:65]
	v_mfma_f32_16x16x32_bf16 v[58:61], v[164:167], v[210:213], v[58:61]
	v_mfma_f32_16x16x32_bf16 v[54:57], v[172:175], v[210:213], v[54:57]
	v_mfma_f32_16x16x32_bf16 v[50:53], v[164:167], v[228:231], v[50:53]
	v_mfma_f32_16x16x32_bf16 v[46:49], v[172:175], v[228:231], v[46:49]
	v_mfma_f32_16x16x32_bf16 v[42:45], v[164:167], v[236:239], v[42:45]
	v_mfma_f32_16x16x32_bf16 v[38:41], v[172:175], v[236:239], v[38:41]
	s_setprio 0
	s_barrier
; __device__ __forceinline__ int opaque_tid(int wave_s) { int l; asm volatile("v_mbcnt_lo_u32_b32 %0, -1, 0\n\tv_mbcnt_hi_u32_b32 %0, -1, %0" : "=v"(l)); return (wave_s << 6) | l; }
; #define PG8_STAGE(bufoff, gbase, voff) do { _Pragma("unroll") for (int _i = 0; _i < 2; ++_i) \
;         __builtin_amdgcn_global_load_lds((const unsigned*)((const char*)(gbase) + (voff)[_i]), (PG8_LAS unsigned*)(lds + (bufoff) + ldsw + _i * 8192), 16, 0, 0); } while (0)
; #define PG8_WAIT_V(n) asm volatile("s_waitcnt vmcnt(" #n ")" ::: "memory")
; template <class Epi, class Sched, bool ALIGN_EPI = false, bool SP2 = false>
; __device__ __forceinline__ void gemm_phase(PG8_LAS unsigned char* lds, const Gemm g, const Sched& S, const Epi& E, const int wave_s) {
;     ...
;         for (int t = 0; t < nt; t += 2) {
;             if constexpr (Epi::KHOOK) { if (t == 6 || t == 12) { const int l3_ = opaque_tid(wave_s) & 63; E.khook(acc, t, wr, l3_ & 15, ui & 1, lds); } }
;             const bool last = (t == nt - 2);
;             const char* a1 = cA + (size_t)(t + 1) * kstep;
;             const char* a2 = last ? nA : cA + (size_t)(t + 2) * kstep; const char* b2 = last ? nB : cB + (size_t)(t + 2) * kstep;
;             const char* a3 = a2 + kstep; const char* b3 = b2 + kstep;
;             if (last && has_next) S.a_ready(nxt);
;             if constexpr (SP2) {
;             PG8_LDB(B0, 0, 0); PG8_LDB(B1, 0, 1); PG8_SCHED; PG8_LDA(At, 0, 0); PG8_STAGE(PG8_SA(1, 1), a1 + hstepA, voffA);
;             PG8_WAIT_V(8); PG8_WAIT_L(0); PG8_BAR; PG8_MMA(0, 0, At, B0); PG8_MMA(0, 1, At, B1); PG8_BAR; PG8_SCHED;
;             PG8_LDA(At, 0, 1); PG8_STAGE(PG8_SB(0, 0), b2, voffB); PG8_STAGE(PG8_SB(0, 1), b2 + hstepB, voffB); PG8_STAGE(PG8_SA(0, 0), a2, voffA);
;             PG8_WAIT_V(8); PG8_WAIT_L(0); PG8_BAR; PG8_MMA(1, 0, At, B0); PG8_MMA(1, 1, At, B1); PG8_BAR; PG8_SCHED;
;             PG8_LDB(B0, 1, 0); PG8_LDB(B1, 1, 1); PG8_SCHED; PG8_LDA(At, 1, 0); PG8_STAGE(PG8_SA(0, 1), a2 + hstepA, voffA);
;             PG8_WAIT_V(8); PG8_WAIT_L(0); PG8_BAR; PG8_MMA(0, 0, At, B0); PG8_MMA(0, 1, At, B1); PG8_BAR; PG8_SCHED;
;             PG8_LDA(At, 1, 1); PG8_STAGE(PG8_SB(1, 0), b3, voffB); PG8_STAGE(PG8_SB(1, 1), b3 + hstepB, voffB); PG8_STAGE(PG8_SA(1, 0), a3, voffA);
;             PG8_WAIT_V(8); PG8_WAIT_L(0); PG8_BAR; PG8_MMA(1, 0, At, B0); PG8_MMA(1, 1, At, B1); PG8_BAR; PG8_SCHED;
	s_add_i32 s14, s19, s52
	v_lshl_add_u64 v[176:177], v[176:177], 0, s[58:59]
	s_mov_b32 m0, s14
	ds_read_b128 v[194:197], v200 offset:49152
	ds_read_b128 v[202:205], v200 offset:50176
	ds_read_b128 v[206:209], v200 offset:51200
	ds_read_b128 v[210:213], v200 offset:52224
	ds_read_b128 v[214:217], v200 offset:53248
	ds_read_b128 v[228:231], v200 offset:54272
	ds_read_b128 v[232:235], v200 offset:55296
	ds_read_b128 v[236:239], v200 offset:56320
	global_load_lds_dwordx4 v[176:177], off
	s_add_i32 m0, s14, 0x2000
	s_add_u32 s4, s4, 0x40080
	v_lshl_add_u64 v[176:177], v[178:179], 0, s[58:59]
	s_addc_u32 s5, s5, 0
	s_add_i32 s14, s35, s52
	global_load_lds_dwordx4 v[176:177], off
	v_lshl_add_u64 v[176:177], s[4:5], 0, v[142:143]
	s_mov_b32 m0, s14
	s_nop 0
	global_load_lds_dwordx4 v[176:177], off
	v_lshl_add_u64 v[176:177], s[4:5], 0, v[146:147]
	s_add_i32 m0, s14, 0x2000
	s_nop 0
	global_load_lds_dwordx4 v[176:177], off
	v_lshl_add_u64 v[176:177], v[180:181], 0, v[248:249]
	s_mov_b32 m0, s20
	s_nop 0
	global_load_lds_dwordx4 v[176:177], off
	v_lshl_add_u64 v[176:177], v[182:183], 0, v[248:249]
	s_mov_b32 m0, s21
	s_nop 0
	global_load_lds_dwordx4 v[176:177], off
	s_waitcnt vmcnt(8)
	s_waitcnt lgkmcnt(0)
	s_barrier
	s_setprio 1
	s_waitcnt lgkmcnt(0)
	v_mfma_f32_16x16x32_bf16 v[106:109], v[86:89], v[194:197], v[106:109]
	v_mfma_f32_16x16x32_bf16 v[102:105], v[152:155], v[194:197], v[102:105]
	v_mfma_f32_16x16x32_bf16 v[98:101], v[86:89], v[206:209], v[98:101]
	v_mfma_f32_16x16x32_bf16 v[94:97], v[152:155], v[206:209], v[94:97]
	v_mfma_f32_16x16x32_bf16 v[82:85], v[86:89], v[214:217], v[82:85]
	v_mfma_f32_16x16x32_bf16 v[78:81], v[152:155], v[214:217], v[78:81]
	v_mfma_f32_16x16x32_bf16 v[74:77], v[86:89], v[232:235], v[74:77]
	v_mfma_f32_16x16x32_bf16 v[70:73], v[152:155], v[232:235], v[70:73]
	v_mfma_f32_16x16x32_bf16 v[106:109], v[90:93], v[202:205], v[106:109]
	v_mfma_f32_16x16x32_bf16 v[102:105], v[156:159], v[202:205], v[102:105]
	v_mfma_f32_16x16x32_bf16 v[98:101], v[90:93], v[210:213], v[98:101]
	v_mfma_f32_16x16x32_bf16 v[94:97], v[156:159], v[210:213], v[94:97]
	v_mfma_f32_16x16x32_bf16 v[82:85], v[90:93], v[228:231], v[82:85]
	v_mfma_f32_16x16x32_bf16 v[78:81], v[156:159], v[228:231], v[78:81]
	v_mfma_f32_16x16x32_bf16 v[74:77], v[90:93], v[236:239], v[74:77]
	v_mfma_f32_16x16x32_bf16 v[70:73], v[156:159], v[236:239], v[70:73]
	s_setprio 0
	s_setprio 1
	v_mfma_f32_16x16x32_bf16 v[34:37], v[160:163], v[194:197], v[34:37]
	v_mfma_f32_16x16x32_bf16 v[30:33], v[168:171], v[194:197], v[30:33]
	v_mfma_f32_16x16x32_bf16 v[26:29], v[160:163], v[206:209], v[26:29]
	v_mfma_f32_16x16x32_bf16 v[22:25], v[168:171], v[206:209], v[22:25]
	v_mfma_f32_16x16x32_bf16 v[18:21], v[160:163], v[214:217], v[18:21]
	v_mfma_f32_16x16x32_bf16 v[10:13], v[168:171], v[214:217], v[10:13]
	v_mfma_f32_16x16x32_bf16 v[6:9], v[160:163], v[232:235], v[6:9]
	v_mfma_f32_16x16x32_bf16 v[2:5], v[168:171], v[232:235], v[2:5]
	v_mfma_f32_16x16x32_bf16 v[34:37], v[164:167], v[202:205], v[34:37]
	v_mfma_f32_16x16x32_bf16 v[30:33], v[172:175], v[202:205], v[30:33]
	v_mfma_f32_16x16x32_bf16 v[26:29], v[164:167], v[210:213], v[26:29]
	v_mfma_f32_16x16x32_bf16 v[22:25], v[172:175], v[210:213], v[22:25]
	v_mfma_f32_16x16x32_bf16 v[18:21], v[164:167], v[228:231], v[18:21]
	v_mfma_f32_16x16x32_bf16 v[10:13], v[172:175], v[228:231], v[10:13]
	v_mfma_f32_16x16x32_bf16 v[6:9], v[164:167], v[236:239], v[6:9]
	v_mfma_f32_16x16x32_bf16 v[2:5], v[172:175], v[236:239], v[2:5]
	s_setprio 0
	s_barrier
	s_add_i32 s18, s18, 2
	s_add_u32 s16, s16, 0x100
	s_addc_u32 s17, s17, 0
	s_add_u32 s8, s8, 0x1000
	s_addc_u32 s9, s9, 0
	s_cmp_gt_u32 s18, 13
	s_cbranch_scc0 .LBB0_422
	s_and_b64 vcc, exec, s[30:31]
	s_cbranch_vccz .LBB0_425
	s_barrier

;     __device__ __forceinline__ void operator()(const f32x4 (&acc)[2][2][4][2], const Unit& u, int wr, int wc, int fr, int fq) const {
;         float rc[8];
;         if constexpr (GN) { ssq_t sc_[8];
; #pragma unroll
;             for (int i = 0; i < 8; ++i) sc_[i] = gsc[u.pm * BM + wr * 64 + fr + (i >> 2) * HALF + (i & 3) * 16];
; #pragma unroll
;             for (int i = 0; i < 8; ++i) rc[i] = 1.0f / sqrtf(ssq_val(sc_[i]) * (1.0f / 256.0f) + EPS); }
;         const int col0 = u.pn * BM + wc * 32 + 8 * fq; const int b = (u.pm * BM) >> 12;
;         const float* gp = gate + (size_t)b * NMOD + col0; const float* sp = sc + (size_t)b * NMOD + col0;
;         f32x4 g[2][2], cf[2][2];
; #pragma unroll
;         for (int bj = 0; bj < 2; ++bj) {
;             g[bj][0] = *(const f32x4*)(gp + bj * HALF); g[bj][1] = *(const f32x4*)(gp + bj * HALF + 4);
;             const f32x4 n0 = *(const f32x4*)(nw + col0 + bj * HALF), n1 = *(const f32x4*)(nw + col0 + bj * HALF + 4);
;             const f32x4 c0 = *(const f32x4*)(sp + bj * HALF), c1 = *(const f32x4*)(sp + bj * HALF + 4);
;             cf[bj][0] = n0 * (c0 + 1.0f); cf[bj][1] = n1 * (c1 + 1.0f);
;         }
; #pragma unroll
;         for (int ai = 0; ai < 2; ++ai)
; #pragma unroll
;         for (int mp = 0; mp < 4; mp += 2) {
;             u32x4 bv[2][2];
; #pragma unroll
;             for (int mm = 0; mm < 2; ++mm)
; #pragma unroll
;                 for (int bj = 0; bj < 2; ++bj)
;                     bv[mm][bj] = *(gl_u32x4*)(PG8_GCPTR(base) + (unsigned)((u.pm * BM + ai * HALF + wr * 64 + (mp + mm) * 16 + fr) * DM + col0 + bj * HALF) * 2u);
; #pragma unroll
;             for (int mm = 0; mm < 2; ++mm) {
;                 const int m = mp + mm;
;                 const int row = u.pm * BM + ai * HALF + wr * 64 + m * 16 + fr; float q = 0.f;
; #pragma unroll
;                 for (int bj = 0; bj < 2; ++bj) {
;                     const unsigned offb = (unsigned)(row * DM + col0 + bj * HALF) * 2u;
;                     const u32x4 bw = bv[mm][bj];
;                     const f32x4 b0 = (f32x4){__uint_as_float(bw.x << 16), __uint_as_float(bw.x & 0xffff0000u), __uint_as_float(bw.y << 16), __uint_as_float(bw.y & 0xffff0000u)};
;                     const f32x4 b1 = (f32x4){__uint_as_float(bw.z << 16), __uint_as_float(bw.z & 0xffff0000u), __uint_as_float(bw.w << 16), __uint_as_float(bw.w & 0xffff0000u)};
.LBB0_1087:
	s_lshl_b32 s2, s10, 8
	v_mbcnt_lo_u32_b32 v0, -1, 0
	v_mbcnt_hi_u32_b32 v0, -1, v0
	s_add_i32 s2, s2, s90
	v_and_b32_e32 v182, 15, v0
	v_or_b32_e32 v216, s2, v182
	v_ashrrev_i32_e32 v217, 31, v216
	v_lshl_add_u64 v[2:3], v[216:217], 3, s[16:17]
	global_load_dwordx2 v[70:71], v[2:3], off
	global_load_dwordx2 v[218:219], v[2:3], off offset:128
	global_load_dwordx2 v[214:215], v[2:3], off offset:256
	global_load_dwordx2 v[212:213], v[2:3], off offset:384
	global_load_dwordx2 v[210:211], v[2:3], off offset:1024
	global_load_dwordx2 v[208:209], v[2:3], off offset:1152
	global_load_dwordx2 v[206:207], v[2:3], off offset:1280
	s_nop 0
	global_load_dwordx2 v[2:3], v[2:3], off offset:1408
	v_bfe_u32 v183, v0, 4, 2
	v_lshlrev_b32_e32 v232, 11, v216
	s_waitcnt vmcnt(0) lgkmcnt(0)
	v_ffbh_u32_e32 v0, v71
	v_min_u32_e32 v0, 32, v0
	v_lshlrev_b64 v[70:71], v0, v[70:71]
	v_min_u32_e32 v70, 1, v70
	v_or_b32_e32 v70, v71, v70
	v_cvt_f32_u32_e32 v70, v70
	v_sub_u32_e32 v0, 32, v0
	v_ldexp_f32 v0, v70, v0
	v_mul_f32_e32 v0, 0x33800000, v0
	v_fmamk_f32 v0, v0, 0x3b800000, v226
	v_cmp_eq_u32_e64 s[8:9], 0, v183
	s_nop 0
	s_lshl_b32 s2, s50, 8
	v_rsq_f32_e32 v0, v0
	s_nop 0
	v_lshl_or_b32 v70, v183, 3, s2
	s_ashr_i32 s2, s10, 4
	v_or_b32_e32 v180, s91, v70
	s_mul_i32 s5, s2, 0x6000
	s_mul_hi_i32 s4, s2, 0x6000
	s_add_u32 s2, s52, s5
	v_ashrrev_i32_e32 v181, 31, v180
	s_addc_u32 s3, s83, s4
	v_lshlrev_b64 v[70:71], 2, v[180:181]
	v_lshl_add_u64 v[158:159], s[2:3], 0, v[70:71]
	s_add_u32 s2, s88, s5
	s_addc_u32 s3, s89, s4
	v_lshl_add_u64 v[174:175], s[2:3], 0, v[70:71]
	v_lshl_add_u64 v[160:161], s[20:21], 0, v[70:71]
	global_load_dwordx4 v[82:85], v[158:159], off
	global_load_dwordx4 v[78:81], v[158:159], off offset:16
	global_load_dwordx4 v[70:73], v[160:161], off offset:16
	global_load_dwordx4 v[74:77], v[160:161], off
	global_load_dwordx4 v[150:153], v[174:175], off
	global_load_dwordx4 v[154:157], v[174:175], off offset:16
	v_lshlrev_b32_e32 v230, 1, v180
	v_add_u32_e32 v231, v230, v232
	v_and_b32_e32 v240, 0xffff8000, v231
	v_bfe_u32 v241, v231, 11, 4
	v_lshl_or_b32 v240, v241, 6, v240
	v_bfe_u32 v241, v231, 9, 2
	v_lshl_or_b32 v240, v241, 13, v240
	v_bfe_u32 v241, v231, 6, 2
	v_lshl_or_b32 v240, v241, 11, v240
	v_and_b32_e32 v241, 48, v231
	v_or_b32_e32 v240, v240, v241
	v_bfe_u32 v242, v231, 6, 2
	v_lshlrev_b32_e32 v242, 10, v242
	v_sub_u32_e32 v242, v240, v242
	v_add_u32_e32 v242, 0x1000, v242
	s_movk_i32 s2, 0x80
	v_pk_mul_f32 v[146:147], v[146:147], v[0:1] op_sel_hi:[1,0]
	v_pk_mul_f32 v[148:149], v[148:149], v[0:1] op_sel_hi:[1,0]
	v_pk_mul_f32 v[142:143], v[142:143], v[0:1] op_sel_hi:[1,0]
	v_pk_mul_f32 v[144:145], v[144:145], v[0:1] op_sel_hi:[1,0]
	v_pk_mul_f32 v[138:139], v[138:139], v[0:1] op_sel_hi:[1,0]
	v_pk_mul_f32 v[140:141], v[140:141], v[0:1] op_sel_hi:[1,0]
	v_pk_mul_f32 v[134:135], v[134:135], v[0:1] op_sel_hi:[1,0]
	v_pk_mul_f32 v[136:137], v[136:137], v[0:1] op_sel_hi:[1,0]
	s_waitcnt vmcnt(0) lgkmcnt(0)
	v_pk_add_f32 v[152:153], v[152:153], 1.0 op_sel_hi:[1,0]
	v_pk_add_f32 v[150:151], v[150:151], 1.0 op_sel_hi:[1,0]
	v_pk_mul_f32 v[200:201], v[76:77], v[152:153]
	v_pk_mul_f32 v[204:205], v[74:75], v[150:151]
	v_pk_add_f32 v[74:75], v[156:157], 1.0 op_sel_hi:[1,0]
	v_pk_add_f32 v[76:77], v[154:155], 1.0 op_sel_hi:[1,0]
	v_pk_mul_f32 v[198:199], v[72:73], v[74:75]
	v_pk_mul_f32 v[202:203], v[70:71], v[76:77]
	global_load_dwordx4 v[74:77], v[158:159], off offset:512
	global_load_dwordx4 v[70:73], v[158:159], off offset:528
	global_load_dwordx4 v[150:153], v[160:161], off offset:528
	global_load_dwordx4 v[154:157], v[160:161], off offset:512
	s_nop 0
	global_load_dwordx4 v[158:161], v[174:175], off offset:512
	global_load_dwordx4 v[176:179], v[174:175], off offset:528
	s_waitcnt vmcnt(0) lgkmcnt(0)
	v_pk_add_f32 v[160:161], v[160:161], 1.0 op_sel_hi:[1,0]
	v_pk_add_f32 v[158:159], v[158:159], 1.0 op_sel_hi:[1,0]
	v_pk_mul_f32 v[196:197], v[156:157], v[160:161]
	v_pk_mul_f32 v[174:175], v[154:155], v[158:159]
	v_pk_add_f32 v[154:155], v[178:179], 1.0 op_sel_hi:[1,0]
	global_load_dwordx4 v[178:181], v240, s[22:23] nt
	global_load_dwordx4 v[158:161], v240, s[22:23] offset:1024 nt
	v_pk_add_f32 v[156:157], v[176:177], 1.0 op_sel_hi:[1,0]
	v_pk_mul_f32 v[176:177], v[152:153], v[154:155]
	v_pk_mul_f32 v[194:195], v[150:151], v[156:157]
	v_lshlrev_b32_e32 v150, 6, v183
	v_lshlrev_b32_e32 v151, 2, v182
	v_bitop3_b32 v229, v150, 64, v151 bitop3:0x36
	v_bitop3_b32 v228, v150, s2, v151 bitop3:0x36
	v_add_u32_e32 v150, 0x8000, v240
	global_load_dwordx4 v[154:157], v150, s[22:23] nt
	s_nop 0
	global_load_dwordx4 v[150:153], v150, s[22:23] offset:1024 nt
	s_waitcnt vmcnt(3)
	v_lshlrev_b32_e32 v182, 16, v178
	v_and_b32_e32 v183, 0xffff0000, v178
	v_lshlrev_b32_e32 v178, 16, v179
	v_and_b32_e32 v179, 0xffff0000, v179
	v_lshlrev_b32_e32 v184, 16, v180
	v_and_b32_e32 v185, 0xffff0000, v180
	v_lshlrev_b32_e32 v180, 16, v181
	v_and_b32_e32 v181, 0xffff0000, v181
	v_pk_fma_f32 v[148:149], v[84:85], v[148:149], v[178:179]
	v_pk_fma_f32 v[146:147], v[82:83], v[146:147], v[182:183]
	v_pk_fma_f32 v[178:179], v[80:81], v[144:145], v[180:181]
	v_pk_fma_f32 v[180:181], v[78:79], v[142:143], v[184:185]
	v_cvt_pk_bf16_f32 v142, v146, v147
	v_cvt_pk_bf16_f32 v143, v148, v149
	v_pk_mul_f32 v[182:183], v[198:199], v[178:179]
	v_cvt_pk_bf16_f32 v144, v180, v181
	v_cvt_pk_bf16_f32 v145, v178, v179
	global_store_dwordx4 v240, v[142:145], s[24:25] nt
	v_pk_mul_f32 v[184:185], v[202:203], v[180:181]
	s_nop 0
	v_pk_mul_f32 v[142:143], v[204:205], v[146:147]
	v_pk_mul_f32 v[144:145], v[200:201], v[148:149]
	v_cvt_pk_bf16_f32 v142, v142, v143
	s_nop 0
	v_cvt_pk_bf16_f32 v143, v144, v145
	v_cvt_pk_bf16_f32 v144, v184, v185
	v_cvt_pk_bf16_f32 v145, v182, v183
	global_store_dwordx4 v242, v[142:145], s[26:27] offset:-4096
	s_nop 1
	v_mul_f32_e32 v142, v147, v147
	v_mul_f32_e32 v143, v149, v149
	v_fmac_f32_e32 v142, v146, v146
	v_fmac_f32_e32 v143, v148, v148
	v_add_f32_e32 v142, v142, v143
	v_mul_f32_e32 v143, v181, v181
	v_fmac_f32_e32 v143, v180, v180
	v_add_f32_e32 v142, v143, v142
	v_mul_f32_e32 v143, v179, v179
	v_fmac_f32_e32 v143, v178, v178
	v_add_f32_e32 v178, v143, v142
	s_waitcnt vmcnt(4)
; __device__ __forceinline__ unsigned cvt_pk_bf16(float lo, float hi) { unsigned r; asm volatile("v_cvt_pk_bf16_f32 %0, %1, %2" : "=v"(r) : "v"(lo), "v"(hi)); return r; }
; #define PG8_GPTR(p) ((__attribute__((address_space(1))) char*)(p))
;     __device__ __forceinline__ void operator()(const f32x4 (&acc)[2][2][4][2], const Unit& u, int wr, int wc, int fr, int fq) const {
;     ...
;             for (int mm = 0; mm < 2; ++mm) {
;                 const int m = mp + mm;
;                 const int row = u.pm * BM + ai * HALF + wr * 64 + m * 16 + fr; float q = 0.f;
; #pragma unroll
;                 for (int bj = 0; bj < 2; ++bj) {
;                     const unsigned offb = (unsigned)(row * DM + col0 + bj * HALF) * 2u;
;                     const u32x4 bw = bv[mm][bj];
;                     const f32x4 b0 = (f32x4){__uint_as_float(bw.x << 16), __uint_as_float(bw.x & 0xffff0000u), __uint_as_float(bw.y << 16), __uint_as_float(bw.y & 0xffff0000u)};
;                     const f32x4 b1 = (f32x4){__uint_as_float(bw.z << 16), __uint_as_float(bw.z & 0xffff0000u), __uint_as_float(bw.w << 16), __uint_as_float(bw.w & 0xffff0000u)};
;                     f32x4 a0 = acc[ai][bj][m][0], a1 = acc[ai][bj][m][1]; if constexpr (GN) { a0 *= rc[ai * 4 + m]; a1 *= rc[ai * 4 + m]; }
;                     const f32x4 o0 = b0 + g[bj][0] * a0, o1 = b1 + g[bj][1] * a1;
;                     u32x4 wo; wo.x = cvt_pk_bf16(o0[0], o0[1]); wo.y = cvt_pk_bf16(o0[2], o0[3]); wo.z = cvt_pk_bf16(o1[0], o1[1]); wo.w = cvt_pk_bf16(o1[2], o1[3]);
;                     *(gs_u32x4*)(PG8_GPTR(out) + offb) = wo;
;                     if (xg) {
;                         const f32x4 h0 = o0 * cf[bj][0], h1 = o1 * cf[bj][1];
;                         u32x4 w; w.x = cvt_pk_bf16(h0[0], h0[1]); w.y = cvt_pk_bf16(h0[2], h0[3]); w.z = cvt_pk_bf16(h1[0], h1[1]); w.w = cvt_pk_bf16(h1[2], h1[3]);
;                         *(gs_u32x4*)(PG8_GPTR(xg) + offb) = w;
;                         q += (o0[0] * o0[0] + o0[1] * o0[1]) + (o0[2] * o0[2] + o0[3] * o0[3]) + (o1[0] * o1[0] + o1[1] * o1[1]) + (o1[2] * o1[2] + o1[3] * o1[3]);
;                     }
;                 }
;                 if (xg) ssq_put(ssq, row, q, fr, fq);
;             }
	v_lshlrev_b32_e32 v142, 16, v158
	v_and_b32_e32 v143, 0xffff0000, v158
	v_lshlrev_b32_e32 v144, 16, v159
	v_and_b32_e32 v145, 0xffff0000, v159
	v_lshlrev_b32_e32 v146, 16, v160
	v_and_b32_e32 v147, 0xffff0000, v160
	v_lshlrev_b32_e32 v148, 16, v161
	v_and_b32_e32 v149, 0xffff0000, v161
	v_pk_fma_f32 v[140:141], v[140:141], v[76:77], v[144:145]
	v_pk_fma_f32 v[138:139], v[138:139], v[74:75], v[142:143]
	v_pk_fma_f32 v[142:143], v[136:137], v[72:73], v[148:149]
	v_pk_fma_f32 v[144:145], v[134:135], v[70:71], v[146:147]
	v_cvt_pk_bf16_f32 v134, v138, v139
	v_cvt_pk_bf16_f32 v135, v140, v141
	v_pk_mul_f32 v[146:147], v[176:177], v[142:143]
	v_cvt_pk_bf16_f32 v136, v144, v145
	v_cvt_pk_bf16_f32 v137, v142, v143
	global_store_dwordx4 v240, v[134:137], s[24:25] offset:1024 nt
	v_pk_mul_f32 v[148:149], v[194:195], v[144:145]
	v_mul_f32_e32 v0, v143, v143
	v_pk_mul_f32 v[136:137], v[196:197], v[140:141]
	v_pk_mul_f32 v[134:135], v[174:175], v[138:139]
	v_fmac_f32_e32 v0, v142, v142
	v_cvt_pk_bf16_f32 v134, v134, v135
	v_cvt_pk_bf16_f32 v135, v136, v137
	v_cvt_pk_bf16_f32 v136, v148, v149
	v_cvt_pk_bf16_f32 v137, v146, v147
	global_store_dwordx4 v242, v[134:137], s[26:27]
	s_nop 1
	v_mul_f32_e32 v135, v139, v139
	v_mul_f32_e32 v136, v141, v141
	v_mul_f32_e32 v134, v145, v145
	v_fmac_f32_e32 v135, v138, v138
	v_fmac_f32_e32 v136, v140, v140
	v_fmac_f32_e32 v134, v144, v144
	v_add_f32_e32 v135, v135, v136
	v_add_f32_e32 v134, v134, v135
	v_add_f32_e32 v0, v0, v134
	v_add_f32_e32 v0, v178, v0
	ds_bpermute_b32 v134, v229, v0
	s_waitcnt lgkmcnt(0)
	v_add_f32_e32 v0, v0, v134
	ds_bpermute_b32 v136, v228, v0
	v_lshl_add_u64 v[134:135], v[216:217], 3, s[28:29]
	s_and_saveexec_b64 s[2:3], s[8:9]
	s_cbranch_execz .LBB0_1089
	s_waitcnt lgkmcnt(0)
	v_add_f32_e32 v0, v0, v136
	v_mul_f32_e32 v0, 0x4b800000, v0
	v_trunc_f32_e32 v0, v0
	v_mul_f32_e32 v136, 0x2f800000, v0
	v_floor_f32_e32 v137, v136
	v_fmac_f32_e32 v0, 0xcf800000, v137
	v_cvt_u32_f32_e32 v136, v0
	v_cvt_u32_f32_e32 v137, v137
	global_atomic_add_x2 v[134:135], v[136:137], off
.LBB0_1089:
	s_or_b64 exec, exec, s[2:3]
	v_ffbh_u32_e32 v0, v219
	v_min_u32_e32 v0, 32, v0
	s_waitcnt lgkmcnt(0)
	v_lshlrev_b64 v[136:137], v0, v[218:219]
	v_min_u32_e32 v136, 1, v136
	v_or_b32_e32 v136, v137, v136
	v_cvt_f32_u32_e32 v136, v136
	v_sub_u32_e32 v0, 32, v0
	s_waitcnt vmcnt(0)
	v_and_b32_e32 v141, 0xffff0000, v155
	v_lshlrev_b32_e32 v142, 16, v156
	v_ldexp_f32 v0, v136, v0
	v_mul_f32_e32 v0, 0x33800000, v0
	v_fmamk_f32 v0, v0, 0x3b800000, v226
	v_and_b32_e32 v143, 0xffff0000, v156
	v_lshlrev_b32_e32 v144, 16, v157
	v_and_b32_e32 v145, 0xffff0000, v157
	s_mov_b32 s2, 0x8000
	v_rsq_f32_e32 v0, v0
	s_nop 0
	v_lshlrev_b32_e32 v136, 11, v216
	v_lshlrev_b32_e32 v138, 16, v154
	v_and_b32_e32 v139, 0xffff0000, v154
	v_lshlrev_b32_e32 v140, 16, v155
	v_pk_mul_f32 v[130:131], v[130:131], v[0:1] op_sel_hi:[1,0]
	v_pk_mul_f32 v[132:133], v[132:133], v[0:1] op_sel_hi:[1,0]
	v_pk_mul_f32 v[126:127], v[126:127], v[0:1] op_sel_hi:[1,0]
	v_add3_u32 v137, v230, v136, s2
	v_add_u32_e32 v241, s2, v240
	v_add_u32_e32 v243, s2, v242
	v_pk_mul_f32 v[128:129], v[128:129], v[0:1] op_sel_hi:[1,0]
	v_pk_fma_f32 v[132:133], v[84:85], v[132:133], v[140:141]
	v_pk_fma_f32 v[130:131], v[82:83], v[130:131], v[138:139]
	v_pk_fma_f32 v[140:141], v[78:79], v[126:127], v[142:143]
	v_cvt_pk_bf16_f32 v126, v130, v131
	v_cvt_pk_bf16_f32 v127, v132, v133
	v_pk_fma_f32 v[138:139], v[80:81], v[128:129], v[144:145]
	v_cvt_pk_bf16_f32 v128, v140, v141
	v_pk_mul_f32 v[144:145], v[202:203], v[140:141]
	v_cvt_pk_bf16_f32 v129, v138, v139
	global_store_dwordx4 v241, v[126:129], s[24:25] nt
	v_pk_mul_f32 v[142:143], v[198:199], v[138:139]
	v_pk_mul_f32 v[122:123], v[122:123], v[0:1] op_sel_hi:[1,0]
	v_pk_mul_f32 v[126:127], v[204:205], v[130:131]
	v_pk_mul_f32 v[128:129], v[200:201], v[132:133]
	v_cvt_pk_bf16_f32 v126, v126, v127
	v_pk_mul_f32 v[124:125], v[124:125], v[0:1] op_sel_hi:[1,0]
	v_cvt_pk_bf16_f32 v127, v128, v129
	v_cvt_pk_bf16_f32 v128, v144, v145
	v_cvt_pk_bf16_f32 v129, v142, v143
	global_store_dwordx4 v243, v[126:129], s[26:27] offset:-4096
	v_pk_mul_f32 v[118:119], v[118:119], v[0:1] op_sel_hi:[1,0]
	v_pk_mul_f32 v[120:121], v[120:121], v[0:1] op_sel_hi:[1,0]
	v_mul_f32_e32 v126, v131, v131
	v_mul_f32_e32 v127, v133, v133
	v_fmac_f32_e32 v126, v130, v130
	v_fmac_f32_e32 v127, v132, v132
	v_add_f32_e32 v126, v126, v127
	v_mul_f32_e32 v127, v141, v141
	v_fmac_f32_e32 v127, v140, v140
	v_add_f32_e32 v126, v127, v126
	v_mul_f32_e32 v127, v139, v139
	v_fmac_f32_e32 v127, v138, v138
	v_add_f32_e32 v138, v127, v126
	v_lshlrev_b32_e32 v126, 16, v150
	v_and_b32_e32 v127, 0xffff0000, v150
	v_lshlrev_b32_e32 v128, 16, v151
	v_and_b32_e32 v129, 0xffff0000, v151
	v_lshlrev_b32_e32 v130, 16, v152
	v_and_b32_e32 v131, 0xffff0000, v152
	v_lshlrev_b32_e32 v132, 16, v153
	v_and_b32_e32 v133, 0xffff0000, v153
	v_pk_fma_f32 v[124:125], v[124:125], v[76:77], v[128:129]
	v_pk_fma_f32 v[122:123], v[122:123], v[74:75], v[126:127]
	v_pk_fma_f32 v[126:127], v[120:121], v[72:73], v[132:133]
	v_pk_fma_f32 v[128:129], v[118:119], v[70:71], v[130:131]
	v_cvt_pk_bf16_f32 v118, v122, v123
	v_cvt_pk_bf16_f32 v119, v124, v125
	v_mul_f32_e32 v0, v127, v127
	v_cvt_pk_bf16_f32 v120, v128, v129
	v_cvt_pk_bf16_f32 v121, v126, v127
	global_store_dwordx4 v241, v[118:121], s[24:25] offset:1024 nt
	v_fmac_f32_e32 v0, v126, v126
	v_pk_mul_f32 v[130:131], v[196:197], v[124:125]
	v_mul_f32_e32 v119, v123, v123
	v_mul_f32_e32 v120, v125, v125
	v_mul_f32_e32 v118, v129, v129
	v_fmac_f32_e32 v119, v122, v122
	v_fmac_f32_e32 v120, v124, v124
	v_fmac_f32_e32 v118, v128, v128
	v_add_f32_e32 v119, v119, v120
	v_add_f32_e32 v118, v118, v119
	v_add_f32_e32 v0, v0, v118
	v_add_f32_e32 v0, v138, v0
	ds_bpermute_b32 v121, v229, v0
	v_pk_mul_f32 v[118:119], v[174:175], v[122:123]
	v_pk_mul_f32 v[122:123], v[194:195], v[128:129]
	v_cvt_pk_bf16_f32 v120, v118, v119
	v_pk_mul_f32 v[124:125], v[176:177], v[126:127]
	s_waitcnt lgkmcnt(0)
	v_add_f32_e32 v0, v0, v121
	ds_bpermute_b32 v118, v228, v0
	v_cvt_pk_bf16_f32 v121, v130, v131
	v_cvt_pk_bf16_f32 v122, v122, v123
	v_cvt_pk_bf16_f32 v123, v124, v125
	global_store_dwordx4 v243, v[120:123], s[26:27]
	s_and_saveexec_b64 s[2:3], s[8:9]
	s_cbranch_execz .LBB0_1091
	s_waitcnt lgkmcnt(0)
	v_add_f32_e32 v0, v0, v118
	v_mul_f32_e32 v0, 0x4b800000, v0
	v_trunc_f32_e32 v0, v0
	v_mul_f32_e32 v118, 0x2f800000, v0
	v_floor_f32_e32 v119, v118
	v_fmac_f32_e32 v0, 0xcf800000, v119
	v_cvt_u32_f32_e32 v118, v0
	v_cvt_u32_f32_e32 v119, v119
	global_atomic_add_x2 v[134:135], v[118:119], off offset:128
;     __device__ __forceinline__ void operator()(const f32x4 (&acc)[2][2][4][2], const Unit& u, int wr, int wc, int fr, int fq) const {
;     ...
;             for (int i = 0; i < 8; ++i) sc_[i] = gsc[u.pm * BM + wr * 64 + fr + (i >> 2) * HALF + (i & 3) * 16];
; #pragma unroll
;             for (int i = 0; i < 8; ++i) rc[i] = 1.0f / sqrtf(ssq_val(sc_[i]) * (1.0f / 256.0f) + EPS); }
;     ...
;                     bv[mm][bj] = *(gl_u32x4*)(PG8_GCPTR(base) + (unsigned)((u.pm * BM + ai * HALF + wr * 64 + (mp + mm) * 16 + fr) * DM + col0 + bj * HALF) * 2u);
; #pragma unroll
;             for (int mm = 0; mm < 2; ++mm) {
;                 const int m = mp + mm;
;                 const int row = u.pm * BM + ai * HALF + wr * 64 + m * 16 + fr; float q = 0.f;
; #pragma unroll
;                 for (int bj = 0; bj < 2; ++bj) {
;                     const unsigned offb = (unsigned)(row * DM + col0 + bj * HALF) * 2u;
;                     const u32x4 bw = bv[mm][bj];
;                     const f32x4 b0 = (f32x4){__uint_as_float(bw.x << 16), __uint_as_float(bw.x & 0xffff0000u), __uint_as_float(bw.y << 16), __uint_as_float(bw.y & 0xffff0000u)};
;                     const f32x4 b1 = (f32x4){__uint_as_float(bw.z << 16), __uint_as_float(bw.z & 0xffff0000u), __uint_as_float(bw.w << 16), __uint_as_float(bw.w & 0xffff0000u)};
;                     f32x4 a0 = acc[ai][bj][m][0], a1 = acc[ai][bj][m][1]; if constexpr (GN) { a0 *= rc[ai * 4 + m]; a1 *= rc[ai * 4 + m]; }
;                     const f32x4 o0 = b0 + g[bj][0] * a0, o1 = b1 + g[bj][1] * a1;
;                     u32x4 wo; wo.x = cvt_pk_bf16(o0[0], o0[1]); wo.y = cvt_pk_bf16(o0[2], o0[3]); wo.z = cvt_pk_bf16(o1[0], o1[1]); wo.w = cvt_pk_bf16(o1[2], o1[3]);
;                     *(gs_u32x4*)(PG8_GPTR(out) + offb) = wo;
;                     if (xg) {
;                         const f32x4 h0 = o0 * cf[bj][0], h1 = o1 * cf[bj][1];
;                         u32x4 w; w.x = cvt_pk_bf16(h0[0], h0[1]); w.y = cvt_pk_bf16(h0[2], h0[3]); w.z = cvt_pk_bf16(h1[0], h1[1]); w.w = cvt_pk_bf16(h1[2], h1[3]);
;                         *(gs_u32x4*)(PG8_GPTR(xg) + offb) = w;
;                         q += (o0[0] * o0[0] + o0[1] * o0[1]) + (o0[2] * o0[2] + o0[3] * o0[3]) + (o1[0] * o1[0] + o1[1] * o1[1]) + (o1[2] * o1[2] + o1[3] * o1[3]);
;                     }
;                 }
;                 if (xg) ssq_put(ssq, row, q, fr, fq);
.LBB0_1091:
	s_or_b64 exec, exec, s[2:3]
	v_ffbh_u32_e32 v0, v215
	v_min_u32_e32 v0, 32, v0
	s_waitcnt lgkmcnt(0)
	v_lshlrev_b64 v[118:119], v0, v[214:215]
	v_min_u32_e32 v118, 1, v118
	v_or_b32_e32 v118, v119, v118
	v_cvt_f32_u32_e32 v118, v118
	v_sub_u32_e32 v0, 32, v0
	v_ldexp_f32 v0, v118, v0
	v_mul_f32_e32 v0, 0x33800000, v0
	v_fmamk_f32 v0, v0, 0x3b800000, v226
	s_mov_b32 s2, 0x10000
	v_add3_u32 v137, v230, v136, s2
	v_add_u32_e32 v241, s2, v240
	v_add_u32_e32 v243, s2, v242
	v_rsq_f32_e32 v0, v0
	s_nop 0
	v_add_u32_e32 v118, 0x10000, v240
	global_load_dwordx4 v[130:133], v118, s[22:23] nt
	global_load_dwordx4 v[126:129], v118, s[22:23] offset:1024 nt
	v_add_u32_e32 v118, 0x18000, v240
	global_load_dwordx4 v[122:125], v118, s[22:23] nt
	s_nop 0
	global_load_dwordx4 v[118:121], v118, s[22:23] offset:1024 nt
	v_pk_mul_f32 v[114:115], v[114:115], v[0:1] op_sel_hi:[1,0]
	v_pk_mul_f32 v[116:117], v[116:117], v[0:1] op_sel_hi:[1,0]
	v_pk_mul_f32 v[110:111], v[110:111], v[0:1] op_sel_hi:[1,0]
	v_pk_mul_f32 v[112:113], v[112:113], v[0:1] op_sel_hi:[1,0]
	v_pk_mul_f32 v[106:107], v[106:107], v[0:1] op_sel_hi:[1,0]
	v_pk_mul_f32 v[108:109], v[108:109], v[0:1] op_sel_hi:[1,0]
	v_pk_mul_f32 v[102:103], v[102:103], v[0:1] op_sel_hi:[1,0]
	v_pk_mul_f32 v[104:105], v[104:105], v[0:1] op_sel_hi:[1,0]
	s_waitcnt vmcnt(0)
	v_lshlrev_b32_e32 v138, 16, v130
	v_and_b32_e32 v139, 0xffff0000, v130
	v_lshlrev_b32_e32 v130, 16, v131
	v_and_b32_e32 v131, 0xffff0000, v131
	v_lshlrev_b32_e32 v140, 16, v132
	v_and_b32_e32 v141, 0xffff0000, v132
	v_lshlrev_b32_e32 v132, 16, v133
	v_and_b32_e32 v133, 0xffff0000, v133
	v_pk_fma_f32 v[116:117], v[84:85], v[116:117], v[130:131]
	v_pk_fma_f32 v[114:115], v[82:83], v[114:115], v[138:139]
	v_pk_fma_f32 v[130:131], v[80:81], v[112:113], v[132:133]
	v_pk_fma_f32 v[132:133], v[78:79], v[110:111], v[140:141]
	v_cvt_pk_bf16_f32 v110, v114, v115
	v_cvt_pk_bf16_f32 v111, v116, v117
	v_pk_mul_f32 v[138:139], v[198:199], v[130:131]
	v_cvt_pk_bf16_f32 v112, v132, v133
	v_cvt_pk_bf16_f32 v113, v130, v131
	global_store_dwordx4 v241, v[110:113], s[24:25] nt
	v_pk_mul_f32 v[140:141], v[202:203], v[132:133]
	s_nop 0
	v_pk_mul_f32 v[110:111], v[204:205], v[114:115]
	v_pk_mul_f32 v[112:113], v[200:201], v[116:117]
	v_cvt_pk_bf16_f32 v110, v110, v111
	s_nop 0
	v_cvt_pk_bf16_f32 v111, v112, v113
	v_cvt_pk_bf16_f32 v112, v140, v141
	v_cvt_pk_bf16_f32 v113, v138, v139
	global_store_dwordx4 v243, v[110:113], s[26:27] offset:-4096
	s_nop 1
	v_mul_f32_e32 v110, v115, v115
	v_mul_f32_e32 v111, v117, v117
	v_fmac_f32_e32 v110, v114, v114
	v_fmac_f32_e32 v111, v116, v116
	v_add_f32_e32 v110, v110, v111
	v_mul_f32_e32 v111, v133, v133
	v_fmac_f32_e32 v111, v132, v132
	v_add_f32_e32 v110, v111, v110
	v_mul_f32_e32 v111, v131, v131
	v_fmac_f32_e32 v111, v130, v130
	v_add_f32_e32 v130, v111, v110
	v_lshlrev_b32_e32 v110, 16, v126
	v_and_b32_e32 v111, 0xffff0000, v126
	v_lshlrev_b32_e32 v112, 16, v127
	v_and_b32_e32 v113, 0xffff0000, v127
	v_lshlrev_b32_e32 v114, 16, v128
	v_and_b32_e32 v115, 0xffff0000, v128
	v_lshlrev_b32_e32 v116, 16, v129
	v_and_b32_e32 v117, 0xffff0000, v129
	v_pk_fma_f32 v[108:109], v[108:109], v[76:77], v[112:113]
	v_pk_fma_f32 v[106:107], v[106:107], v[74:75], v[110:111]
	v_pk_fma_f32 v[110:111], v[104:105], v[72:73], v[116:117]
	v_pk_fma_f32 v[112:113], v[102:103], v[70:71], v[114:115]
	v_cvt_pk_bf16_f32 v102, v106, v107
	v_cvt_pk_bf16_f32 v103, v108, v109
	v_pk_mul_f32 v[114:115], v[176:177], v[110:111]
	v_cvt_pk_bf16_f32 v104, v112, v113
	v_cvt_pk_bf16_f32 v105, v110, v111
	global_store_dwordx4 v241, v[102:105], s[24:25] offset:1024 nt
	v_pk_mul_f32 v[116:117], v[194:195], v[112:113]
	v_mul_f32_e32 v0, v111, v111
	v_pk_mul_f32 v[104:105], v[196:197], v[108:109]
	v_pk_mul_f32 v[102:103], v[174:175], v[106:107]
	v_fmac_f32_e32 v0, v110, v110
	v_cvt_pk_bf16_f32 v102, v102, v103
	v_cvt_pk_bf16_f32 v103, v104, v105
	v_cvt_pk_bf16_f32 v104, v116, v117
	v_cvt_pk_bf16_f32 v105, v114, v115
	global_store_dwordx4 v243, v[102:105], s[26:27]
	s_nop 1
	v_mul_f32_e32 v103, v107, v107
	v_mul_f32_e32 v104, v109, v109
	v_mul_f32_e32 v102, v113, v113
	v_fmac_f32_e32 v103, v106, v106
	v_fmac_f32_e32 v104, v108, v108
	v_fmac_f32_e32 v102, v112, v112
	v_add_f32_e32 v103, v103, v104
	v_add_f32_e32 v102, v102, v103
	v_add_f32_e32 v0, v0, v102
	v_add_f32_e32 v0, v130, v0
	ds_bpermute_b32 v102, v229, v0
	s_waitcnt lgkmcnt(0)
	v_add_f32_e32 v0, v0, v102
	ds_bpermute_b32 v102, v228, v0
	s_and_saveexec_b64 s[2:3], s[8:9]
	s_cbranch_execz .LBB0_1093
	s_waitcnt lgkmcnt(0)
	v_add_f32_e32 v0, v0, v102
	v_mul_f32_e32 v0, 0x4b800000, v0
	v_trunc_f32_e32 v0, v0
	v_mul_f32_e32 v102, 0x2f800000, v0
	v_floor_f32_e32 v103, v102
	v_fmac_f32_e32 v0, 0xcf800000, v103
	v_cvt_u32_f32_e32 v102, v0
	v_cvt_u32_f32_e32 v103, v103
	global_atomic_add_x2 v[134:135], v[102:103], off offset:256
;     __device__ __forceinline__ void operator()(const f32x4 (&acc)[2][2][4][2], const Unit& u, int wr, int wc, int fr, int fq) const {
;     ...
;             for (int i = 0; i < 8; ++i) sc_[i] = gsc[u.pm * BM + wr * 64 + fr + (i >> 2) * HALF + (i & 3) * 16];
; #pragma unroll
;             for (int i = 0; i < 8; ++i) rc[i] = 1.0f / sqrtf(ssq_val(sc_[i]) * (1.0f / 256.0f) + EPS); }
;     ...
;                     bv[mm][bj] = *(gl_u32x4*)(PG8_GCPTR(base) + (unsigned)((u.pm * BM + ai * HALF + wr * 64 + (mp + mm) * 16 + fr) * DM + col0 + bj * HALF) * 2u);
; #pragma unroll
;             for (int mm = 0; mm < 2; ++mm) {
;                 const int m = mp + mm;
;                 const int row = u.pm * BM + ai * HALF + wr * 64 + m * 16 + fr; float q = 0.f;
; #pragma unroll
;                 for (int bj = 0; bj < 2; ++bj) {
;                     const unsigned offb = (unsigned)(row * DM + col0 + bj * HALF) * 2u;
;                     const u32x4 bw = bv[mm][bj];
;                     const f32x4 b0 = (f32x4){__uint_as_float(bw.x << 16), __uint_as_float(bw.x & 0xffff0000u), __uint_as_float(bw.y << 16), __uint_as_float(bw.y & 0xffff0000u)};
;                     const f32x4 b1 = (f32x4){__uint_as_float(bw.z << 16), __uint_as_float(bw.z & 0xffff0000u), __uint_as_float(bw.w << 16), __uint_as_float(bw.w & 0xffff0000u)};
;                     f32x4 a0 = acc[ai][bj][m][0], a1 = acc[ai][bj][m][1]; if constexpr (GN) { a0 *= rc[ai * 4 + m]; a1 *= rc[ai * 4 + m]; }
;                     const f32x4 o0 = b0 + g[bj][0] * a0, o1 = b1 + g[bj][1] * a1;
;                     u32x4 wo; wo.x = cvt_pk_bf16(o0[0], o0[1]); wo.y = cvt_pk_bf16(o0[2], o0[3]); wo.z = cvt_pk_bf16(o1[0], o1[1]); wo.w = cvt_pk_bf16(o1[2], o1[3]);
;                     *(gs_u32x4*)(PG8_GPTR(out) + offb) = wo;
;                     if (xg) {
;                         const f32x4 h0 = o0 * cf[bj][0], h1 = o1 * cf[bj][1];
;                         u32x4 w; w.x = cvt_pk_bf16(h0[0], h0[1]); w.y = cvt_pk_bf16(h0[2], h0[3]); w.z = cvt_pk_bf16(h1[0], h1[1]); w.w = cvt_pk_bf16(h1[2], h1[3]);
;                         *(gs_u32x4*)(PG8_GPTR(xg) + offb) = w;
;                         q += (o0[0] * o0[0] + o0[1] * o0[1]) + (o0[2] * o0[2] + o0[3] * o0[3]) + (o1[0] * o1[0] + o1[1] * o1[1]) + (o1[2] * o1[2] + o1[3] * o1[3]);
;                     }
;                 }
;                 if (xg) ssq_put(ssq, row, q, fr, fq);
.LBB0_1093:
	s_or_b64 exec, exec, s[2:3]
	v_ffbh_u32_e32 v0, v213
	v_min_u32_e32 v0, 32, v0
	s_waitcnt lgkmcnt(0)
	v_lshlrev_b64 v[102:103], v0, v[212:213]
	v_min_u32_e32 v102, 1, v102
	v_or_b32_e32 v102, v103, v102
	v_cvt_f32_u32_e32 v102, v102
	v_sub_u32_e32 v0, 32, v0
	v_and_b32_e32 v107, 0xffff0000, v124
	v_lshlrev_b32_e32 v108, 16, v125
	v_ldexp_f32 v0, v102, v0
	v_mul_f32_e32 v0, 0x33800000, v0
	v_fmamk_f32 v0, v0, 0x3b800000, v226
	v_and_b32_e32 v109, 0xffff0000, v125
	s_nop 0
	s_mov_b32 s2, 0x18000
	v_add3_u32 v110, v230, v136, s2
	v_add_u32_e32 v241, s2, v240
	v_add_u32_e32 v243, s2, v242
	v_rsq_f32_e32 v0, v0
	s_nop 0
	v_lshlrev_b32_e32 v102, 16, v122
	v_and_b32_e32 v103, 0xffff0000, v122
	v_lshlrev_b32_e32 v104, 16, v123
	v_and_b32_e32 v105, 0xffff0000, v123
	v_lshlrev_b32_e32 v106, 16, v124
	v_pk_mul_f32 v[98:99], v[98:99], v[0:1] op_sel_hi:[1,0]
	v_pk_mul_f32 v[100:101], v[100:101], v[0:1] op_sel_hi:[1,0]
	v_pk_mul_f32 v[94:95], v[94:95], v[0:1] op_sel_hi:[1,0]
	v_pk_mul_f32 v[96:97], v[96:97], v[0:1] op_sel_hi:[1,0]
	v_pk_fma_f32 v[100:101], v[84:85], v[100:101], v[104:105]
	v_pk_fma_f32 v[98:99], v[82:83], v[98:99], v[102:103]
	v_pk_fma_f32 v[104:105], v[78:79], v[94:95], v[106:107]
	v_cvt_pk_bf16_f32 v94, v98, v99
	v_cvt_pk_bf16_f32 v95, v100, v101
	v_pk_fma_f32 v[102:103], v[80:81], v[96:97], v[108:109]
	v_cvt_pk_bf16_f32 v96, v104, v105
	v_pk_mul_f32 v[108:109], v[202:203], v[104:105]
	v_cvt_pk_bf16_f32 v97, v102, v103
	global_store_dwordx4 v241, v[94:97], s[24:25] nt
	v_pk_mul_f32 v[106:107], v[198:199], v[102:103]
	v_pk_mul_f32 v[90:91], v[90:91], v[0:1] op_sel_hi:[1,0]
	v_pk_mul_f32 v[94:95], v[204:205], v[98:99]
	v_pk_mul_f32 v[96:97], v[200:201], v[100:101]
	v_cvt_pk_bf16_f32 v94, v94, v95
	v_pk_mul_f32 v[92:93], v[92:93], v[0:1] op_sel_hi:[1,0]
	v_cvt_pk_bf16_f32 v95, v96, v97
	v_cvt_pk_bf16_f32 v96, v108, v109
	v_cvt_pk_bf16_f32 v97, v106, v107
	global_store_dwordx4 v243, v[94:97], s[26:27] offset:-4096
	v_pk_mul_f32 v[86:87], v[86:87], v[0:1] op_sel_hi:[1,0]
	v_pk_mul_f32 v[88:89], v[88:89], v[0:1] op_sel_hi:[1,0]
	v_mul_f32_e32 v94, v99, v99
	v_mul_f32_e32 v95, v101, v101
	v_fmac_f32_e32 v94, v98, v98
	v_fmac_f32_e32 v95, v100, v100
	v_add_f32_e32 v94, v94, v95
	v_mul_f32_e32 v95, v105, v105
	v_fmac_f32_e32 v95, v104, v104
	v_add_f32_e32 v94, v95, v94
	v_mul_f32_e32 v95, v103, v103
	v_fmac_f32_e32 v95, v102, v102
	v_add_f32_e32 v102, v95, v94
	v_lshlrev_b32_e32 v94, 16, v118
	v_and_b32_e32 v95, 0xffff0000, v118
	v_lshlrev_b32_e32 v96, 16, v119
	v_and_b32_e32 v97, 0xffff0000, v119
	v_lshlrev_b32_e32 v98, 16, v120
	v_and_b32_e32 v99, 0xffff0000, v120
	v_lshlrev_b32_e32 v100, 16, v121
	v_and_b32_e32 v101, 0xffff0000, v121
	v_pk_fma_f32 v[92:93], v[92:93], v[76:77], v[96:97]
	v_pk_fma_f32 v[90:91], v[90:91], v[74:75], v[94:95]
	v_pk_fma_f32 v[94:95], v[88:89], v[72:73], v[100:101]
	v_pk_fma_f32 v[96:97], v[86:87], v[70:71], v[98:99]
	v_cvt_pk_bf16_f32 v86, v90, v91
	v_cvt_pk_bf16_f32 v87, v92, v93
	v_mul_f32_e32 v0, v95, v95
	v_cvt_pk_bf16_f32 v88, v96, v97
	v_cvt_pk_bf16_f32 v89, v94, v95
	global_store_dwordx4 v241, v[86:89], s[24:25] offset:1024 nt
	v_fmac_f32_e32 v0, v94, v94
	v_pk_mul_f32 v[98:99], v[196:197], v[92:93]
	v_mul_f32_e32 v87, v91, v91
	v_mul_f32_e32 v88, v93, v93
	v_mul_f32_e32 v86, v97, v97
	v_fmac_f32_e32 v87, v90, v90
	v_fmac_f32_e32 v88, v92, v92
	v_fmac_f32_e32 v86, v96, v96
	v_add_f32_e32 v87, v87, v88
	v_add_f32_e32 v86, v86, v87
	v_add_f32_e32 v0, v0, v86
	v_add_f32_e32 v0, v102, v0
	ds_bpermute_b32 v89, v229, v0
	v_pk_mul_f32 v[86:87], v[174:175], v[90:91]
	v_pk_mul_f32 v[90:91], v[194:195], v[96:97]
	v_cvt_pk_bf16_f32 v88, v86, v87
	v_pk_mul_f32 v[92:93], v[176:177], v[94:95]
	s_waitcnt lgkmcnt(0)
	v_add_f32_e32 v0, v0, v89
	ds_bpermute_b32 v86, v228, v0
	v_cvt_pk_bf16_f32 v89, v98, v99
	v_cvt_pk_bf16_f32 v90, v90, v91
	v_cvt_pk_bf16_f32 v91, v92, v93
	global_store_dwordx4 v243, v[88:91], s[26:27]
	s_and_saveexec_b64 s[2:3], s[8:9]
	s_cbranch_execz .LBB0_1095
	s_waitcnt lgkmcnt(0)
	v_add_f32_e32 v0, v0, v86
	v_mul_f32_e32 v0, 0x4b800000, v0
	v_trunc_f32_e32 v0, v0
	v_mul_f32_e32 v86, 0x2f800000, v0
	v_floor_f32_e32 v87, v86
	v_fmac_f32_e32 v0, 0xcf800000, v87
	v_cvt_u32_f32_e32 v86, v0
	v_cvt_u32_f32_e32 v87, v87
	global_atomic_add_x2 v[134:135], v[86:87], off offset:384
;     __device__ __forceinline__ void operator()(const f32x4 (&acc)[2][2][4][2], const Unit& u, int wr, int wc, int fr, int fq) const {
;     ...
;             for (int i = 0; i < 8; ++i) sc_[i] = gsc[u.pm * BM + wr * 64 + fr + (i >> 2) * HALF + (i & 3) * 16];
; #pragma unroll
;             for (int i = 0; i < 8; ++i) rc[i] = 1.0f / sqrtf(ssq_val(sc_[i]) * (1.0f / 256.0f) + EPS); }
;     ...
;                     bv[mm][bj] = *(gl_u32x4*)(PG8_GCPTR(base) + (unsigned)((u.pm * BM + ai * HALF + wr * 64 + (mp + mm) * 16 + fr) * DM + col0 + bj * HALF) * 2u);
; #pragma unroll
;             for (int mm = 0; mm < 2; ++mm) {
;                 const int m = mp + mm;
;                 const int row = u.pm * BM + ai * HALF + wr * 64 + m * 16 + fr; float q = 0.f;
; #pragma unroll
;                 for (int bj = 0; bj < 2; ++bj) {
;                     const unsigned offb = (unsigned)(row * DM + col0 + bj * HALF) * 2u;
;                     const u32x4 bw = bv[mm][bj];
;                     const f32x4 b0 = (f32x4){__uint_as_float(bw.x << 16), __uint_as_float(bw.x & 0xffff0000u), __uint_as_float(bw.y << 16), __uint_as_float(bw.y & 0xffff0000u)};
;                     const f32x4 b1 = (f32x4){__uint_as_float(bw.z << 16), __uint_as_float(bw.z & 0xffff0000u), __uint_as_float(bw.w << 16), __uint_as_float(bw.w & 0xffff0000u)};
;                     f32x4 a0 = acc[ai][bj][m][0], a1 = acc[ai][bj][m][1]; if constexpr (GN) { a0 *= rc[ai * 4 + m]; a1 *= rc[ai * 4 + m]; }
;                     const f32x4 o0 = b0 + g[bj][0] * a0, o1 = b1 + g[bj][1] * a1;
;                     u32x4 wo; wo.x = cvt_pk_bf16(o0[0], o0[1]); wo.y = cvt_pk_bf16(o0[2], o0[3]); wo.z = cvt_pk_bf16(o1[0], o1[1]); wo.w = cvt_pk_bf16(o1[2], o1[3]);
;                     *(gs_u32x4*)(PG8_GPTR(out) + offb) = wo;
;                     if (xg) {
;                         const f32x4 h0 = o0 * cf[bj][0], h1 = o1 * cf[bj][1];
;                         u32x4 w; w.x = cvt_pk_bf16(h0[0], h0[1]); w.y = cvt_pk_bf16(h0[2], h0[3]); w.z = cvt_pk_bf16(h1[0], h1[1]); w.w = cvt_pk_bf16(h1[2], h1[3]);
;                         *(gs_u32x4*)(PG8_GPTR(xg) + offb) = w;
;                         q += (o0[0] * o0[0] + o0[1] * o0[1]) + (o0[2] * o0[2] + o0[3] * o0[3]) + (o1[0] * o1[0] + o1[1] * o1[1]) + (o1[2] * o1[2] + o1[3] * o1[3]);
;                     }
;                 }
;                 if (xg) ssq_put(ssq, row, q, fr, fq);
.LBB0_1095:
	s_or_b64 exec, exec, s[2:3]
	v_ffbh_u32_e32 v0, v211
	v_min_u32_e32 v0, 32, v0
	s_waitcnt lgkmcnt(0)
	v_lshlrev_b64 v[86:87], v0, v[210:211]
	v_min_u32_e32 v86, 1, v86
	v_or_b32_e32 v86, v87, v86
	v_cvt_f32_u32_e32 v86, v86
	v_sub_u32_e32 v0, 32, v0
	v_ldexp_f32 v0, v86, v0
	v_mul_f32_e32 v0, 0x33800000, v0
	v_fmamk_f32 v0, v0, 0x3b800000, v226
	s_mov_b32 s2, 0x40000
	v_add3_u32 v106, v232, v230, s2
	v_add_u32_e32 v241, s2, v240
	v_add_u32_e32 v243, s2, v242
	v_rsq_f32_e32 v0, v0
	s_nop 0
	v_add_u32_e32 v86, 0x40000, v240
	global_load_dwordx4 v[98:101], v86, s[22:23] nt
	global_load_dwordx4 v[94:97], v86, s[22:23] offset:1024 nt
	v_add_u32_e32 v86, 0x48000, v240
	global_load_dwordx4 v[90:93], v86, s[22:23] nt
	s_nop 0
	global_load_dwordx4 v[86:89], v86, s[22:23] offset:1024 nt
	v_pk_mul_f32 v[66:67], v[66:67], v[0:1] op_sel_hi:[1,0]
	v_pk_mul_f32 v[68:69], v[68:69], v[0:1] op_sel_hi:[1,0]
	v_pk_mul_f32 v[62:63], v[62:63], v[0:1] op_sel_hi:[1,0]
	v_pk_mul_f32 v[64:65], v[64:65], v[0:1] op_sel_hi:[1,0]
	v_pk_mul_f32 v[58:59], v[58:59], v[0:1] op_sel_hi:[1,0]
	v_pk_mul_f32 v[60:61], v[60:61], v[0:1] op_sel_hi:[1,0]
	v_pk_mul_f32 v[54:55], v[54:55], v[0:1] op_sel_hi:[1,0]
	v_pk_mul_f32 v[56:57], v[56:57], v[0:1] op_sel_hi:[1,0]
	s_waitcnt vmcnt(0)
	v_lshlrev_b32_e32 v102, 16, v98
	v_and_b32_e32 v103, 0xffff0000, v98
	v_lshlrev_b32_e32 v98, 16, v99
	v_and_b32_e32 v99, 0xffff0000, v99
	v_lshlrev_b32_e32 v104, 16, v100
	v_and_b32_e32 v105, 0xffff0000, v100
	v_lshlrev_b32_e32 v100, 16, v101
	v_and_b32_e32 v101, 0xffff0000, v101
	v_pk_fma_f32 v[68:69], v[84:85], v[68:69], v[98:99]
	v_pk_fma_f32 v[66:67], v[82:83], v[66:67], v[102:103]
	v_pk_fma_f32 v[98:99], v[80:81], v[64:65], v[100:101]
	v_pk_fma_f32 v[100:101], v[78:79], v[62:63], v[104:105]
	v_cvt_pk_bf16_f32 v62, v66, v67
	v_cvt_pk_bf16_f32 v63, v68, v69
	v_pk_mul_f32 v[102:103], v[198:199], v[98:99]
	v_cvt_pk_bf16_f32 v64, v100, v101
	v_cvt_pk_bf16_f32 v65, v98, v99
	global_store_dwordx4 v241, v[62:65], s[24:25] nt
	v_pk_mul_f32 v[104:105], v[202:203], v[100:101]
	s_nop 0
	v_pk_mul_f32 v[62:63], v[204:205], v[66:67]
	v_pk_mul_f32 v[64:65], v[200:201], v[68:69]
	v_cvt_pk_bf16_f32 v62, v62, v63
	s_nop 0
	v_cvt_pk_bf16_f32 v63, v64, v65
	v_cvt_pk_bf16_f32 v64, v104, v105
	v_cvt_pk_bf16_f32 v65, v102, v103
	global_store_dwordx4 v243, v[62:65], s[26:27] offset:-4096
	s_nop 1
	v_mul_f32_e32 v62, v67, v67
	v_mul_f32_e32 v63, v69, v69
	v_fmac_f32_e32 v62, v66, v66
	v_fmac_f32_e32 v63, v68, v68
	v_add_f32_e32 v62, v62, v63
	v_mul_f32_e32 v63, v101, v101
	v_fmac_f32_e32 v63, v100, v100
	v_add_f32_e32 v62, v63, v62
	v_mul_f32_e32 v63, v99, v99
	v_fmac_f32_e32 v63, v98, v98
	v_add_f32_e32 v98, v63, v62
	v_lshlrev_b32_e32 v62, 16, v94
	v_and_b32_e32 v63, 0xffff0000, v94
	v_lshlrev_b32_e32 v64, 16, v95
	v_and_b32_e32 v65, 0xffff0000, v95
	v_lshlrev_b32_e32 v66, 16, v96
	v_and_b32_e32 v67, 0xffff0000, v96
	v_lshlrev_b32_e32 v68, 16, v97
	v_and_b32_e32 v69, 0xffff0000, v97
	v_pk_fma_f32 v[60:61], v[60:61], v[76:77], v[64:65]
	v_pk_fma_f32 v[58:59], v[58:59], v[74:75], v[62:63]
	v_pk_fma_f32 v[62:63], v[56:57], v[72:73], v[68:69]
	v_pk_fma_f32 v[64:65], v[54:55], v[70:71], v[66:67]
	v_cvt_pk_bf16_f32 v54, v58, v59
	v_cvt_pk_bf16_f32 v55, v60, v61
	v_pk_mul_f32 v[66:67], v[176:177], v[62:63]
	v_cvt_pk_bf16_f32 v56, v64, v65
	v_cvt_pk_bf16_f32 v57, v62, v63
	global_store_dwordx4 v241, v[54:57], s[24:25] offset:1024 nt
	v_pk_mul_f32 v[68:69], v[194:195], v[64:65]
	v_mul_f32_e32 v0, v63, v63
	v_pk_mul_f32 v[56:57], v[196:197], v[60:61]
	v_pk_mul_f32 v[54:55], v[174:175], v[58:59]
	v_fmac_f32_e32 v0, v62, v62
	v_cvt_pk_bf16_f32 v54, v54, v55
	v_cvt_pk_bf16_f32 v55, v56, v57
	v_cvt_pk_bf16_f32 v56, v68, v69
	v_cvt_pk_bf16_f32 v57, v66, v67
	global_store_dwordx4 v243, v[54:57], s[26:27]
	s_nop 1
	v_mul_f32_e32 v55, v59, v59
	v_mul_f32_e32 v56, v61, v61
	v_mul_f32_e32 v54, v65, v65
	v_fmac_f32_e32 v55, v58, v58
	v_fmac_f32_e32 v56, v60, v60
	v_fmac_f32_e32 v54, v64, v64
	v_add_f32_e32 v55, v55, v56
	v_add_f32_e32 v54, v54, v55
	v_add_f32_e32 v0, v0, v54
	v_add_f32_e32 v0, v98, v0
	ds_bpermute_b32 v54, v229, v0
	s_waitcnt lgkmcnt(0)
	v_add_f32_e32 v0, v0, v54
	ds_bpermute_b32 v54, v228, v0
	s_and_saveexec_b64 s[2:3], s[8:9]
	s_cbranch_execz .LBB0_1097
	s_waitcnt lgkmcnt(0)
	v_add_f32_e32 v0, v0, v54
	v_mul_f32_e32 v0, 0x4b800000, v0
	v_trunc_f32_e32 v0, v0
	v_mul_f32_e32 v54, 0x2f800000, v0
	v_floor_f32_e32 v55, v54
	v_fmac_f32_e32 v0, 0xcf800000, v55
	v_cvt_u32_f32_e32 v54, v0
	v_cvt_u32_f32_e32 v55, v55
	global_atomic_add_x2 v[134:135], v[54:55], off offset:1024
;     __device__ __forceinline__ void operator()(const f32x4 (&acc)[2][2][4][2], const Unit& u, int wr, int wc, int fr, int fq) const {
;     ...
;             for (int i = 0; i < 8; ++i) sc_[i] = gsc[u.pm * BM + wr * 64 + fr + (i >> 2) * HALF + (i & 3) * 16];
; #pragma unroll
;             for (int i = 0; i < 8; ++i) rc[i] = 1.0f / sqrtf(ssq_val(sc_[i]) * (1.0f / 256.0f) + EPS); }
;     ...
;                     bv[mm][bj] = *(gl_u32x4*)(PG8_GCPTR(base) + (unsigned)((u.pm * BM + ai * HALF + wr * 64 + (mp + mm) * 16 + fr) * DM + col0 + bj * HALF) * 2u);
; #pragma unroll
;             for (int mm = 0; mm < 2; ++mm) {
;                 const int m = mp + mm;
;                 const int row = u.pm * BM + ai * HALF + wr * 64 + m * 16 + fr; float q = 0.f;
; #pragma unroll
;                 for (int bj = 0; bj < 2; ++bj) {
;                     const unsigned offb = (unsigned)(row * DM + col0 + bj * HALF) * 2u;
;                     const u32x4 bw = bv[mm][bj];
;                     const f32x4 b0 = (f32x4){__uint_as_float(bw.x << 16), __uint_as_float(bw.x & 0xffff0000u), __uint_as_float(bw.y << 16), __uint_as_float(bw.y & 0xffff0000u)};
;                     const f32x4 b1 = (f32x4){__uint_as_float(bw.z << 16), __uint_as_float(bw.z & 0xffff0000u), __uint_as_float(bw.w << 16), __uint_as_float(bw.w & 0xffff0000u)};
;                     f32x4 a0 = acc[ai][bj][m][0], a1 = acc[ai][bj][m][1]; if constexpr (GN) { a0 *= rc[ai * 4 + m]; a1 *= rc[ai * 4 + m]; }
;                     const f32x4 o0 = b0 + g[bj][0] * a0, o1 = b1 + g[bj][1] * a1;
;                     u32x4 wo; wo.x = cvt_pk_bf16(o0[0], o0[1]); wo.y = cvt_pk_bf16(o0[2], o0[3]); wo.z = cvt_pk_bf16(o1[0], o1[1]); wo.w = cvt_pk_bf16(o1[2], o1[3]);
;                     *(gs_u32x4*)(PG8_GPTR(out) + offb) = wo;
;                     if (xg) {
;                         const f32x4 h0 = o0 * cf[bj][0], h1 = o1 * cf[bj][1];
;                         u32x4 w; w.x = cvt_pk_bf16(h0[0], h0[1]); w.y = cvt_pk_bf16(h0[2], h0[3]); w.z = cvt_pk_bf16(h1[0], h1[1]); w.w = cvt_pk_bf16(h1[2], h1[3]);
;                         *(gs_u32x4*)(PG8_GPTR(xg) + offb) = w;
;                         q += (o0[0] * o0[0] + o0[1] * o0[1]) + (o0[2] * o0[2] + o0[3] * o0[3]) + (o1[0] * o1[0] + o1[1] * o1[1]) + (o1[2] * o1[2] + o1[3] * o1[3]);
;                     }
;                 }
;                 if (xg) ssq_put(ssq, row, q, fr, fq);
.LBB0_1097:
	s_or_b64 exec, exec, s[2:3]
	v_ffbh_u32_e32 v0, v209
	v_min_u32_e32 v0, 32, v0
	s_waitcnt lgkmcnt(0)
	v_lshlrev_b64 v[54:55], v0, v[208:209]
	v_min_u32_e32 v54, 1, v54
	v_or_b32_e32 v54, v55, v54
	v_cvt_f32_u32_e32 v54, v54
	v_sub_u32_e32 v0, 32, v0
	v_and_b32_e32 v59, 0xffff0000, v92
	v_lshlrev_b32_e32 v60, 16, v93
	v_ldexp_f32 v0, v54, v0
	v_mul_f32_e32 v0, 0x33800000, v0
	v_fmamk_f32 v0, v0, 0x3b800000, v226
	v_and_b32_e32 v61, 0xffff0000, v93
	s_nop 0
	s_mov_b32 s2, 0x48000
	v_add3_u32 v62, v136, v230, s2
	v_add_u32_e32 v241, s2, v240
	v_add_u32_e32 v243, s2, v242
	v_rsq_f32_e32 v0, v0
	s_nop 0
	v_lshlrev_b32_e32 v54, 16, v90
	v_and_b32_e32 v55, 0xffff0000, v90
	v_lshlrev_b32_e32 v56, 16, v91
	v_and_b32_e32 v57, 0xffff0000, v91
	v_lshlrev_b32_e32 v58, 16, v92
	v_pk_mul_f32 v[50:51], v[50:51], v[0:1] op_sel_hi:[1,0]
	v_pk_mul_f32 v[52:53], v[52:53], v[0:1] op_sel_hi:[1,0]
	v_pk_mul_f32 v[46:47], v[46:47], v[0:1] op_sel_hi:[1,0]
	v_pk_mul_f32 v[48:49], v[48:49], v[0:1] op_sel_hi:[1,0]
	v_pk_fma_f32 v[52:53], v[84:85], v[52:53], v[56:57]
	v_pk_fma_f32 v[50:51], v[82:83], v[50:51], v[54:55]
	v_pk_fma_f32 v[56:57], v[78:79], v[46:47], v[58:59]
	v_cvt_pk_bf16_f32 v46, v50, v51
	v_cvt_pk_bf16_f32 v47, v52, v53
	v_pk_fma_f32 v[54:55], v[80:81], v[48:49], v[60:61]
	v_cvt_pk_bf16_f32 v48, v56, v57
	v_pk_mul_f32 v[60:61], v[202:203], v[56:57]
	v_cvt_pk_bf16_f32 v49, v54, v55
	global_store_dwordx4 v241, v[46:49], s[24:25] nt
	v_pk_mul_f32 v[58:59], v[198:199], v[54:55]
	v_pk_mul_f32 v[42:43], v[42:43], v[0:1] op_sel_hi:[1,0]
	v_pk_mul_f32 v[46:47], v[204:205], v[50:51]
	v_pk_mul_f32 v[48:49], v[200:201], v[52:53]
	v_cvt_pk_bf16_f32 v46, v46, v47
	v_pk_mul_f32 v[44:45], v[44:45], v[0:1] op_sel_hi:[1,0]
	v_cvt_pk_bf16_f32 v47, v48, v49
	v_cvt_pk_bf16_f32 v48, v60, v61
	v_cvt_pk_bf16_f32 v49, v58, v59
	global_store_dwordx4 v243, v[46:49], s[26:27] offset:-4096
	v_pk_mul_f32 v[38:39], v[38:39], v[0:1] op_sel_hi:[1,0]
	v_pk_mul_f32 v[40:41], v[40:41], v[0:1] op_sel_hi:[1,0]
	v_mul_f32_e32 v46, v51, v51
	v_mul_f32_e32 v47, v53, v53
	v_fmac_f32_e32 v46, v50, v50
	v_fmac_f32_e32 v47, v52, v52
	v_add_f32_e32 v46, v46, v47
	v_mul_f32_e32 v47, v57, v57
	v_fmac_f32_e32 v47, v56, v56
	v_add_f32_e32 v46, v47, v46
	v_mul_f32_e32 v47, v55, v55
	v_fmac_f32_e32 v47, v54, v54
	v_add_f32_e32 v54, v47, v46
	v_lshlrev_b32_e32 v46, 16, v86
	v_and_b32_e32 v47, 0xffff0000, v86
	v_lshlrev_b32_e32 v48, 16, v87
	v_and_b32_e32 v49, 0xffff0000, v87
	v_lshlrev_b32_e32 v50, 16, v88
	v_and_b32_e32 v51, 0xffff0000, v88
	v_lshlrev_b32_e32 v52, 16, v89
	v_and_b32_e32 v53, 0xffff0000, v89
	v_pk_fma_f32 v[44:45], v[76:77], v[44:45], v[48:49]
	v_pk_fma_f32 v[42:43], v[74:75], v[42:43], v[46:47]
	v_pk_fma_f32 v[46:47], v[40:41], v[72:73], v[52:53]
	v_pk_fma_f32 v[48:49], v[38:39], v[70:71], v[50:51]
	v_cvt_pk_bf16_f32 v38, v42, v43
	v_cvt_pk_bf16_f32 v39, v44, v45
	v_mul_f32_e32 v0, v47, v47
	v_cvt_pk_bf16_f32 v40, v48, v49
	v_cvt_pk_bf16_f32 v41, v46, v47
	global_store_dwordx4 v241, v[38:41], s[24:25] offset:1024 nt
	v_fmac_f32_e32 v0, v46, v46
	v_pk_mul_f32 v[50:51], v[196:197], v[44:45]
	v_mul_f32_e32 v39, v43, v43
	v_mul_f32_e32 v40, v45, v45
	v_mul_f32_e32 v38, v49, v49
	v_fmac_f32_e32 v39, v42, v42
	v_fmac_f32_e32 v40, v44, v44
	v_fmac_f32_e32 v38, v48, v48
	v_add_f32_e32 v39, v39, v40
	v_add_f32_e32 v38, v38, v39
	v_add_f32_e32 v0, v0, v38
	v_add_f32_e32 v0, v54, v0
	ds_bpermute_b32 v41, v229, v0
	v_pk_mul_f32 v[38:39], v[174:175], v[42:43]
	v_pk_mul_f32 v[42:43], v[194:195], v[48:49]
	v_cvt_pk_bf16_f32 v40, v38, v39
	v_pk_mul_f32 v[44:45], v[176:177], v[46:47]
	s_waitcnt lgkmcnt(0)
	v_add_f32_e32 v0, v0, v41
	ds_bpermute_b32 v38, v228, v0
	v_cvt_pk_bf16_f32 v41, v50, v51
	v_cvt_pk_bf16_f32 v42, v42, v43
	v_cvt_pk_bf16_f32 v43, v44, v45
	global_store_dwordx4 v243, v[40:43], s[26:27]
	s_and_saveexec_b64 s[2:3], s[8:9]
	s_cbranch_execz .LBB0_1099
	s_waitcnt lgkmcnt(0)
	v_add_f32_e32 v0, v0, v38
	v_mul_f32_e32 v0, 0x4b800000, v0
	v_trunc_f32_e32 v0, v0
	v_mul_f32_e32 v38, 0x2f800000, v0
	v_floor_f32_e32 v39, v38
	v_fmac_f32_e32 v0, 0xcf800000, v39
	v_cvt_u32_f32_e32 v38, v0
	v_cvt_u32_f32_e32 v39, v39
	global_atomic_add_x2 v[134:135], v[38:39], off offset:1152
.LBB0_1099:
	s_or_b64 exec, exec, s[2:3]
	v_ffbh_u32_e32 v0, v207
	v_min_u32_e32 v0, 32, v0
	s_waitcnt lgkmcnt(0)
	v_lshlrev_b64 v[38:39], v0, v[206:207]
	v_min_u32_e32 v38, 1, v38
	v_or_b32_e32 v38, v39, v38
	v_cvt_f32_u32_e32 v38, v38
	v_sub_u32_e32 v0, 32, v0
	v_ldexp_f32 v0, v38, v0
	v_mul_f32_e32 v0, 0x33800000, v0
	v_fmamk_f32 v0, v0, 0x3b800000, v226
	s_mov_b32 s2, 0x50000
	v_add3_u32 v58, v136, v230, s2
	v_add_u32_e32 v241, s2, v240
	v_add_u32_e32 v243, s2, v242
	v_rsq_f32_e32 v0, v0
	s_nop 0
	v_add_u32_e32 v38, 0x50000, v240
	global_load_dwordx4 v[50:53], v38, s[22:23] nt
	global_load_dwordx4 v[46:49], v38, s[22:23] offset:1024 nt
	v_add_u32_e32 v38, 0x58000, v240
	global_load_dwordx4 v[42:45], v38, s[22:23] nt
	s_nop 0
	global_load_dwordx4 v[38:41], v38, s[22:23] offset:1024 nt
	v_pk_mul_f32 v[34:35], v[34:35], v[0:1] op_sel_hi:[1,0]
	v_pk_mul_f32 v[36:37], v[36:37], v[0:1] op_sel_hi:[1,0]
	v_pk_mul_f32 v[30:31], v[30:31], v[0:1] op_sel_hi:[1,0]
	v_pk_mul_f32 v[32:33], v[32:33], v[0:1] op_sel_hi:[1,0]
	v_pk_mul_f32 v[26:27], v[26:27], v[0:1] op_sel_hi:[1,0]
	v_pk_mul_f32 v[28:29], v[28:29], v[0:1] op_sel_hi:[1,0]
	v_pk_mul_f32 v[22:23], v[22:23], v[0:1] op_sel_hi:[1,0]
	v_pk_mul_f32 v[24:25], v[24:25], v[0:1] op_sel_hi:[1,0]
	s_waitcnt vmcnt(0)
; __device__ __forceinline__ unsigned cvt_pk_bf16(float lo, float hi) { unsigned r; asm volatile("v_cvt_pk_bf16_f32 %0, %1, %2" : "=v"(r) : "v"(lo), "v"(hi)); return r; }
; #define PG8_GPTR(p) ((__attribute__((address_space(1))) char*)(p))
;     __device__ __forceinline__ void operator()(const f32x4 (&acc)[2][2][4][2], const Unit& u, int wr, int wc, int fr, int fq) const {
;     ...
;             for (int mm = 0; mm < 2; ++mm) {
;                 const int m = mp + mm;
;                 const int row = u.pm * BM + ai * HALF + wr * 64 + m * 16 + fr; float q = 0.f;
; #pragma unroll
;                 for (int bj = 0; bj < 2; ++bj) {
;                     const unsigned offb = (unsigned)(row * DM + col0 + bj * HALF) * 2u;
;                     const u32x4 bw = bv[mm][bj];
;                     const f32x4 b0 = (f32x4){__uint_as_float(bw.x << 16), __uint_as_float(bw.x & 0xffff0000u), __uint_as_float(bw.y << 16), __uint_as_float(bw.y & 0xffff0000u)};
;                     const f32x4 b1 = (f32x4){__uint_as_float(bw.z << 16), __uint_as_float(bw.z & 0xffff0000u), __uint_as_float(bw.w << 16), __uint_as_float(bw.w & 0xffff0000u)};
;                     f32x4 a0 = acc[ai][bj][m][0], a1 = acc[ai][bj][m][1]; if constexpr (GN) { a0 *= rc[ai * 4 + m]; a1 *= rc[ai * 4 + m]; }
;                     const f32x4 o0 = b0 + g[bj][0] * a0, o1 = b1 + g[bj][1] * a1;
;                     u32x4 wo; wo.x = cvt_pk_bf16(o0[0], o0[1]); wo.y = cvt_pk_bf16(o0[2], o0[3]); wo.z = cvt_pk_bf16(o1[0], o1[1]); wo.w = cvt_pk_bf16(o1[2], o1[3]);
;                     *(gs_u32x4*)(PG8_GPTR(out) + offb) = wo;
;                     if (xg) {
;                         const f32x4 h0 = o0 * cf[bj][0], h1 = o1 * cf[bj][1];
;                         u32x4 w; w.x = cvt_pk_bf16(h0[0], h0[1]); w.y = cvt_pk_bf16(h0[2], h0[3]); w.z = cvt_pk_bf16(h1[0], h1[1]); w.w = cvt_pk_bf16(h1[2], h1[3]);
;                         *(gs_u32x4*)(PG8_GPTR(xg) + offb) = w;
;                         q += (o0[0] * o0[0] + o0[1] * o0[1]) + (o0[2] * o0[2] + o0[3] * o0[3]) + (o1[0] * o1[0] + o1[1] * o1[1]) + (o1[2] * o1[2] + o1[3] * o1[3]);
;                     }
;                 }
;                 if (xg) ssq_put(ssq, row, q, fr, fq);
	v_lshlrev_b32_e32 v54, 16, v50
	v_and_b32_e32 v55, 0xffff0000, v50
	v_lshlrev_b32_e32 v50, 16, v51
	v_and_b32_e32 v51, 0xffff0000, v51
	v_lshlrev_b32_e32 v56, 16, v52
	v_and_b32_e32 v57, 0xffff0000, v52
	v_lshlrev_b32_e32 v52, 16, v53
	v_and_b32_e32 v53, 0xffff0000, v53
	v_pk_fma_f32 v[36:37], v[84:85], v[36:37], v[50:51]
	v_pk_fma_f32 v[34:35], v[82:83], v[34:35], v[54:55]
	v_pk_fma_f32 v[50:51], v[80:81], v[32:33], v[52:53]
	v_pk_fma_f32 v[52:53], v[78:79], v[30:31], v[56:57]
	v_cvt_pk_bf16_f32 v30, v34, v35
	v_cvt_pk_bf16_f32 v31, v36, v37
	v_pk_mul_f32 v[54:55], v[198:199], v[50:51]
	v_cvt_pk_bf16_f32 v32, v52, v53
	v_cvt_pk_bf16_f32 v33, v50, v51
	global_store_dwordx4 v241, v[30:33], s[24:25] nt
	v_pk_mul_f32 v[56:57], v[202:203], v[52:53]
	s_nop 0
	v_pk_mul_f32 v[30:31], v[204:205], v[34:35]
	v_pk_mul_f32 v[32:33], v[200:201], v[36:37]
	v_cvt_pk_bf16_f32 v30, v30, v31
	s_nop 0
	v_cvt_pk_bf16_f32 v31, v32, v33
	v_cvt_pk_bf16_f32 v32, v56, v57
	v_cvt_pk_bf16_f32 v33, v54, v55
	global_store_dwordx4 v243, v[30:33], s[26:27] offset:-4096
	s_nop 1
	v_mul_f32_e32 v30, v35, v35
	v_mul_f32_e32 v31, v37, v37
	v_fmac_f32_e32 v30, v34, v34
	v_fmac_f32_e32 v31, v36, v36
	v_add_f32_e32 v30, v30, v31
	v_mul_f32_e32 v31, v53, v53
	v_fmac_f32_e32 v31, v52, v52
	v_add_f32_e32 v30, v31, v30
	v_mul_f32_e32 v31, v51, v51
	v_fmac_f32_e32 v31, v50, v50
	v_add_f32_e32 v50, v31, v30
	v_lshlrev_b32_e32 v30, 16, v46
	v_and_b32_e32 v31, 0xffff0000, v46
	v_lshlrev_b32_e32 v32, 16, v47
	v_and_b32_e32 v33, 0xffff0000, v47
	v_lshlrev_b32_e32 v34, 16, v48
	v_and_b32_e32 v35, 0xffff0000, v48
	v_lshlrev_b32_e32 v36, 16, v49
	v_and_b32_e32 v37, 0xffff0000, v49
	v_pk_fma_f32 v[28:29], v[76:77], v[28:29], v[32:33]
	v_pk_fma_f32 v[26:27], v[74:75], v[26:27], v[30:31]
	v_pk_fma_f32 v[30:31], v[72:73], v[24:25], v[36:37]
	v_pk_fma_f32 v[32:33], v[70:71], v[22:23], v[34:35]
	v_cvt_pk_bf16_f32 v22, v26, v27
	v_cvt_pk_bf16_f32 v23, v28, v29
	v_pk_mul_f32 v[34:35], v[176:177], v[30:31]
	v_cvt_pk_bf16_f32 v24, v32, v33
	v_cvt_pk_bf16_f32 v25, v30, v31
	global_store_dwordx4 v241, v[22:25], s[24:25] offset:1024 nt
	v_pk_mul_f32 v[36:37], v[194:195], v[32:33]
	v_mul_f32_e32 v0, v31, v31
	v_pk_mul_f32 v[24:25], v[196:197], v[28:29]
	v_pk_mul_f32 v[22:23], v[174:175], v[26:27]
	v_fmac_f32_e32 v0, v30, v30
	v_cvt_pk_bf16_f32 v22, v22, v23
	v_cvt_pk_bf16_f32 v23, v24, v25
	v_cvt_pk_bf16_f32 v24, v36, v37
	v_cvt_pk_bf16_f32 v25, v34, v35
	global_store_dwordx4 v243, v[22:25], s[26:27]
	s_nop 1
	v_mul_f32_e32 v23, v27, v27
	v_mul_f32_e32 v24, v29, v29
	v_mul_f32_e32 v22, v33, v33
	v_fmac_f32_e32 v23, v26, v26
	v_fmac_f32_e32 v24, v28, v28
	v_fmac_f32_e32 v22, v32, v32
	v_add_f32_e32 v23, v23, v24
	v_add_f32_e32 v22, v22, v23
	v_add_f32_e32 v0, v0, v22
	v_add_f32_e32 v0, v50, v0
	ds_bpermute_b32 v22, v229, v0
	s_waitcnt lgkmcnt(0)
	v_add_f32_e32 v0, v0, v22
	ds_bpermute_b32 v22, v228, v0
	s_and_saveexec_b64 s[2:3], s[8:9]
	s_cbranch_execz .LBB0_1101
	s_waitcnt lgkmcnt(0)
	v_add_f32_e32 v0, v0, v22
	v_mul_f32_e32 v0, 0x4b800000, v0
	v_trunc_f32_e32 v0, v0
	v_mul_f32_e32 v22, 0x2f800000, v0
	v_floor_f32_e32 v23, v22
	v_fmac_f32_e32 v0, 0xcf800000, v23
	v_cvt_u32_f32_e32 v22, v0
	v_cvt_u32_f32_e32 v23, v23
	global_atomic_add_x2 v[134:135], v[22:23], off offset:1280
; __device__ __forceinline__ unsigned cvt_pk_bf16(float lo, float hi) { unsigned r; asm volatile("v_cvt_pk_bf16_f32 %0, %1, %2" : "=v"(r) : "v"(lo), "v"(hi)); return r; }
;     __device__ __forceinline__ void operator()(const f32x4 (&acc)[2][2][4][2], const Unit& u, int wr, int wc, int fr, int fq) const {
;     ...
;             for (int i = 0; i < 8; ++i) sc_[i] = gsc[u.pm * BM + wr * 64 + fr + (i >> 2) * HALF + (i & 3) * 16];
; #pragma unroll
;             for (int i = 0; i < 8; ++i) rc[i] = 1.0f / sqrtf(ssq_val(sc_[i]) * (1.0f / 256.0f) + EPS); }
;     ...
;             for (int mm = 0; mm < 2; ++mm) {
;                 const int m = mp + mm;
;                 const int row = u.pm * BM + ai * HALF + wr * 64 + m * 16 + fr; float q = 0.f;
; #pragma unroll
;                 for (int bj = 0; bj < 2; ++bj) {
;                     const unsigned offb = (unsigned)(row * DM + col0 + bj * HALF) * 2u;
;                     const u32x4 bw = bv[mm][bj];
;                     const f32x4 b0 = (f32x4){__uint_as_float(bw.x << 16), __uint_as_float(bw.x & 0xffff0000u), __uint_as_float(bw.y << 16), __uint_as_float(bw.y & 0xffff0000u)};
;                     const f32x4 b1 = (f32x4){__uint_as_float(bw.z << 16), __uint_as_float(bw.z & 0xffff0000u), __uint_as_float(bw.w << 16), __uint_as_float(bw.w & 0xffff0000u)};
;                     f32x4 a0 = acc[ai][bj][m][0], a1 = acc[ai][bj][m][1]; if constexpr (GN) { a0 *= rc[ai * 4 + m]; a1 *= rc[ai * 4 + m]; }
;                     const f32x4 o0 = b0 + g[bj][0] * a0, o1 = b1 + g[bj][1] * a1;
;                     u32x4 wo; wo.x = cvt_pk_bf16(o0[0], o0[1]); wo.y = cvt_pk_bf16(o0[2], o0[3]); wo.z = cvt_pk_bf16(o1[0], o1[1]); wo.w = cvt_pk_bf16(o1[2], o1[3]);
;                     *(gs_u32x4*)(PG8_GPTR(out) + offb) = wo;
;                     if (xg) {
;                         const f32x4 h0 = o0 * cf[bj][0], h1 = o1 * cf[bj][1];
;                         u32x4 w; w.x = cvt_pk_bf16(h0[0], h0[1]); w.y = cvt_pk_bf16(h0[2], h0[3]); w.z = cvt_pk_bf16(h1[0], h1[1]); w.w = cvt_pk_bf16(h1[2], h1[3]);
;                         *(gs_u32x4*)(PG8_GPTR(xg) + offb) = w;
;                         q += (o0[0] * o0[0] + o0[1] * o0[1]) + (o0[2] * o0[2] + o0[3] * o0[3]) + (o1[0] * o1[0] + o1[1] * o1[1]) + (o1[2] * o1[2] + o1[3] * o1[3]);
;                     }
;                 }
;                 if (xg) ssq_put(ssq, row, q, fr, fq);
.LBB0_1101:
	s_or_b64 exec, exec, s[2:3]
	v_ffbh_u32_e32 v0, v3
	v_min_u32_e32 v0, 32, v0
	v_lshlrev_b64 v[2:3], v0, v[2:3]
	v_min_u32_e32 v2, 1, v2
	v_or_b32_e32 v2, v3, v2
	v_cvt_f32_u32_e32 v2, v2
	v_sub_u32_e32 v0, 32, v0
	v_and_b32_e32 v25, 0xffff0000, v44
	v_lshlrev_b32_e32 v26, 16, v45
	v_ldexp_f32 v0, v2, v0
	v_mul_f32_e32 v0, 0x33800000, v0
	v_fmamk_f32 v0, v0, 0x3b800000, v226
	v_and_b32_e32 v27, 0xffff0000, v45
	s_nop 0
	s_waitcnt lgkmcnt(0)
	s_mov_b32 s2, 0x58000
	v_add3_u32 v28, v136, v230, s2
	v_add_u32_e32 v241, s2, v240
	v_add_u32_e32 v243, s2, v242
	v_rsq_f32_e32 v0, v0
	s_nop 0
	v_lshlrev_b32_e32 v2, 16, v42
	v_and_b32_e32 v3, 0xffff0000, v42
	v_lshlrev_b32_e32 v22, 16, v43
	v_and_b32_e32 v23, 0xffff0000, v43
	v_lshlrev_b32_e32 v24, 16, v44
	v_pk_mul_f32 v[18:19], v[18:19], v[0:1] op_sel_hi:[1,0]
	v_pk_mul_f32 v[20:21], v[20:21], v[0:1] op_sel_hi:[1,0]
	v_pk_mul_f32 v[12:13], v[12:13], v[0:1] op_sel_hi:[1,0]
	v_pk_mul_f32 v[14:15], v[14:15], v[0:1] op_sel_hi:[1,0]
	v_pk_fma_f32 v[20:21], v[84:85], v[20:21], v[22:23]
	v_pk_fma_f32 v[2:3], v[82:83], v[18:19], v[2:3]
	v_pk_fma_f32 v[22:23], v[78:79], v[12:13], v[24:25]
	v_cvt_pk_bf16_f32 v12, v2, v3
	v_cvt_pk_bf16_f32 v13, v20, v21
	v_pk_fma_f32 v[18:19], v[80:81], v[14:15], v[26:27]
	v_cvt_pk_bf16_f32 v14, v22, v23
	v_pk_mul_f32 v[26:27], v[202:203], v[22:23]
	v_cvt_pk_bf16_f32 v15, v18, v19
	global_store_dwordx4 v241, v[12:15], s[24:25] nt
	v_pk_mul_f32 v[24:25], v[198:199], v[18:19]
	v_pk_mul_f32 v[8:9], v[8:9], v[0:1] op_sel_hi:[1,0]
	v_pk_mul_f32 v[12:13], v[204:205], v[2:3]
	v_mul_f32_e32 v3, v3, v3
	v_fmac_f32_e32 v3, v2, v2
	v_mul_f32_e32 v2, v21, v21
	v_fmac_f32_e32 v2, v20, v20
	v_add_f32_e32 v2, v3, v2
	v_mul_f32_e32 v3, v23, v23
	v_fmac_f32_e32 v3, v22, v22
	v_pk_mul_f32 v[14:15], v[200:201], v[20:21]
	v_add_f32_e32 v2, v3, v2
	v_mul_f32_e32 v3, v19, v19
	v_cvt_pk_bf16_f32 v12, v12, v13
	v_cvt_pk_bf16_f32 v13, v14, v15
	v_cvt_pk_bf16_f32 v14, v26, v27
	v_cvt_pk_bf16_f32 v15, v24, v25
	v_fmac_f32_e32 v3, v18, v18
	global_store_dwordx4 v243, v[12:15], s[26:27] offset:-4096
	v_add_f32_e32 v20, v3, v2
	v_lshlrev_b32_e32 v2, 16, v38
	v_and_b32_e32 v3, 0xffff0000, v38
	v_lshlrev_b32_e32 v12, 16, v39
	v_and_b32_e32 v13, 0xffff0000, v39
	v_lshlrev_b32_e32 v14, 16, v40
	v_and_b32_e32 v15, 0xffff0000, v40
	v_pk_mul_f32 v[10:11], v[10:11], v[0:1] op_sel_hi:[1,0]
	v_pk_mul_f32 v[4:5], v[4:5], v[0:1] op_sel_hi:[1,0]
	v_lshlrev_b32_e32 v18, 16, v41
	v_and_b32_e32 v19, 0xffff0000, v41
	v_pk_mul_f32 v[6:7], v[6:7], v[0:1] op_sel_hi:[1,0]
	v_pk_fma_f32 v[10:11], v[76:77], v[10:11], v[12:13]
	v_pk_fma_f32 v[8:9], v[74:75], v[8:9], v[2:3]
	v_pk_fma_f32 v[12:13], v[70:71], v[4:5], v[14:15]
	v_cvt_pk_bf16_f32 v2, v8, v9
	v_cvt_pk_bf16_f32 v3, v10, v11
	v_pk_fma_f32 v[6:7], v[72:73], v[6:7], v[18:19]
	v_cvt_pk_bf16_f32 v4, v12, v13
	v_pk_mul_f32 v[14:15], v[196:197], v[10:11]
	v_cvt_pk_bf16_f32 v5, v6, v7
	global_store_dwordx4 v241, v[2:5], s[24:25] offset:1024 nt
	v_mul_f32_e32 v0, v7, v7
	v_fmac_f32_e32 v0, v6, v6
	v_mul_f32_e32 v3, v9, v9
	v_mul_f32_e32 v4, v11, v11
	v_mul_f32_e32 v2, v13, v13
	v_fmac_f32_e32 v3, v8, v8
	v_fmac_f32_e32 v4, v10, v10
	v_fmac_f32_e32 v2, v12, v12
	v_add_f32_e32 v3, v3, v4
	v_add_f32_e32 v2, v2, v3
	v_add_f32_e32 v0, v0, v2
	v_add_f32_e32 v0, v20, v0
	ds_bpermute_b32 v5, v229, v0
	v_pk_mul_f32 v[2:3], v[174:175], v[8:9]
	v_pk_mul_f32 v[8:9], v[176:177], v[6:7]
	v_cvt_pk_bf16_f32 v4, v2, v3
	v_pk_mul_f32 v[6:7], v[194:195], v[12:13]
	s_waitcnt lgkmcnt(0)
	v_add_f32_e32 v0, v0, v5
	ds_bpermute_b32 v2, v228, v0
	v_cvt_pk_bf16_f32 v5, v14, v15
	v_cvt_pk_bf16_f32 v6, v6, v7
	v_cvt_pk_bf16_f32 v7, v8, v9
	global_store_dwordx4 v243, v[4:7], s[26:27]
	s_and_saveexec_b64 s[2:3], s[8:9]
	s_cbranch_execz .LBB0_1103
	s_waitcnt lgkmcnt(0)
	v_add_f32_e32 v0, v0, v2
	v_mul_f32_e32 v0, 0x4b800000, v0
	v_trunc_f32_e32 v0, v0
	v_mul_f32_e32 v2, 0x2f800000, v0
	v_floor_f32_e32 v3, v2
	v_fmac_f32_e32 v0, 0xcf800000, v3
	v_cvt_u32_f32_e32 v2, v0
	v_cvt_u32_f32_e32 v3, v3
	global_atomic_add_x2 v[134:135], v[2:3], off offset:1408

; __device__ __forceinline__ int opaque_tid(int wave_s) { int l; asm volatile("v_mbcnt_lo_u32_b32 %0, -1, 0\n\tv_mbcnt_hi_u32_b32 %0, -1, %0" : "=v"(l)); return (wave_s << 6) | l; }
; #define PG8_STAGE(bufoff, gbase, voff) do { _Pragma("unroll") for (int _i = 0; _i < 2; ++_i) \
;         __builtin_amdgcn_global_load_lds((const unsigned*)((const char*)(gbase) + (voff)[_i]), (PG8_LAS unsigned*)(lds + (bufoff) + ldsw + _i * 8192), 16, 0, 0); } while (0)
; #define PG8_WAIT_V(n) asm volatile("s_waitcnt vmcnt(" #n ")" ::: "memory")
; #define PG8_BAR __builtin_amdgcn_s_barrier()
; template <class Epi, class Sched, bool ALIGN_EPI = false, bool SP2 = false>
; __device__ __forceinline__ void gemm_phase(PG8_LAS unsigned char* lds, const Gemm g, const Sched& S, const Epi& E, const int wave_s) {
;     const int tid = opaque_tid(wave_s), wid = __builtin_amdgcn_readfirstlane(tid >> 6), lane = tid & 63, wr = wid >> 2, wc = wid & 3, fr = lane & 15, fq = lane >> 4;
;     const int K = g.K, nt = K / BK;
;     unsigned voffA[2], voffB[2];
; #pragma unroll
;     for (int i = 0; i < 2; ++i) { int R, C; stage_rc(tid * 16 + i * 8192, R, C); const int Rb = Epi::PERM ? ((R & ~31) + perm32(R & 31)) : R;
;         voffA[i] = (unsigned)(R * g.lda + C) * 2u; voffB[i] = (unsigned)(Rb * K + C) * 2u; }
;     const size_t kstep = (size_t)(BK * 2);
;     const size_t hstepA = (size_t)HALF * g.lda * 2, hstepB = (size_t)HALF * K * 2;
;     const size_t tstepA = 2 * hstepA, tstepB = 2 * hstepB;
;     const unsigned ldsw = (unsigned)wid * 1024u;
;     const int aoff = lds_byte(wr * 64 + fr, fq * 8), boff = lds_byte(wc * 32 + fr, fq * 8);
;     ...
;     const char* cA = (const char*)g.A + (size_t)cur.pm * tstepA; const char* cB = (const char*)g.Bt + (size_t)cur.pn * tstepB;
;     S.a_ready(cur);
;     if constexpr (SP2) {
;         PG8_STAGE(PG8_SB(0, 0), cB, voffB); PG8_STAGE(PG8_SB(0, 1), cB + hstepB, voffB); PG8_STAGE(PG8_SA(0, 0), cA, voffA); PG8_STAGE(PG8_SA(0, 1), cA + hstepA, voffA);
;         if (wr == 1) PG8_BAR;
;         PG8_WAIT_V(2); PG8_BAR;
;         PG8_STAGE(PG8_SB(1, 0), cB + kstep, voffB); PG8_STAGE(PG8_SA(1, 0), cA + kstep, voffA); PG8_STAGE(PG8_SB(1, 1), cB + hstepB + kstep, voffB);
;         PG8_WAIT_V(6); PG8_BAR;
.LBB0_1157:
	s_or_b64 exec, exec, s[14:15]
	v_ashrrev_i32_e32 v5, 31, v2
	v_lshrrev_b32_e32 v5, 26, v5
	v_lshlrev_b32_e32 v4, 4, v2
	v_add_u32_e32 v5, v2, v5
	v_bfe_i32 v2, v2, 27, 1
	v_lshrrev_b32_e32 v2, 22, v2
	v_add_u32_e32 v2, v4, v2
	v_and_b32_e32 v2, 0xfffffc00, v2
	v_sub_u32_e32 v2, v4, v2
	v_ashrrev_i32_e32 v11, 6, v5
	v_lshrrev_b32_e32 v5, 4, v2
	v_bitop3_b32 v2, v5, v2, 32 bitop3:0x6c
	v_ashrrev_i32_e32 v6, 31, v2
	s_ashr_i32 s37, s34, 31
	v_lshrrev_b32_e32 v6, 26, v6
	s_add_u32 s40, s12, 0x35000000
	v_add_u32_e32 v6, v2, v6
	s_addc_u32 s41, s13, 0
	s_mul_i32 s3, s30, 0xb00000
	v_lshlrev_b32_e32 v5, 3, v11
	v_ashrrev_i32_e32 v12, 6, v6
	v_and_b32_e32 v6, 0xc0, v6
	s_mul_hi_u32 s2, s30, 0xb00000
	s_add_u32 s3, s4, s3
	v_and_b32_e32 v5, -16, v5
	v_sub_u32_e32 v2, v2, v6
	v_mov_b32_e32 v9, 1
	s_addc_u32 s2, s5, s2
	v_add_u32_e32 v5, v12, v5
	v_ashrrev_i16_sdwa v2, v9, sext(v2) dst_sel:DWORD dst_unused:UNUSED_PAD src0_sel:DWORD src1_sel:BYTE_0
	s_add_u32 s42, s3, 0x1d00000
	v_lshlrev_b32_e32 v7, 5, v11
	v_bfe_i32 v13, v2, 0, 16
	v_lshlrev_b32_e32 v2, 1, v5
	v_lshrrev_b32_e32 v6, 2, v5
	v_and_b32_e32 v8, 3, v12
	s_mov_b32 s3, 0x1fffe0
	v_and_b32_e32 v7, 32, v7
	v_and_b32_e32 v2, 24, v2
	v_and_b32_e32 v6, 4, v6
	v_and_or_b32 v8, v5, s3, v8
	v_or3_b32 v2, v8, v6, v2
	v_add_lshl_u32 v6, v7, v13, 1
	v_lshl_add_u32 v150, v2, 11, v6
	v_add_u32_e32 v2, 0x2000, v4
	v_ashrrev_i32_e32 v4, 31, v2
	v_lshrrev_b32_e32 v4, 22, v4
	v_add_u32_e32 v4, v2, v4
	v_ashrrev_i32_e32 v18, 10, v4
	v_mul_i32_i24_e32 v4, 0x400, v18
	v_sub_u32_e32 v2, v2, v4
	v_lshrrev_b32_e32 v4, 4, v2
	v_bitop3_b32 v2, v4, v2, 32 bitop3:0x6c
	v_lshl_add_u32 v14, v5, 11, v6
	v_and_b32_e32 v250, 0xffff8000, v14
	v_bfe_u32 v251, v14, 11, 4
	v_lshl_or_b32 v250, v251, 6, v250
	v_bfe_u32 v251, v14, 6, 1
	v_lshl_or_b32 v250, v251, 10, v250
	v_and_b32_e32 v251, 63, v14
	v_or_b32_e32 v14, v250, v251
	v_mov_b32_e32 v248, 0x800
	v_mov_b32_e32 v249, 0
	v_ashrrev_i32_e32 v5, 31, v2
	v_lshrrev_b32_e32 v5, 26, v5
	v_lshlrev_b32_e32 v4, 3, v18
	v_add_u32_e32 v5, v2, v5
	v_and_b32_e32 v4, -16, v4
	v_ashrrev_i32_e32 v19, 6, v5
	v_add_u32_e32 v4, v19, v4
	v_and_b32_e32 v7, 3, v19
	s_addc_u32 s43, s2, 0
	v_and_b32_e32 v5, 0xc0, v5
	v_and_or_b32 v7, v4, s3, v7
	s_ashr_i32 s3, s16, 6
	s_ashr_i32 s29, s28, 31
	s_ashr_i32 s27, s26, 31
	s_ashr_i32 s2, s16, 8
	v_sub_u32_e32 v2, v2, v5
	s_lshl_b32 s44, s3, 10
	s_lshl_b64 s[4:5], s[28:29], 19
	s_lshl_b64 s[6:7], s[26:27], 19
	v_ashrrev_i16_sdwa v2, v9, sext(v2) dst_sel:DWORD dst_unused:UNUSED_PAD src0_sel:DWORD src1_sel:BYTE_0
	s_add_u32 s6, s42, s6
	v_lshlrev_b32_e32 v6, 5, v18
	v_bfe_i32 v20, v2, 0, 16
	v_lshlrev_b32_e32 v2, 1, v4
	v_lshrrev_b32_e32 v5, 2, v4
	v_lshl_add_u32 v0, v0, 2, 0
	s_addc_u32 s7, s43, s7
	s_add_i32 s27, s44, 0
	v_and_b32_e32 v6, 32, v6
	v_and_b32_e32 v2, 24, v2
	v_and_b32_e32 v5, 4, v5
	v_add_u32_e32 v0, 0x21400, v0
	s_add_i32 m0, s27, 0x10000
	v_or3_b32 v2, v7, v5, v2
	v_add_lshl_u32 v5, v6, v20, 1
	s_waitcnt vmcnt(0) lgkmcnt(0)
	ds_write_b32 v0, v3
	global_load_lds_dwordx4 v150, s[6:7]
	s_add_i32 m0, s27, 0x12000
	v_lshl_add_u32 v154, v2, 11, v5
	s_add_u32 s12, s6, 0x40000
	global_load_lds_dwordx4 v154, s[6:7]
	s_addc_u32 s13, s7, 0
	s_add_i32 m0, s27, 0x14000
	v_lshl_add_u32 v152, v4, 11, v5
	v_and_b32_e32 v250, 0xffff8000, v152
	v_bfe_u32 v251, v152, 11, 4
	v_lshl_or_b32 v250, v251, 6, v250
	v_bfe_u32 v251, v152, 6, 1
	v_lshl_or_b32 v250, v251, 10, v250
	v_and_b32_e32 v251, 63, v152
	v_or_b32_e32 v152, v250, v251
	global_load_lds_dwordx4 v150, s[12:13]
	s_add_i32 m0, s27, 0x16000
	s_add_u32 s30, s40, s4
	s_addc_u32 s31, s41, s5
	s_add_i32 s29, s27, 0x2000
	global_load_lds_dwordx4 v154, s[12:13]
	s_mov_b32 m0, s27
	s_add_u32 s4, s30, 0x40000
	global_load_lds_dwordx4 v14, s[30:31]
	s_mov_b32 m0, s29
	s_addc_u32 s5, s31, 0
	s_add_i32 s45, s27, 0x4000
	global_load_lds_dwordx4 v152, s[30:31]
	s_mov_b32 m0, s45
	s_add_i32 s46, s27, 0x6000
	global_load_lds_dwordx4 v14, s[4:5]
	s_mov_b32 m0, s46
	v_mov_b32_e32 v151, v1
	global_load_lds_dwordx4 v152, s[4:5]
	v_mov_b32_e32 v155, v1
	v_mov_b32_e32 v15, v1
	v_mov_b32_e32 v153, v1
	s_cmp_eq_u32 s2, 1
	v_lshl_add_u64 v[8:9], s[6:7], 0, v[150:151]
	v_lshl_add_u64 v[6:7], s[6:7], 0, v[154:155]
	v_lshl_add_u64 v[2:3], s[30:31], 0, v[14:15]
	s_cselect_b64 s[12:13], -1, 0
	s_cmp_lg_u32 s2, 1
	v_lshl_add_u64 v[4:5], s[30:31], 0, v[152:153]
	s_cbranch_scc1 .LBB0_1159
	s_barrier
.LBB0_1159:
	s_add_u32 s14, s8, 0x10000000
	v_and_b32_e32 v0, 48, v10
	v_lshlrev_b32_e32 v17, 6, v10
	s_movk_i32 s4, 0x3c0
	v_lshlrev_b32_e32 v10, 2, v10
	s_addc_u32 s15, s9, 0
	s_lshl_b32 s47, s2, 6
	s_lshl_b32 s2, s2, 13
	v_and_or_b32 v0, v17, s4, v0
	v_and_b32_e32 v10, 32, v10
	v_bitop3_b32 v21, v0, s2, v10 bitop3:0xde
	s_lshl_b32 s2, s3, 5
	s_and_b32 s48, s2, 0x60
	s_add_i32 m0, s27, 0x18000
	v_lshl_add_u64 v[8:9], v[8:9], 0, s[58:59]
	s_lshl_b32 s2, s48, 7
	s_waitcnt vmcnt(2)
	s_barrier
	global_load_lds_dwordx4 v[8:9], off
	v_lshl_add_u64 v[6:7], v[6:7], 0, s[58:59]
	s_add_i32 m0, s27, 0x1a000
	s_add_i32 s49, s27, 0x8000
	s_add_i32 s50, s27, 0xa000
	v_bitop3_b32 v17, s2, v0, v10 bitop3:0xf6
	global_load_lds_dwordx4 v[6:7], off
	v_lshl_add_u64 v[2:3], v[2:3], 0, v[248:249]
	s_mov_b32 m0, s49
	s_add_u32 s2, s6, 0x40080
	global_load_lds_dwordx4 v[2:3], off
	v_lshl_add_u64 v[2:3], v[4:5], 0, v[248:249]
	s_mov_b32 m0, s50
	s_addc_u32 s3, s7, 0
	global_load_lds_dwordx4 v[2:3], off
	s_add_i32 m0, s27, 0x1c000
	v_lshl_add_u64 v[2:3], s[2:3], 0, v[150:151]
	global_load_lds_dwordx4 v[2:3], off
	v_lshl_add_u64 v[2:3], s[2:3], 0, v[154:155]
	s_add_i32 m0, s27, 0x1e000
	v_lshlrev_b32_e32 v0, 14, v18
	global_load_lds_dwordx4 v[2:3], off
	v_and_b32_e32 v0, 0xffff8000, v0
	v_lshl_add_u32 v0, v19, 11, v0
	v_and_b32_e32 v2, 1, v18
	v_lshl_or_b32 v0, v2, 6, v0
	v_lshl_add_u32 v156, v20, 1, v0
	v_and_b32_e32 v250, 0xffff8000, v156
	v_bfe_u32 v251, v156, 11, 4
	v_lshl_or_b32 v250, v251, 6, v250
	v_bfe_u32 v251, v156, 6, 1
	v_lshl_or_b32 v250, v251, 10, v250
	v_and_b32_e32 v251, 63, v156
	v_or_b32_e32 v156, v250, v251
	v_lshlrev_b32_e32 v0, 14, v11
	v_and_b32_e32 v0, 0xffff8000, v0
	s_waitcnt vmcnt(6)
	v_lshl_add_u32 v0, v12, 11, v0
	v_and_b32_e32 v2, 1, v11
	s_cmpk_lt_u32 s16, 0x100
	v_lshl_or_b32 v0, v2, 6, v0
	s_cselect_b64 s[16:17], -1, 0
	v_mov_b32_e32 v157, v1
	v_lshl_add_u32 v158, v13, 1, v0
	v_and_b32_e32 v250, 0xffff8000, v158
	v_bfe_u32 v251, v158, 11, 4
	v_lshl_or_b32 v250, v251, 6, v250
	v_bfe_u32 v251, v158, 6, 1
	v_lshl_or_b32 v250, v251, 10, v250
	v_and_b32_e32 v251, 63, v158
	v_or_b32_e32 v158, v250, v251
	v_mov_b32_e32 v159, v1
	s_mov_b32 s52, 0
	v_add_u32_e32 v166, 0, v21
	s_barrier
	s_branch .LBB0_1162

; __device__ __forceinline__ int opaque_tid(int wave_s) { int l; asm volatile("v_mbcnt_lo_u32_b32 %0, -1, 0\n\tv_mbcnt_hi_u32_b32 %0, -1, %0" : "=v"(l)); return (wave_s << 6) | l; }
; #define PG8_STAGE(bufoff, gbase, voff) do { _Pragma("unroll") for (int _i = 0; _i < 2; ++_i) \
;         __builtin_amdgcn_global_load_lds((const unsigned*)((const char*)(gbase) + (voff)[_i]), (PG8_LAS unsigned*)(lds + (bufoff) + ldsw + _i * 8192), 16, 0, 0); } while (0)
; #define PG8_LDA(dst, b, h) do { _Pragma("unroll") for (int m = 0; m < 4; ++m) _Pragma("unroll") for (int k = 0; k < 2; ++k) dst[m][k] = *(const PG8_LAS bf16x8*)(lds + PG8_SA(b, h) + aoff + m * 2048 + k * 1024); } while (0)
; #define PG8_LDB(dst, b, h) do { _Pragma("unroll") for (int n = 0; n < 2; ++n) _Pragma("unroll") for (int k = 0; k < 2; ++k) dst[n][k] = *(const PG8_LAS bf16x8*)(lds + PG8_SB(b, h) + boff + n * 2048 + k * 1024); } while (0)
; template <class Epi, class Sched, bool ALIGN_EPI = false, bool SP2 = false>
; __device__ __forceinline__ void gemm_phase(PG8_LAS unsigned char* lds, const Gemm g, const Sched& S, const Epi& E, const int wave_s) {
;     ...
;         const bool has_next = S.next(ui + 1, nxt);
;         const char* nA = has_next ? (const char*)g.A + (size_t)nxt.pm * tstepA : cA; const char* nB = has_next ? (const char*)g.Bt + (size_t)nxt.pn * tstepB : cB;
;         for (int t = 0; t < nt; t += 2) {
;             if constexpr (Epi::KHOOK) { if (t == 6 || t == 12) { const int l3_ = opaque_tid(wave_s) & 63; E.khook(acc, t, wr, l3_ & 15, ui & 1, lds); } }
;             const bool last = (t == nt - 2);
;             const char* a1 = cA + (size_t)(t + 1) * kstep;
;             const char* a2 = last ? nA : cA + (size_t)(t + 2) * kstep; const char* b2 = last ? nB : cB + (size_t)(t + 2) * kstep;
;             const char* a3 = a2 + kstep; const char* b3 = b2 + kstep;
;             if (last && has_next) S.a_ready(nxt);
;             if constexpr (SP2) {
;             PG8_LDB(B0, 0, 0); PG8_LDB(B1, 0, 1); PG8_SCHED; PG8_LDA(At, 0, 0); PG8_STAGE(PG8_SA(1, 1), a1 + hstepA, voffA);
;     ...
; #pragma unroll
;         for (int a = 0; a < 2; ++a)
; #pragma unroll
;             for (int b = 0; b < 2; ++b)
; #pragma unroll
;                 for (int m = 0; m < 4; ++m)
; #pragma unroll
;                     for (int n = 0; n < 2; ++n) acc[a][b][m][n] = (f32x4){0.f, 0.f, 0.f, 0.f};
;         cur = nxt; cA = nA; cB = nB; ++ui;
.LBB0_1164:
	s_ashr_i32 s19, s18, 31
	s_lshl_b64 s[2:3], s[18:19], 19
	s_add_u32 s22, s40, s2
	s_addc_u32 s23, s41, s3
	s_and_b64 s[2:3], s[8:9], exec
	s_cselect_b32 s2, s23, s31
	s_cselect_b32 s3, s22, s30
	s_ashr_i32 s21, s20, 31
	s_lshl_b64 s[4:5], s[20:21], 19
	s_add_u32 s24, s42, s4
	s_addc_u32 s25, s43, s5
	s_and_b64 s[4:5], s[8:9], exec
	s_cselect_b32 s19, s25, s7
	s_cselect_b32 s21, s24, s6
	s_add_u32 s54, s6, 0x100
	s_addc_u32 s55, s7, 0
	s_add_u32 s6, s30, 0x40800
	v_mov_b32_e32 v2, 0
	s_addc_u32 s7, s31, 0
	s_mov_b32 s56, -2
	v_mov_b32_e32 v3, v2
	v_mov_b32_e32 v4, v2
	v_mov_b32_e32 v5, v2
	v_mov_b32_e32 v6, v2
	v_mov_b32_e32 v7, v2
	v_mov_b32_e32 v8, v2
	v_mov_b32_e32 v9, v2
	v_mov_b32_e32 v22, v2
	v_mov_b32_e32 v23, v2
	v_mov_b32_e32 v24, v2
	v_mov_b32_e32 v25, v2
	v_mov_b32_e32 v26, v2
	v_mov_b32_e32 v27, v2
	v_mov_b32_e32 v28, v2
	v_mov_b32_e32 v29, v2
	v_mov_b32_e32 v38, v2
	v_mov_b32_e32 v39, v2
	v_mov_b32_e32 v40, v2
	v_mov_b32_e32 v41, v2
	v_mov_b32_e32 v42, v2
	v_mov_b32_e32 v43, v2
	v_mov_b32_e32 v44, v2
	v_mov_b32_e32 v45, v2
	v_mov_b32_e32 v54, v2
	v_mov_b32_e32 v55, v2
	v_mov_b32_e32 v56, v2
	v_mov_b32_e32 v57, v2
	v_mov_b32_e32 v58, v2
	v_mov_b32_e32 v59, v2
	v_mov_b32_e32 v60, v2
	v_mov_b32_e32 v61, v2
	v_mov_b32_e32 v10, v2
	v_mov_b32_e32 v11, v2
	v_mov_b32_e32 v12, v2
	v_mov_b32_e32 v13, v2
	v_mov_b32_e32 v18, v2
	v_mov_b32_e32 v19, v2
	v_mov_b32_e32 v20, v2
	v_mov_b32_e32 v21, v2
	v_mov_b32_e32 v30, v2
	v_mov_b32_e32 v31, v2
	v_mov_b32_e32 v32, v2
	v_mov_b32_e32 v33, v2
	v_mov_b32_e32 v34, v2
	v_mov_b32_e32 v35, v2
	v_mov_b32_e32 v36, v2
	v_mov_b32_e32 v37, v2
	v_mov_b32_e32 v46, v2
	v_mov_b32_e32 v47, v2
	v_mov_b32_e32 v48, v2
	v_mov_b32_e32 v49, v2
	v_mov_b32_e32 v50, v2
	v_mov_b32_e32 v51, v2
	v_mov_b32_e32 v52, v2
	v_mov_b32_e32 v53, v2
	v_mov_b32_e32 v62, v2
	v_mov_b32_e32 v63, v2
	v_mov_b32_e32 v64, v2
	v_mov_b32_e32 v65, v2
	v_mov_b32_e32 v66, v2
	v_mov_b32_e32 v67, v2
	v_mov_b32_e32 v68, v2
	v_mov_b32_e32 v69, v2
	v_mov_b32_e32 v70, v2
	v_mov_b32_e32 v71, v2
	v_mov_b32_e32 v72, v2
	v_mov_b32_e32 v73, v2
	v_mov_b32_e32 v74, v2
	v_mov_b32_e32 v75, v2
	v_mov_b32_e32 v76, v2
	v_mov_b32_e32 v77, v2
	v_mov_b32_e32 v86, v2
	v_mov_b32_e32 v87, v2
	v_mov_b32_e32 v88, v2
	v_mov_b32_e32 v89, v2
	v_mov_b32_e32 v94, v2
	v_mov_b32_e32 v95, v2
	v_mov_b32_e32 v96, v2
	v_mov_b32_e32 v97, v2
	v_mov_b32_e32 v118, v2
	v_mov_b32_e32 v119, v2
	v_mov_b32_e32 v120, v2
	v_mov_b32_e32 v121, v2
	v_mov_b32_e32 v122, v2
	v_mov_b32_e32 v123, v2
	v_mov_b32_e32 v124, v2
	v_mov_b32_e32 v125, v2
	v_mov_b32_e32 v134, v2
	v_mov_b32_e32 v135, v2
	v_mov_b32_e32 v136, v2
	v_mov_b32_e32 v137, v2
	v_mov_b32_e32 v138, v2
	v_mov_b32_e32 v139, v2
	v_mov_b32_e32 v140, v2
	v_mov_b32_e32 v141, v2
	v_mov_b32_e32 v78, v2
	v_mov_b32_e32 v79, v2
	v_mov_b32_e32 v80, v2
	v_mov_b32_e32 v81, v2
	v_mov_b32_e32 v82, v2
	v_mov_b32_e32 v83, v2
	v_mov_b32_e32 v84, v2
	v_mov_b32_e32 v85, v2
	v_mov_b32_e32 v110, v2
	v_mov_b32_e32 v111, v2
	v_mov_b32_e32 v112, v2
	v_mov_b32_e32 v113, v2
	v_mov_b32_e32 v114, v2
	v_mov_b32_e32 v115, v2
	v_mov_b32_e32 v116, v2
	v_mov_b32_e32 v117, v2
	v_mov_b32_e32 v126, v2
	v_mov_b32_e32 v127, v2
	v_mov_b32_e32 v128, v2
	v_mov_b32_e32 v129, v2
	v_mov_b32_e32 v130, v2
	v_mov_b32_e32 v131, v2
	v_mov_b32_e32 v132, v2
	v_mov_b32_e32 v133, v2
	v_mov_b32_e32 v142, v2
	v_mov_b32_e32 v143, v2
	v_mov_b32_e32 v144, v2
	v_mov_b32_e32 v145, v2
	v_mov_b32_e32 v146, v2
	v_mov_b32_e32 v147, v2
	v_mov_b32_e32 v148, v2
	v_mov_b32_e32 v149, v2
.LBB0_1165:
	s_add_u32 s4, s6, 0xfffc0800
	s_addc_u32 s5, s7, -1
	s_add_i32 s57, 0, 0x10000
	s_cmp_eq_u32 s56, 12
	s_cselect_b32 s31, s2, s5
	s_cselect_b32 s30, s3, s4
	v_add_u32_e32 v0, s57, v17
	s_cselect_b32 s5, s19, s55
	s_cselect_b32 s4, s21, s54
	s_add_i32 s73, 0, 0x14000
	ds_read_b128 v[90:93], v0
	ds_read_b128 v[98:101], v0 offset:1024
	ds_read_b128 v[102:105], v0 offset:2048
	ds_read_b128 v[106:109], v0 offset:3072
	v_add_u32_e32 v0, s73, v17
	ds_read_b128 v[160:163], v0
	ds_read_b128 v[168:171], v0 offset:1024
	ds_read_b128 v[172:175], v0 offset:2048
	ds_read_b128 v[176:179], v0 offset:3072
	v_lshl_add_u64 v[164:165], s[6:7], 0, v[158:159]
	s_add_i32 m0, s27, 0xc000
	ds_read_b128 v[180:183], v166
	ds_read_b128 v[184:187], v166 offset:1024
	ds_read_b128 v[188:191], v166 offset:2048
	ds_read_b128 v[192:195], v166 offset:3072
	ds_read_b128 v[196:199], v166 offset:4096
	ds_read_b128 v[200:203], v166 offset:5120
	ds_read_b128 v[204:207], v166 offset:6144
	ds_read_b128 v[208:211], v166 offset:7168
	global_load_lds_dwordx4 v[164:165], off
	v_lshl_add_u64 v[164:165], s[6:7], 0, v[156:157]
	s_add_i32 m0, s27, 0xe000
	s_nop 0
	global_load_lds_dwordx4 v[164:165], off
	s_waitcnt vmcnt(8)
	s_waitcnt lgkmcnt(0)
	s_barrier
; #define PG8_STAGE(bufoff, gbase, voff) do { _Pragma("unroll") for (int _i = 0; _i < 2; ++_i) \
;         __builtin_amdgcn_global_load_lds((const unsigned*)((const char*)(gbase) + (voff)[_i]), (PG8_LAS unsigned*)(lds + (bufoff) + ldsw + _i * 8192), 16, 0, 0); } while (0)
; #define PG8_LDA(dst, b, h) do { _Pragma("unroll") for (int m = 0; m < 4; ++m) _Pragma("unroll") for (int k = 0; k < 2; ++k) dst[m][k] = *(const PG8_LAS bf16x8*)(lds + PG8_SA(b, h) + aoff + m * 2048 + k * 1024); } while (0)
; #define PG8_LDB(dst, b, h) do { _Pragma("unroll") for (int n = 0; n < 2; ++n) _Pragma("unroll") for (int k = 0; k < 2; ++k) dst[n][k] = *(const PG8_LAS bf16x8*)(lds + PG8_SB(b, h) + boff + n * 2048 + k * 1024); } while (0)
; #define PG8_MMA(ai, bj, At, Bt) do { __builtin_amdgcn_s_setprio(1); _Pragma("unroll") for (int m = 0; m < 4; ++m) _Pragma("unroll") for (int n = 0; n < 2; ++n) _Pragma("unroll") for (int k = 0; k < 2; ++k) \
;         acc[ai][bj][m][n] = __builtin_amdgcn_mfma_f32_16x16x32_bf16(Bt[n][k], At[m][k], acc[ai][bj][m][n], 0, 0, 0); __builtin_amdgcn_s_setprio(0); } while (0)
; #define PG8_WAIT_V(n) asm volatile("s_waitcnt vmcnt(" #n ")" ::: "memory")
; #define PG8_WAIT_L(n) asm volatile("s_waitcnt lgkmcnt(" #n ")" ::: "memory")
; #define PG8_BAR __builtin_amdgcn_s_barrier()
; #define PG8_SCHED __builtin_amdgcn_sched_barrier(0)
; template <class Epi, class Sched, bool ALIGN_EPI = false, bool SP2 = false>
; __device__ __forceinline__ void gemm_phase(PG8_LAS unsigned char* lds, const Gemm g, const Sched& S, const Epi& E, const int wave_s) {
;     ...
;             PG8_LDB(B0, 0, 0); PG8_LDB(B1, 0, 1); PG8_SCHED; PG8_LDA(At, 0, 0); PG8_STAGE(PG8_SA(1, 1), a1 + hstepA, voffA);
;             PG8_WAIT_V(8); PG8_WAIT_L(0); PG8_BAR; PG8_MMA(0, 0, At, B0); PG8_MMA(0, 1, At, B1); PG8_BAR; PG8_SCHED;
;             PG8_LDA(At, 0, 1); PG8_STAGE(PG8_SB(0, 0), b2, voffB); PG8_STAGE(PG8_SB(0, 1), b2 + hstepB, voffB); PG8_STAGE(PG8_SA(0, 0), a2, voffA);
;             PG8_WAIT_V(8); PG8_WAIT_L(0); PG8_BAR; PG8_MMA(1, 0, At, B0); PG8_MMA(1, 1, At, B1); PG8_BAR; PG8_SCHED;
	s_setprio 1
	s_waitcnt lgkmcnt(0)
	v_mfma_f32_16x16x32_bf16 v[146:149], v[90:93], v[180:183], v[146:149]
	v_mfma_f32_16x16x32_bf16 v[142:145], v[102:105], v[180:183], v[142:145]
	v_mfma_f32_16x16x32_bf16 v[130:133], v[90:93], v[188:191], v[130:133]
	v_mfma_f32_16x16x32_bf16 v[126:129], v[102:105], v[188:191], v[126:129]
	v_mfma_f32_16x16x32_bf16 v[114:117], v[90:93], v[196:199], v[114:117]
	v_mfma_f32_16x16x32_bf16 v[110:113], v[102:105], v[196:199], v[110:113]
	v_mfma_f32_16x16x32_bf16 v[82:85], v[90:93], v[204:207], v[82:85]
	v_mfma_f32_16x16x32_bf16 v[78:81], v[102:105], v[204:207], v[78:81]
	v_mfma_f32_16x16x32_bf16 v[146:149], v[98:101], v[184:187], v[146:149]
	v_mfma_f32_16x16x32_bf16 v[142:145], v[106:109], v[184:187], v[142:145]
	v_mfma_f32_16x16x32_bf16 v[130:133], v[98:101], v[192:195], v[130:133]
	v_mfma_f32_16x16x32_bf16 v[126:129], v[106:109], v[192:195], v[126:129]
	v_mfma_f32_16x16x32_bf16 v[114:117], v[98:101], v[200:203], v[114:117]
	v_mfma_f32_16x16x32_bf16 v[110:113], v[106:109], v[200:203], v[110:113]
	v_mfma_f32_16x16x32_bf16 v[82:85], v[98:101], v[208:211], v[82:85]
	v_mfma_f32_16x16x32_bf16 v[78:81], v[106:109], v[208:211], v[78:81]
	s_setprio 0
	s_setprio 1
	v_mfma_f32_16x16x32_bf16 v[138:141], v[160:163], v[180:183], v[138:141]
	v_mfma_f32_16x16x32_bf16 v[134:137], v[172:175], v[180:183], v[134:137]
	v_mfma_f32_16x16x32_bf16 v[122:125], v[160:163], v[188:191], v[122:125]
	v_mfma_f32_16x16x32_bf16 v[118:121], v[172:175], v[188:191], v[118:121]
	v_mfma_f32_16x16x32_bf16 v[94:97], v[160:163], v[196:199], v[94:97]
	v_mfma_f32_16x16x32_bf16 v[86:89], v[172:175], v[196:199], v[86:89]
	v_mfma_f32_16x16x32_bf16 v[74:77], v[160:163], v[204:207], v[74:77]
	v_mfma_f32_16x16x32_bf16 v[70:73], v[172:175], v[204:207], v[70:73]
	v_mfma_f32_16x16x32_bf16 v[138:141], v[168:171], v[184:187], v[138:141]
	v_mfma_f32_16x16x32_bf16 v[134:137], v[176:179], v[184:187], v[134:137]
	v_mfma_f32_16x16x32_bf16 v[122:125], v[168:171], v[192:195], v[122:125]
	v_mfma_f32_16x16x32_bf16 v[118:121], v[176:179], v[192:195], v[118:121]
	v_mfma_f32_16x16x32_bf16 v[94:97], v[168:171], v[200:203], v[94:97]
	v_mfma_f32_16x16x32_bf16 v[86:89], v[176:179], v[200:203], v[86:89]
	v_mfma_f32_16x16x32_bf16 v[74:77], v[168:171], v[208:211], v[74:77]
	v_mfma_f32_16x16x32_bf16 v[70:73], v[176:179], v[208:211], v[70:73]
	s_setprio 0
	s_barrier
	s_add_i32 s57, s57, s44
	v_lshl_add_u64 v[164:165], s[4:5], 0, v[150:151]
	s_mov_b32 m0, s57
	ds_read_b128 v[180:183], v166 offset:16384
	ds_read_b128 v[184:187], v166 offset:17408
	ds_read_b128 v[188:191], v166 offset:18432
	ds_read_b128 v[192:195], v166 offset:19456
	ds_read_b128 v[196:199], v166 offset:20480
	ds_read_b128 v[200:203], v166 offset:21504
	ds_read_b128 v[204:207], v166 offset:22528
	ds_read_b128 v[208:211], v166 offset:23552
	global_load_lds_dwordx4 v[164:165], off
	s_add_i32 m0, s57, 0x2000
	s_add_u32 s66, s4, 0x40000
	v_lshl_add_u64 v[212:213], s[4:5], 0, v[154:155]
	s_addc_u32 s67, s5, 0
	s_add_i32 s57, s73, s44
	global_load_lds_dwordx4 v[212:213], off
	v_lshl_add_u64 v[214:215], s[66:67], 0, v[150:151]
	s_mov_b32 m0, s57
	v_lshl_add_u64 v[216:217], s[30:31], 0, v[152:153]
	global_load_lds_dwordx4 v[214:215], off
	v_lshl_add_u64 v[214:215], s[66:67], 0, v[154:155]
	s_add_i32 m0, s57, 0x2000
	s_nop 0
	global_load_lds_dwordx4 v[214:215], off
	v_lshl_add_u64 v[214:215], s[30:31], 0, v[14:15]
	s_mov_b32 m0, s27
	s_nop 0
	global_load_lds_dwordx4 v[214:215], off
	s_mov_b32 m0, s29
	s_nop 0
	global_load_lds_dwordx4 v[216:217], off
	s_waitcnt vmcnt(8)
	s_waitcnt lgkmcnt(0)
	s_barrier
	s_setprio 1
	s_waitcnt lgkmcnt(0)
	v_mfma_f32_16x16x32_bf16 v[66:69], v[90:93], v[180:183], v[66:69]
	v_mfma_f32_16x16x32_bf16 v[62:65], v[102:105], v[180:183], v[62:65]
	v_mfma_f32_16x16x32_bf16 v[50:53], v[90:93], v[188:191], v[50:53]
	v_mfma_f32_16x16x32_bf16 v[46:49], v[102:105], v[188:191], v[46:49]
	v_mfma_f32_16x16x32_bf16 v[34:37], v[90:93], v[196:199], v[34:37]
	v_mfma_f32_16x16x32_bf16 v[30:33], v[102:105], v[196:199], v[30:33]
	v_mfma_f32_16x16x32_bf16 v[18:21], v[90:93], v[204:207], v[18:21]
	v_mfma_f32_16x16x32_bf16 v[10:13], v[102:105], v[204:207], v[10:13]
	v_mfma_f32_16x16x32_bf16 v[66:69], v[98:101], v[184:187], v[66:69]
	v_mfma_f32_16x16x32_bf16 v[62:65], v[106:109], v[184:187], v[62:65]
	v_mfma_f32_16x16x32_bf16 v[50:53], v[98:101], v[192:195], v[50:53]
	v_mfma_f32_16x16x32_bf16 v[46:49], v[106:109], v[192:195], v[46:49]
	v_mfma_f32_16x16x32_bf16 v[34:37], v[98:101], v[200:203], v[34:37]
	v_mfma_f32_16x16x32_bf16 v[30:33], v[106:109], v[200:203], v[30:33]
	v_mfma_f32_16x16x32_bf16 v[18:21], v[98:101], v[208:211], v[18:21]
	v_mfma_f32_16x16x32_bf16 v[10:13], v[106:109], v[208:211], v[10:13]
	s_setprio 0
	s_setprio 1
	v_mfma_f32_16x16x32_bf16 v[58:61], v[160:163], v[180:183], v[58:61]
	v_mfma_f32_16x16x32_bf16 v[54:57], v[172:175], v[180:183], v[54:57]
	v_mfma_f32_16x16x32_bf16 v[42:45], v[160:163], v[188:191], v[42:45]
	v_mfma_f32_16x16x32_bf16 v[38:41], v[172:175], v[188:191], v[38:41]
	v_mfma_f32_16x16x32_bf16 v[26:29], v[160:163], v[196:199], v[26:29]
	v_mfma_f32_16x16x32_bf16 v[22:25], v[172:175], v[196:199], v[22:25]
	v_mfma_f32_16x16x32_bf16 v[6:9], v[160:163], v[204:207], v[6:9]
	v_mfma_f32_16x16x32_bf16 v[2:5], v[172:175], v[204:207], v[2:5]
	v_mfma_f32_16x16x32_bf16 v[58:61], v[168:171], v[184:187], v[58:61]
	v_mfma_f32_16x16x32_bf16 v[54:57], v[176:179], v[184:187], v[54:57]
	v_mfma_f32_16x16x32_bf16 v[42:45], v[168:171], v[192:195], v[42:45]
	v_mfma_f32_16x16x32_bf16 v[38:41], v[176:179], v[192:195], v[38:41]
	v_mfma_f32_16x16x32_bf16 v[26:29], v[168:171], v[200:203], v[26:29]
	v_mfma_f32_16x16x32_bf16 v[22:25], v[176:179], v[200:203], v[22:25]
	v_mfma_f32_16x16x32_bf16 v[6:9], v[168:171], v[208:211], v[6:9]
	v_mfma_f32_16x16x32_bf16 v[2:5], v[176:179], v[208:211], v[2:5]
	s_setprio 0
	s_barrier
; #define PG8_STAGE(bufoff, gbase, voff) do { _Pragma("unroll") for (int _i = 0; _i < 2; ++_i) \
;         __builtin_amdgcn_global_load_lds((const unsigned*)((const char*)(gbase) + (voff)[_i]), (PG8_LAS unsigned*)(lds + (bufoff) + ldsw + _i * 8192), 16, 0, 0); } while (0)
; #define PG8_LDA(dst, b, h) do { _Pragma("unroll") for (int m = 0; m < 4; ++m) _Pragma("unroll") for (int k = 0; k < 2; ++k) dst[m][k] = *(const PG8_LAS bf16x8*)(lds + PG8_SA(b, h) + aoff + m * 2048 + k * 1024); } while (0)
; #define PG8_LDB(dst, b, h) do { _Pragma("unroll") for (int n = 0; n < 2; ++n) _Pragma("unroll") for (int k = 0; k < 2; ++k) dst[n][k] = *(const PG8_LAS bf16x8*)(lds + PG8_SB(b, h) + boff + n * 2048 + k * 1024); } while (0)
; #define PG8_MMA(ai, bj, At, Bt) do { __builtin_amdgcn_s_setprio(1); _Pragma("unroll") for (int m = 0; m < 4; ++m) _Pragma("unroll") for (int n = 0; n < 2; ++n) _Pragma("unroll") for (int k = 0; k < 2; ++k) \
;         acc[ai][bj][m][n] = __builtin_amdgcn_mfma_f32_16x16x32_bf16(Bt[n][k], At[m][k], acc[ai][bj][m][n], 0, 0, 0); __builtin_amdgcn_s_setprio(0); } while (0)
; #define PG8_WAIT_V(n) asm volatile("s_waitcnt vmcnt(" #n ")" ::: "memory")
; #define PG8_WAIT_L(n) asm volatile("s_waitcnt lgkmcnt(" #n ")" ::: "memory")
; #define PG8_BAR __builtin_amdgcn_s_barrier()
; #define PG8_SCHED __builtin_amdgcn_sched_barrier(0)
; template <class Epi, class Sched, bool ALIGN_EPI = false, bool SP2 = false>
; __device__ __forceinline__ void gemm_phase(PG8_LAS unsigned char* lds, const Gemm g, const Sched& S, const Epi& E, const int wave_s) {
;     ...
;             PG8_LDB(B0, 1, 0); PG8_LDB(B1, 1, 1); PG8_SCHED; PG8_LDA(At, 1, 0); PG8_STAGE(PG8_SA(0, 1), a2 + hstepA, voffA);
;             PG8_WAIT_V(8); PG8_WAIT_L(0); PG8_BAR; PG8_MMA(0, 0, At, B0); PG8_MMA(0, 1, At, B1); PG8_BAR; PG8_SCHED;
	s_add_i32 s57, 0, 0x18000
	v_add_u32_e32 v0, s57, v17
	s_add_i32 s66, 0, 0x1c000
	ds_read_b128 v[90:93], v0
	ds_read_b128 v[98:101], v0 offset:1024
	ds_read_b128 v[102:105], v0 offset:2048
	ds_read_b128 v[106:109], v0 offset:3072
	v_add_u32_e32 v0, s66, v17
	ds_read_b128 v[160:163], v0
	ds_read_b128 v[168:171], v0 offset:1024
	ds_read_b128 v[172:175], v0 offset:2048
	ds_read_b128 v[176:179], v0 offset:3072
	s_add_u32 s30, s30, 0x40000
	s_addc_u32 s31, s31, 0
	s_mov_b32 m0, s45
	v_lshl_add_u64 v[218:219], s[30:31], 0, v[14:15]
	ds_read_b128 v[180:183], v166 offset:32768
	ds_read_b128 v[184:187], v166 offset:33792
	ds_read_b128 v[188:191], v166 offset:34816
	ds_read_b128 v[192:195], v166 offset:35840
	ds_read_b128 v[196:199], v166 offset:36864
	ds_read_b128 v[200:203], v166 offset:37888
	ds_read_b128 v[204:207], v166 offset:38912
	ds_read_b128 v[208:211], v166 offset:39936
	global_load_lds_dwordx4 v[218:219], off
	v_lshl_add_u64 v[218:219], s[30:31], 0, v[152:153]
	s_mov_b32 m0, s46
	s_nop 0
	global_load_lds_dwordx4 v[218:219], off
	s_waitcnt vmcnt(8)
	s_waitcnt lgkmcnt(0)
	s_barrier
	s_setprio 1
	s_waitcnt lgkmcnt(0)
	v_mfma_f32_16x16x32_bf16 v[146:149], v[90:93], v[180:183], v[146:149]
	v_mfma_f32_16x16x32_bf16 v[142:145], v[102:105], v[180:183], v[142:145]
	v_mfma_f32_16x16x32_bf16 v[130:133], v[90:93], v[188:191], v[130:133]
	v_mfma_f32_16x16x32_bf16 v[126:129], v[102:105], v[188:191], v[126:129]
	v_mfma_f32_16x16x32_bf16 v[114:117], v[90:93], v[196:199], v[114:117]
	v_mfma_f32_16x16x32_bf16 v[110:113], v[102:105], v[196:199], v[110:113]
	v_mfma_f32_16x16x32_bf16 v[82:85], v[90:93], v[204:207], v[82:85]
	v_mfma_f32_16x16x32_bf16 v[78:81], v[102:105], v[204:207], v[78:81]
	v_mfma_f32_16x16x32_bf16 v[146:149], v[98:101], v[184:187], v[146:149]
	v_mfma_f32_16x16x32_bf16 v[142:145], v[106:109], v[184:187], v[142:145]
	v_mfma_f32_16x16x32_bf16 v[130:133], v[98:101], v[192:195], v[130:133]
	v_mfma_f32_16x16x32_bf16 v[126:129], v[106:109], v[192:195], v[126:129]
	v_mfma_f32_16x16x32_bf16 v[114:117], v[98:101], v[200:203], v[114:117]
	v_mfma_f32_16x16x32_bf16 v[110:113], v[106:109], v[200:203], v[110:113]
	v_mfma_f32_16x16x32_bf16 v[82:85], v[98:101], v[208:211], v[82:85]
	v_mfma_f32_16x16x32_bf16 v[78:81], v[106:109], v[208:211], v[78:81]
	s_setprio 0
	s_setprio 1
	v_mfma_f32_16x16x32_bf16 v[138:141], v[160:163], v[180:183], v[138:141]
	v_mfma_f32_16x16x32_bf16 v[134:137], v[172:175], v[180:183], v[134:137]
	v_mfma_f32_16x16x32_bf16 v[122:125], v[160:163], v[188:191], v[122:125]
	v_mfma_f32_16x16x32_bf16 v[118:121], v[172:175], v[188:191], v[118:121]
	v_mfma_f32_16x16x32_bf16 v[94:97], v[160:163], v[196:199], v[94:97]
	v_mfma_f32_16x16x32_bf16 v[86:89], v[172:175], v[196:199], v[86:89]
	v_mfma_f32_16x16x32_bf16 v[74:77], v[160:163], v[204:207], v[74:77]
	v_mfma_f32_16x16x32_bf16 v[70:73], v[172:175], v[204:207], v[70:73]
	v_mfma_f32_16x16x32_bf16 v[138:141], v[168:171], v[184:187], v[138:141]
	v_mfma_f32_16x16x32_bf16 v[134:137], v[176:179], v[184:187], v[134:137]
	v_mfma_f32_16x16x32_bf16 v[122:125], v[168:171], v[192:195], v[122:125]
	v_mfma_f32_16x16x32_bf16 v[118:121], v[176:179], v[192:195], v[118:121]
	v_mfma_f32_16x16x32_bf16 v[94:97], v[168:171], v[200:203], v[94:97]
	v_mfma_f32_16x16x32_bf16 v[86:89], v[176:179], v[200:203], v[86:89]
	v_mfma_f32_16x16x32_bf16 v[74:77], v[168:171], v[208:211], v[74:77]
	v_mfma_f32_16x16x32_bf16 v[70:73], v[176:179], v[208:211], v[70:73]
	s_setprio 0
	s_barrier
; #define PG8_STAGE(bufoff, gbase, voff) do { _Pragma("unroll") for (int _i = 0; _i < 2; ++_i) \
;         __builtin_amdgcn_global_load_lds((const unsigned*)((const char*)(gbase) + (voff)[_i]), (PG8_LAS unsigned*)(lds + (bufoff) + ldsw + _i * 8192), 16, 0, 0); } while (0)
; #define PG8_LDA(dst, b, h) do { _Pragma("unroll") for (int m = 0; m < 4; ++m) _Pragma("unroll") for (int k = 0; k < 2; ++k) dst[m][k] = *(const PG8_LAS bf16x8*)(lds + PG8_SA(b, h) + aoff + m * 2048 + k * 1024); } while (0)
; #define PG8_MMA(ai, bj, At, Bt) do { __builtin_amdgcn_s_setprio(1); _Pragma("unroll") for (int m = 0; m < 4; ++m) _Pragma("unroll") for (int n = 0; n < 2; ++n) _Pragma("unroll") for (int k = 0; k < 2; ++k) \
;         acc[ai][bj][m][n] = __builtin_amdgcn_mfma_f32_16x16x32_bf16(Bt[n][k], At[m][k], acc[ai][bj][m][n], 0, 0, 0); __builtin_amdgcn_s_setprio(0); } while (0)
; #define PG8_WAIT_V(n) asm volatile("s_waitcnt vmcnt(" #n ")" ::: "memory")
; #define PG8_WAIT_L(n) asm volatile("s_waitcnt lgkmcnt(" #n ")" ::: "memory")
; #define PG8_BAR __builtin_amdgcn_s_barrier()
; #define PG8_SCHED __builtin_amdgcn_sched_barrier(0)
; template <class Epi, class Sched, bool ALIGN_EPI = false, bool SP2 = false>
; __device__ __forceinline__ void gemm_phase(PG8_LAS unsigned char* lds, const Gemm g, const Sched& S, const Epi& E, const int wave_s) {
;     ...
;         for (int t = 0; t < nt; t += 2) {
;     ...
;             PG8_LDA(At, 1, 1); PG8_STAGE(PG8_SB(1, 0), b3, voffB); PG8_STAGE(PG8_SB(1, 1), b3 + hstepB, voffB); PG8_STAGE(PG8_SA(1, 0), a3, voffA);
;             PG8_WAIT_V(8); PG8_WAIT_L(0); PG8_BAR; PG8_MMA(1, 0, At, B0); PG8_MMA(1, 1, At, B1); PG8_BAR; PG8_SCHED;
	s_add_i32 s30, s57, s44
	v_lshl_add_u64 v[164:165], v[164:165], 0, s[58:59]
	s_mov_b32 m0, s30
	ds_read_b128 v[180:183], v166 offset:49152
	ds_read_b128 v[184:187], v166 offset:50176
	ds_read_b128 v[188:191], v166 offset:51200
	ds_read_b128 v[192:195], v166 offset:52224
	ds_read_b128 v[196:199], v166 offset:53248
	ds_read_b128 v[200:203], v166 offset:54272
	ds_read_b128 v[204:207], v166 offset:55296
	ds_read_b128 v[208:211], v166 offset:56320
	global_load_lds_dwordx4 v[164:165], off
	s_add_i32 m0, s30, 0x2000
	s_add_u32 s4, s4, 0x40080
	v_lshl_add_u64 v[164:165], v[212:213], 0, s[58:59]
	s_addc_u32 s5, s5, 0
	s_add_i32 s30, s66, s44
	global_load_lds_dwordx4 v[164:165], off
	v_lshl_add_u64 v[164:165], s[4:5], 0, v[150:151]
	s_mov_b32 m0, s30
	s_nop 0
	global_load_lds_dwordx4 v[164:165], off
	v_lshl_add_u64 v[164:165], s[4:5], 0, v[154:155]
	s_add_i32 m0, s30, 0x2000
	s_nop 0
	global_load_lds_dwordx4 v[164:165], off
	v_lshl_add_u64 v[164:165], v[214:215], 0, v[248:249]
	s_mov_b32 m0, s49
	s_nop 0
	global_load_lds_dwordx4 v[164:165], off
	v_lshl_add_u64 v[164:165], v[216:217], 0, v[248:249]
	s_mov_b32 m0, s50
	s_nop 0
	global_load_lds_dwordx4 v[164:165], off
	s_waitcnt vmcnt(8)
	s_waitcnt lgkmcnt(0)
	s_barrier
	s_setprio 1
	s_waitcnt lgkmcnt(0)
	v_mfma_f32_16x16x32_bf16 v[66:69], v[90:93], v[180:183], v[66:69]
	v_mfma_f32_16x16x32_bf16 v[62:65], v[102:105], v[180:183], v[62:65]
	v_mfma_f32_16x16x32_bf16 v[50:53], v[90:93], v[188:191], v[50:53]
	v_mfma_f32_16x16x32_bf16 v[46:49], v[102:105], v[188:191], v[46:49]
	v_mfma_f32_16x16x32_bf16 v[34:37], v[90:93], v[196:199], v[34:37]
	v_mfma_f32_16x16x32_bf16 v[30:33], v[102:105], v[196:199], v[30:33]
	v_mfma_f32_16x16x32_bf16 v[18:21], v[90:93], v[204:207], v[18:21]
	v_mfma_f32_16x16x32_bf16 v[10:13], v[102:105], v[204:207], v[10:13]
	v_mfma_f32_16x16x32_bf16 v[66:69], v[98:101], v[184:187], v[66:69]
	v_mfma_f32_16x16x32_bf16 v[62:65], v[106:109], v[184:187], v[62:65]
	v_mfma_f32_16x16x32_bf16 v[50:53], v[98:101], v[192:195], v[50:53]
	v_mfma_f32_16x16x32_bf16 v[46:49], v[106:109], v[192:195], v[46:49]
	v_mfma_f32_16x16x32_bf16 v[34:37], v[98:101], v[200:203], v[34:37]
	v_mfma_f32_16x16x32_bf16 v[30:33], v[106:109], v[200:203], v[30:33]
	v_mfma_f32_16x16x32_bf16 v[18:21], v[98:101], v[208:211], v[18:21]
	v_mfma_f32_16x16x32_bf16 v[10:13], v[106:109], v[208:211], v[10:13]
	s_setprio 0
	s_setprio 1
	v_mfma_f32_16x16x32_bf16 v[58:61], v[160:163], v[180:183], v[58:61]
	v_mfma_f32_16x16x32_bf16 v[54:57], v[172:175], v[180:183], v[54:57]
	v_mfma_f32_16x16x32_bf16 v[42:45], v[160:163], v[188:191], v[42:45]
	v_mfma_f32_16x16x32_bf16 v[38:41], v[172:175], v[188:191], v[38:41]
	v_mfma_f32_16x16x32_bf16 v[26:29], v[160:163], v[196:199], v[26:29]
	v_mfma_f32_16x16x32_bf16 v[22:25], v[172:175], v[196:199], v[22:25]
	v_mfma_f32_16x16x32_bf16 v[6:9], v[160:163], v[204:207], v[6:9]
	v_mfma_f32_16x16x32_bf16 v[2:5], v[172:175], v[204:207], v[2:5]
	v_mfma_f32_16x16x32_bf16 v[58:61], v[168:171], v[184:187], v[58:61]
	v_mfma_f32_16x16x32_bf16 v[54:57], v[176:179], v[184:187], v[54:57]
	v_mfma_f32_16x16x32_bf16 v[42:45], v[168:171], v[192:195], v[42:45]
	v_mfma_f32_16x16x32_bf16 v[38:41], v[176:179], v[192:195], v[38:41]
	v_mfma_f32_16x16x32_bf16 v[26:29], v[168:171], v[200:203], v[26:29]
	v_mfma_f32_16x16x32_bf16 v[22:25], v[176:179], v[200:203], v[22:25]
	v_mfma_f32_16x16x32_bf16 v[6:9], v[168:171], v[208:211], v[6:9]
	v_mfma_f32_16x16x32_bf16 v[2:5], v[176:179], v[208:211], v[2:5]
	s_setprio 0
	s_barrier
	s_add_i32 s56, s56, 2
	s_add_u32 s54, s54, 0x100
	s_addc_u32 s55, s55, 0
	s_add_u32 s6, s6, 0x1000
	s_addc_u32 s7, s7, 0
	s_cmp_gt_u32 s56, 13
	s_cbranch_scc0 .LBB0_1165
	s_and_b64 vcc, exec, s[16:17]
	s_cbranch_vccz .LBB0_1168
	s_barrier

; #define PG8_GCPTR(p) ((__attribute__((address_space(1))) const char*)(p))
;     __device__ __forceinline__ void operator()(const f32x4 (&acc)[2][2][4][2], const Unit& u, int wr, int wc, int fr, int fq) const {
;     ...
;         const int col0 = u.pn * BM + wc * 32 + 8 * fq; const int b = (u.pm * BM) >> 12;
;         const float* gp = gate + (size_t)b * NMOD + col0; const float* sp = sc + (size_t)b * NMOD + col0;
;         f32x4 g[2][2], cf[2][2];
; #pragma unroll
;         for (int bj = 0; bj < 2; ++bj) {
;             g[bj][0] = *(const f32x4*)(gp + bj * HALF); g[bj][1] = *(const f32x4*)(gp + bj * HALF + 4);
;             const f32x4 n0 = *(const f32x4*)(nw + col0 + bj * HALF), n1 = *(const f32x4*)(nw + col0 + bj * HALF + 4);
;             const f32x4 c0 = *(const f32x4*)(sp + bj * HALF), c1 = *(const f32x4*)(sp + bj * HALF + 4);
;             cf[bj][0] = n0 * (c0 + 1.0f); cf[bj][1] = n1 * (c1 + 1.0f);
;         }
; #pragma unroll
;         for (int ai = 0; ai < 2; ++ai)
; #pragma unroll
;         for (int mp = 0; mp < 4; mp += 2) {
;             u32x4 bv[2][2];
; #pragma unroll
;             for (int mm = 0; mm < 2; ++mm)
; #pragma unroll
;                 for (int bj = 0; bj < 2; ++bj)
;                     bv[mm][bj] = *(gl_u32x4*)(PG8_GCPTR(base) + (unsigned)((u.pm * BM + ai * HALF + wr * 64 + (mp + mm) * 16 + fr) * DM + col0 + bj * HALF) * 2u);
; #pragma unroll
;             for (int mm = 0; mm < 2; ++mm) {
;                 const int m = mp + mm;
;                 const int row = u.pm * BM + ai * HALF + wr * 64 + m * 16 + fr; float q = 0.f;
; #pragma unroll
;                 for (int bj = 0; bj < 2; ++bj) {
;                     const unsigned offb = (unsigned)(row * DM + col0 + bj * HALF) * 2u;
;                     const u32x4 bw = bv[mm][bj];
;                     const f32x4 b0 = (f32x4){__uint_as_float(bw.x << 16), __uint_as_float(bw.x & 0xffff0000u), __uint_as_float(bw.y << 16), __uint_as_float(bw.y & 0xffff0000u)};
;                     const f32x4 b1 = (f32x4){__uint_as_float(bw.z << 16), __uint_as_float(bw.z & 0xffff0000u), __uint_as_float(bw.w << 16), __uint_as_float(bw.w & 0xffff0000u)};
;                     f32x4 a0 = acc[ai][bj][m][0], a1 = acc[ai][bj][m][1]; if constexpr (GN) { a0 *= rc[ai * 4 + m]; a1 *= rc[ai * 4 + m]; }
;                     const f32x4 o0 = b0 + g[bj][0] * a0, o1 = b1 + g[bj][1] * a1;
.LBB0_1246:
	v_mbcnt_lo_u32_b32 v0, -1, 0
	v_mbcnt_hi_u32_b32 v0, -1, v0
	s_lshl_b32 s2, s88, 8
	v_bfe_u32 v205, v0, 4, 2
	v_and_b32_e32 v219, 15, v0
	v_lshl_or_b32 v0, v205, 3, s2
	s_ashr_i32 s2, s87, 4
	v_or_b32_e32 v174, s51, v0
	s_mul_i32 s5, s2, 0x6000
	s_mul_hi_i32 s4, s2, 0x6000
	s_add_u32 s2, s67, s5
	v_ashrrev_i32_e32 v175, 31, v174
	s_addc_u32 s3, s73, s4
	v_lshlrev_b64 v[62:63], 2, v[174:175]
	v_lshl_add_u64 v[158:159], s[2:3], 0, v[62:63]
	s_add_u32 s2, s48, s5
	s_addc_u32 s3, s49, s4
	v_lshl_add_u64 v[162:163], s[2:3], 0, v[62:63]
	v_lshl_add_u64 v[164:165], s[18:19], 0, v[62:63]
	global_load_dwordx4 v[74:77], v[158:159], off
	global_load_dwordx4 v[70:73], v[158:159], off offset:16
	global_load_dwordx4 v[62:65], v[164:165], off offset:16
	global_load_dwordx4 v[66:69], v[164:165], off
	global_load_dwordx4 v[150:153], v[162:163], off
	global_load_dwordx4 v[154:157], v[162:163], off offset:16
	s_lshl_b32 s2, s87, 8
	s_add_i32 s2, s2, s50
	v_or_b32_e32 v204, s2, v219
	v_lshlrev_b32_e32 v217, 1, v174
	v_lshlrev_b32_e32 v218, 11, v204
	v_add_u32_e32 v0, v217, v218
	v_and_b32_e32 v240, 0xffff8000, v0
	v_bfe_u32 v241, v0, 11, 4
	v_lshl_or_b32 v240, v241, 6, v240
	v_bfe_u32 v241, v0, 9, 2
	v_lshl_or_b32 v240, v241, 13, v240
	v_bfe_u32 v241, v0, 6, 2
	v_lshl_or_b32 v240, v241, 11, v240
	v_and_b32_e32 v241, 48, v0
	v_or_b32_e32 v240, v240, v241
	v_bfe_u32 v242, v0, 6, 2
	v_lshlrev_b32_e32 v242, 10, v242
	v_sub_u32_e32 v242, v240, v242
	v_add_u32_e32 v242, 0x1000, v242
	s_andn2_b64 vcc, exec, s[26:27]
	v_lshl_add_u64 v[214:215], s[12:13], 0, v[0:1]
	s_waitcnt vmcnt(0) lgkmcnt(0)
	v_pk_add_f32 v[152:153], v[152:153], 1.0 op_sel_hi:[1,0]
	v_pk_add_f32 v[150:151], v[150:151], 1.0 op_sel_hi:[1,0]
	v_pk_mul_f32 v[210:211], v[68:69], v[152:153]
	v_pk_mul_f32 v[212:213], v[66:67], v[150:151]
	v_pk_add_f32 v[66:67], v[156:157], 1.0 op_sel_hi:[1,0]
	v_pk_add_f32 v[68:69], v[154:155], 1.0 op_sel_hi:[1,0]
	v_pk_mul_f32 v[206:207], v[64:65], v[66:67]
	v_pk_mul_f32 v[208:209], v[62:63], v[68:69]
	global_load_dwordx4 v[66:69], v[158:159], off offset:512
	global_load_dwordx4 v[62:65], v[158:159], off offset:528
	s_nop 0
	global_load_dwordx4 v[158:161], v[164:165], off offset:528
	global_load_dwordx4 v[166:169], v[164:165], off offset:512
	global_load_dwordx4 v[170:173], v[162:163], off offset:512
	s_nop 0
	global_load_dwordx4 v[162:165], v[162:163], off offset:528
	s_nop 0
	global_load_dwordx4 v[178:181], v240, s[20:21] nt
	global_load_dwordx4 v[174:177], v240, s[20:21] offset:1024 nt
	v_add_u32_e32 v150, 0x8000, v240
	global_load_dwordx4 v[154:157], v150, s[20:21] nt
	s_nop 0
	global_load_dwordx4 v[150:153], v150, s[20:21] offset:1024 nt
	s_waitcnt vmcnt(0)
	v_lshlrev_b32_e32 v182, 16, v178
	v_and_b32_e32 v183, 0xffff0000, v178
	v_lshlrev_b32_e32 v178, 16, v179
	v_and_b32_e32 v179, 0xffff0000, v179
	v_lshlrev_b32_e32 v184, 16, v180
	v_and_b32_e32 v185, 0xffff0000, v180
	v_lshlrev_b32_e32 v180, 16, v181
	v_and_b32_e32 v181, 0xffff0000, v181
	v_pk_fma_f32 v[148:149], v[148:149], v[76:77], v[178:179]
	v_pk_fma_f32 v[146:147], v[146:147], v[74:75], v[182:183]
	v_pk_fma_f32 v[144:145], v[144:145], v[72:73], v[180:181]
	v_cvt_pk_bf16_f32 v178, v146, v147
	v_pk_fma_f32 v[142:143], v[142:143], v[70:71], v[184:185]
	v_cvt_pk_bf16_f32 v179, v148, v149
	s_nop 0
	v_cvt_pk_bf16_f32 v180, v142, v143
	v_cvt_pk_bf16_f32 v181, v144, v145
	global_store_dwordx4 v240, v[178:181], s[22:23] nt
	s_nop 1
	v_cndmask_b32_e64 v178, 0, 1, s[26:27]
	v_cmp_ne_u32_e64 s[8:9], 1, v178
	s_cbranch_vccnz .LBB0_1248
	v_pk_mul_f32 v[178:179], v[212:213], v[146:147]
	v_pk_mul_f32 v[180:181], v[210:211], v[148:149]
	v_cvt_pk_bf16_f32 v178, v178, v179
	v_pk_mul_f32 v[148:149], v[148:149], v[148:149]
	v_cvt_pk_bf16_f32 v179, v180, v181
	v_pk_mul_f32 v[146:147], v[146:147], v[146:147]
	v_pk_mul_f32 v[182:183], v[206:207], v[144:145]
	v_pk_mul_f32 v[184:185], v[208:209], v[142:143]
	v_pk_mul_f32 v[144:145], v[144:145], v[144:145]
	v_cvt_pk_bf16_f32 v180, v184, v185
	v_cvt_pk_bf16_f32 v181, v182, v183
	global_store_dwordx4 v242, v[178:181], s[12:13] offset:-4096
	v_pk_mul_f32 v[142:143], v[142:143], v[142:143]
	s_nop 0
	v_mov_b32_e32 v178, v146
	v_mov_b32_e32 v179, v149
	v_pk_mov_b32 v[146:147], v[146:147], v[148:149] op_sel:[1,0]
	v_mov_b32_e32 v148, v144
	v_pk_add_f32 v[146:147], v[146:147], v[178:179]
	v_mov_b32_e32 v149, v142
	v_mov_b32_e32 v142, v145
	v_pk_add_f32 v[142:143], v[148:149], v[142:143]
	v_add_f32_e32 v144, v146, v147
	v_add_f32_e32 v143, v143, v144
	v_add_f32_e32 v227, v142, v143
	s_branch .LBB0_1249

; __device__ __forceinline__ unsigned cvt_pk_bf16(float lo, float hi) { unsigned r; asm volatile("v_cvt_pk_bf16_f32 %0, %1, %2" : "=v"(r) : "v"(lo), "v"(hi)); return r; }
; #define PG8_GPTR(p) ((__attribute__((address_space(1))) char*)(p))
;     __device__ __forceinline__ void operator()(const f32x4 (&acc)[2][2][4][2], const Unit& u, int wr, int wc, int fr, int fq) const {
;     ...
;                 for (int bj = 0; bj < 2; ++bj) {
;                     const unsigned offb = (unsigned)(row * DM + col0 + bj * HALF) * 2u;
;                     const u32x4 bw = bv[mm][bj];
;                     const f32x4 b0 = (f32x4){__uint_as_float(bw.x << 16), __uint_as_float(bw.x & 0xffff0000u), __uint_as_float(bw.y << 16), __uint_as_float(bw.y & 0xffff0000u)};
;                     const f32x4 b1 = (f32x4){__uint_as_float(bw.z << 16), __uint_as_float(bw.z & 0xffff0000u), __uint_as_float(bw.w << 16), __uint_as_float(bw.w & 0xffff0000u)};
;                     f32x4 a0 = acc[ai][bj][m][0], a1 = acc[ai][bj][m][1]; if constexpr (GN) { a0 *= rc[ai * 4 + m]; a1 *= rc[ai * 4 + m]; }
;                     const f32x4 o0 = b0 + g[bj][0] * a0, o1 = b1 + g[bj][1] * a1;
;                     u32x4 wo; wo.x = cvt_pk_bf16(o0[0], o0[1]); wo.y = cvt_pk_bf16(o0[2], o0[3]); wo.z = cvt_pk_bf16(o1[0], o1[1]); wo.w = cvt_pk_bf16(o1[2], o1[3]);
;                     *(gs_u32x4*)(PG8_GPTR(out) + offb) = wo;
;                     if (xg) {
;                         const f32x4 h0 = o0 * cf[bj][0], h1 = o1 * cf[bj][1];
;                         u32x4 w; w.x = cvt_pk_bf16(h0[0], h0[1]); w.y = cvt_pk_bf16(h0[2], h0[3]); w.z = cvt_pk_bf16(h1[0], h1[1]); w.w = cvt_pk_bf16(h1[2], h1[3]);
;                         *(gs_u32x4*)(PG8_GPTR(xg) + offb) = w;
;                         q += (o0[0] * o0[0] + o0[1] * o0[1]) + (o0[2] * o0[2] + o0[3] * o0[3]) + (o1[0] * o1[0] + o1[1] * o1[1]) + (o1[2] * o1[2] + o1[3] * o1[3]);
;                     }
;                 }
;                 if (xg) ssq_put(ssq, row, q, fr, fq);
.LBB0_1249:
	s_waitcnt lgkmcnt(0)
	v_pk_add_f32 v[142:143], v[172:173], 1.0 op_sel_hi:[1,0]
	v_pk_add_f32 v[144:145], v[170:171], 1.0 op_sel_hi:[1,0]
	v_pk_mul_f32 v[148:149], v[168:169], v[142:143]
	v_pk_mul_f32 v[142:143], v[166:167], v[144:145]
	v_pk_add_f32 v[144:145], v[164:165], 1.0 op_sel_hi:[1,0]
	v_pk_add_f32 v[146:147], v[162:163], 1.0 op_sel_hi:[1,0]
	v_pk_mul_f32 v[144:145], v[160:161], v[144:145]
	v_pk_mul_f32 v[146:147], v[158:159], v[146:147]
	v_lshlrev_b32_e32 v158, 6, v205
	v_lshlrev_b32_e32 v160, 2, v219
	s_movk_i32 s2, 0x80
	v_bitop3_b32 v159, v158, 64, v160 bitop3:0x36
	v_bitop3_b32 v158, v158, s2, v160 bitop3:0x36
	v_lshlrev_b32_e32 v160, 16, v174
	v_and_b32_e32 v161, 0xffff0000, v174
	v_lshlrev_b32_e32 v162, 16, v175
	v_and_b32_e32 v163, 0xffff0000, v175
	v_lshlrev_b32_e32 v164, 16, v176
	v_and_b32_e32 v165, 0xffff0000, v176
	v_lshlrev_b32_e32 v166, 16, v177
	v_and_b32_e32 v167, 0xffff0000, v177
	v_lshl_add_u64 v[178:179], s[22:23], 0, v[0:1]
	v_cmp_eq_u32_e64 s[10:11], 0, v205
	v_pk_fma_f32 v[140:141], v[140:141], v[68:69], v[162:163]
	v_pk_fma_f32 v[138:139], v[138:139], v[66:67], v[160:161]
	v_pk_fma_f32 v[136:137], v[136:137], v[64:65], v[166:167]
	v_pk_fma_f32 v[134:135], v[134:135], v[62:63], v[164:165]
	s_and_b64 vcc, exec, s[8:9]
	v_cvt_pk_bf16_f32 v160, v138, v139
	v_cvt_pk_bf16_f32 v161, v140, v141
	v_cvt_pk_bf16_f32 v162, v134, v135
	v_cvt_pk_bf16_f32 v163, v136, v137
	global_store_dwordx4 v240, v[160:163], s[22:23] offset:1024 nt
	s_cbranch_vccnz .LBB0_1253
	s_nop 0
	v_pk_mul_f32 v[160:161], v[148:149], v[140:141]
	v_mul_f32_e32 v164, v139, v139
	v_mul_f32_e32 v141, v141, v141
	v_mul_f32_e32 v163, v135, v135
	v_fmac_f32_e32 v164, v138, v138
	v_fmac_f32_e32 v141, v140, v140
	v_mul_f32_e32 v162, v137, v137
	v_fmac_f32_e32 v163, v134, v134
	v_add_f32_e32 v140, v164, v141
	v_fmac_f32_e32 v162, v136, v136
	v_add_f32_e32 v140, v163, v140
	v_add_f32_e32 v140, v162, v140
	v_add_f32_e32 v164, v140, v227
	ds_bpermute_b32 v165, v159, v164
	v_pk_mul_f32 v[162:163], v[146:147], v[134:135]
	v_pk_mul_f32 v[138:139], v[142:143], v[138:139]
	v_pk_mul_f32 v[140:141], v[144:145], v[136:137]
	v_cvt_pk_bf16_f32 v136, v138, v139
	s_waitcnt lgkmcnt(0)
	v_add_f32_e32 v134, v164, v165
	ds_bpermute_b32 v135, v158, v134
	v_cvt_pk_bf16_f32 v137, v160, v161
	v_cvt_pk_bf16_f32 v138, v162, v163
	v_cvt_pk_bf16_f32 v139, v140, v141
	global_store_dwordx4 v242, v[136:139], s[12:13]
	s_and_saveexec_b64 s[2:3], s[10:11]
	s_cbranch_execz .LBB0_1252
	s_waitcnt lgkmcnt(0)
	v_add_f32_e32 v134, v134, v135
	v_mul_f32_e32 v134, 0x4b800000, v134
	v_trunc_f32_e32 v134, v134
	v_mul_f32_e32 v135, 0x2f800000, v134
	v_floor_f32_e32 v135, v135
	v_fmac_f32_e32 v134, 0xcf800000, v135
	v_cvt_u32_f32_e32 v134, v134
	v_cvt_u32_f32_e32 v135, v135
	v_ashrrev_i32_e32 v205, 31, v204
	v_lshl_add_u64 v[136:137], v[204:205], 3, s[16:17]
	global_atomic_add_x2 v[136:137], v[134:135], off

; __device__ __forceinline__ unsigned cvt_pk_bf16(float lo, float hi) { unsigned r; asm volatile("v_cvt_pk_bf16_f32 %0, %1, %2" : "=v"(r) : "v"(lo), "v"(hi)); return r; }
; #define PG8_GPTR(p) ((__attribute__((address_space(1))) char*)(p))
;     __device__ __forceinline__ void operator()(const f32x4 (&acc)[2][2][4][2], const Unit& u, int wr, int wc, int fr, int fq) const {
;     ...
;             for (int mm = 0; mm < 2; ++mm) {
;                 const int m = mp + mm;
;                 const int row = u.pm * BM + ai * HALF + wr * 64 + m * 16 + fr; float q = 0.f;
; #pragma unroll
;                 for (int bj = 0; bj < 2; ++bj) {
;                     const unsigned offb = (unsigned)(row * DM + col0 + bj * HALF) * 2u;
;                     const u32x4 bw = bv[mm][bj];
;                     const f32x4 b0 = (f32x4){__uint_as_float(bw.x << 16), __uint_as_float(bw.x & 0xffff0000u), __uint_as_float(bw.y << 16), __uint_as_float(bw.y & 0xffff0000u)};
;                     const f32x4 b1 = (f32x4){__uint_as_float(bw.z << 16), __uint_as_float(bw.z & 0xffff0000u), __uint_as_float(bw.w << 16), __uint_as_float(bw.w & 0xffff0000u)};
;                     f32x4 a0 = acc[ai][bj][m][0], a1 = acc[ai][bj][m][1]; if constexpr (GN) { a0 *= rc[ai * 4 + m]; a1 *= rc[ai * 4 + m]; }
;                     const f32x4 o0 = b0 + g[bj][0] * a0, o1 = b1 + g[bj][1] * a1;
;                     u32x4 wo; wo.x = cvt_pk_bf16(o0[0], o0[1]); wo.y = cvt_pk_bf16(o0[2], o0[3]); wo.z = cvt_pk_bf16(o1[0], o1[1]); wo.w = cvt_pk_bf16(o1[2], o1[3]);
;                     *(gs_u32x4*)(PG8_GPTR(out) + offb) = wo;
;                     if (xg) {
;                         const f32x4 h0 = o0 * cf[bj][0], h1 = o1 * cf[bj][1];
;                         u32x4 w; w.x = cvt_pk_bf16(h0[0], h0[1]); w.y = cvt_pk_bf16(h0[2], h0[3]); w.z = cvt_pk_bf16(h1[0], h1[1]); w.w = cvt_pk_bf16(h1[2], h1[3]);
;                         *(gs_u32x4*)(PG8_GPTR(xg) + offb) = w;
.LBB0_1253:
	s_mov_b32 s2, 0x8000
	v_add3_u32 v134, v217, v218, s2
	v_add_u32_e32 v241, s2, v240
	v_add_u32_e32 v243, s2, v242
	v_lshlrev_b32_e32 v136, 16, v154
	v_and_b32_e32 v137, 0xffff0000, v154
	v_lshlrev_b32_e32 v138, 16, v155
	v_and_b32_e32 v139, 0xffff0000, v155
	v_lshlrev_b32_e32 v140, 16, v156
	v_and_b32_e32 v141, 0xffff0000, v156
	v_lshlrev_b32_e32 v154, 16, v157
	v_and_b32_e32 v155, 0xffff0000, v157
	s_waitcnt lgkmcnt(0)
	v_mov_b32_e32 v135, v1
	v_pk_fma_f32 v[132:133], v[132:133], v[76:77], v[138:139]
	v_pk_fma_f32 v[130:131], v[130:131], v[74:75], v[136:137]
	v_pk_fma_f32 v[128:129], v[128:129], v[72:73], v[154:155]
	v_pk_fma_f32 v[136:137], v[126:127], v[70:71], v[140:141]
	s_and_b64 vcc, exec, s[8:9]
	v_lshl_add_u64 v[126:127], s[12:13], 0, v[134:135]
	v_cvt_pk_bf16_f32 v138, v130, v131
	v_cvt_pk_bf16_f32 v139, v132, v133
	v_cvt_pk_bf16_f32 v140, v136, v137
	v_cvt_pk_bf16_f32 v141, v128, v129
	global_store_dwordx4 v241, v[138:141], s[22:23] nt
	s_cbranch_vccnz .LBB0_1255
	s_nop 0
	v_pk_mul_f32 v[138:139], v[212:213], v[130:131]
	v_pk_mul_f32 v[140:141], v[210:211], v[132:133]
	v_cvt_pk_bf16_f32 v138, v138, v139
	v_pk_mul_f32 v[132:133], v[132:133], v[132:133]
	v_cvt_pk_bf16_f32 v139, v140, v141
	v_pk_mul_f32 v[130:131], v[130:131], v[130:131]
	v_pk_mul_f32 v[154:155], v[206:207], v[128:129]
	v_pk_mul_f32 v[156:157], v[208:209], v[136:137]
	v_pk_mul_f32 v[128:129], v[128:129], v[128:129]
	v_cvt_pk_bf16_f32 v140, v156, v157
	v_cvt_pk_bf16_f32 v141, v154, v155
	global_store_dwordx4 v243, v[138:141], s[12:13] offset:-4096
	s_nop 1
	v_mov_b32_e32 v138, v130
	v_mov_b32_e32 v139, v133
	v_pk_mov_b32 v[130:131], v[130:131], v[132:133] op_sel:[1,0]
	v_pk_mul_f32 v[132:133], v[136:137], v[136:137]
	v_pk_add_f32 v[130:131], v[130:131], v[138:139]
	v_mov_b32_e32 v136, v128
	v_mov_b32_e32 v137, v132
	v_mov_b32_e32 v132, v129
	v_pk_add_f32 v[128:129], v[136:137], v[132:133]
	v_add_f32_e32 v130, v130, v131
	v_add_f32_e32 v129, v129, v130
	v_add_f32_e32 v128, v128, v129
	s_branch .LBB0_1256

; __device__ __forceinline__ unsigned cvt_pk_bf16(float lo, float hi) { unsigned r; asm volatile("v_cvt_pk_bf16_f32 %0, %1, %2" : "=v"(r) : "v"(lo), "v"(hi)); return r; }
; #define PG8_GPTR(p) ((__attribute__((address_space(1))) char*)(p))
;     __device__ __forceinline__ void operator()(const f32x4 (&acc)[2][2][4][2], const Unit& u, int wr, int wc, int fr, int fq) const {
;     ...
;             for (int mm = 0; mm < 2; ++mm) {
;                 const int m = mp + mm;
;                 const int row = u.pm * BM + ai * HALF + wr * 64 + m * 16 + fr; float q = 0.f;
; #pragma unroll
;                 for (int bj = 0; bj < 2; ++bj) {
;                     const unsigned offb = (unsigned)(row * DM + col0 + bj * HALF) * 2u;
;                     const u32x4 bw = bv[mm][bj];
;                     const f32x4 b0 = (f32x4){__uint_as_float(bw.x << 16), __uint_as_float(bw.x & 0xffff0000u), __uint_as_float(bw.y << 16), __uint_as_float(bw.y & 0xffff0000u)};
;                     const f32x4 b1 = (f32x4){__uint_as_float(bw.z << 16), __uint_as_float(bw.z & 0xffff0000u), __uint_as_float(bw.w << 16), __uint_as_float(bw.w & 0xffff0000u)};
;                     f32x4 a0 = acc[ai][bj][m][0], a1 = acc[ai][bj][m][1]; if constexpr (GN) { a0 *= rc[ai * 4 + m]; a1 *= rc[ai * 4 + m]; }
;                     const f32x4 o0 = b0 + g[bj][0] * a0, o1 = b1 + g[bj][1] * a1;
;                     u32x4 wo; wo.x = cvt_pk_bf16(o0[0], o0[1]); wo.y = cvt_pk_bf16(o0[2], o0[3]); wo.z = cvt_pk_bf16(o1[0], o1[1]); wo.w = cvt_pk_bf16(o1[2], o1[3]);
;                     *(gs_u32x4*)(PG8_GPTR(out) + offb) = wo;
;                     if (xg) {
;                         const f32x4 h0 = o0 * cf[bj][0], h1 = o1 * cf[bj][1];
;                         u32x4 w; w.x = cvt_pk_bf16(h0[0], h0[1]); w.y = cvt_pk_bf16(h0[2], h0[3]); w.z = cvt_pk_bf16(h1[0], h1[1]); w.w = cvt_pk_bf16(h1[2], h1[3]);
;                         *(gs_u32x4*)(PG8_GPTR(xg) + offb) = w;
;                         q += (o0[0] * o0[0] + o0[1] * o0[1]) + (o0[2] * o0[2] + o0[3] * o0[3]) + (o1[0] * o1[0] + o1[1] * o1[1]) + (o1[2] * o1[2] + o1[3] * o1[3]);
;                     }
;                 }
;                 if (xg) ssq_put(ssq, row, q, fr, fq);
.LBB0_1256:
	v_lshlrev_b32_e32 v130, 16, v150
	v_and_b32_e32 v131, 0xffff0000, v150
	v_lshlrev_b32_e32 v132, 16, v151
	v_and_b32_e32 v133, 0xffff0000, v151
	v_lshlrev_b32_e32 v136, 16, v152
	v_and_b32_e32 v137, 0xffff0000, v152
	v_lshlrev_b32_e32 v138, 16, v153
	v_and_b32_e32 v139, 0xffff0000, v153
	v_lshl_add_u64 v[134:135], s[22:23], 0, v[134:135]
	v_pk_fma_f32 v[124:125], v[124:125], v[68:69], v[132:133]
	v_pk_fma_f32 v[122:123], v[122:123], v[66:67], v[130:131]
	v_pk_fma_f32 v[120:121], v[120:121], v[64:65], v[138:139]
	v_pk_fma_f32 v[118:119], v[118:119], v[62:63], v[136:137]
	s_and_b64 vcc, exec, s[8:9]
	v_cvt_pk_bf16_f32 v130, v122, v123
	v_cvt_pk_bf16_f32 v131, v124, v125
	v_cvt_pk_bf16_f32 v132, v118, v119
	v_cvt_pk_bf16_f32 v133, v120, v121
	global_store_dwordx4 v241, v[130:133], s[22:23] offset:1024 nt
	s_cbranch_vccnz .LBB0_1260
	s_nop 0
	v_pk_mul_f32 v[130:131], v[148:149], v[124:125]
	v_mul_f32_e32 v133, v123, v123
	v_mul_f32_e32 v125, v125, v125
	v_mul_f32_e32 v132, v119, v119
	v_fmac_f32_e32 v133, v122, v122
	v_fmac_f32_e32 v125, v124, v124
	v_mul_f32_e32 v129, v121, v121
	v_fmac_f32_e32 v132, v118, v118
	v_add_f32_e32 v124, v133, v125
	v_fmac_f32_e32 v129, v120, v120
	v_add_f32_e32 v124, v132, v124
	v_add_f32_e32 v124, v129, v124
	v_add_f32_e32 v132, v124, v128
	ds_bpermute_b32 v133, v159, v132
	v_pk_mul_f32 v[128:129], v[146:147], v[118:119]
	v_pk_mul_f32 v[122:123], v[142:143], v[122:123]
	v_pk_mul_f32 v[124:125], v[144:145], v[120:121]
	v_cvt_pk_bf16_f32 v120, v122, v123
	s_waitcnt lgkmcnt(0)
	v_add_f32_e32 v118, v132, v133
	ds_bpermute_b32 v119, v158, v118
	v_cvt_pk_bf16_f32 v121, v130, v131
	v_cvt_pk_bf16_f32 v122, v128, v129
	v_cvt_pk_bf16_f32 v123, v124, v125
	global_store_dwordx4 v243, v[120:123], s[12:13]
	s_and_saveexec_b64 s[2:3], s[10:11]
	s_cbranch_execz .LBB0_1259
	s_waitcnt lgkmcnt(0)
	v_add_f32_e32 v118, v118, v119
	v_mul_f32_e32 v118, 0x4b800000, v118
	v_trunc_f32_e32 v118, v118
	v_mul_f32_e32 v119, 0x2f800000, v118
	v_floor_f32_e32 v119, v119
	v_fmac_f32_e32 v118, 0xcf800000, v119
	v_cvt_u32_f32_e32 v118, v118
	v_cvt_u32_f32_e32 v119, v119
	v_ashrrev_i32_e32 v205, 31, v204
	v_lshl_add_u64 v[120:121], v[204:205], 3, s[16:17]
	global_atomic_add_x2 v[120:121], v[118:119], off offset:128

; __device__ __forceinline__ unsigned cvt_pk_bf16(float lo, float hi) { unsigned r; asm volatile("v_cvt_pk_bf16_f32 %0, %1, %2" : "=v"(r) : "v"(lo), "v"(hi)); return r; }
; #define PG8_GPTR(p) ((__attribute__((address_space(1))) char*)(p))
; #define PG8_GCPTR(p) ((__attribute__((address_space(1))) const char*)(p))
;     __device__ __forceinline__ void operator()(const f32x4 (&acc)[2][2][4][2], const Unit& u, int wr, int wc, int fr, int fq) const {
;     ...
;                     bv[mm][bj] = *(gl_u32x4*)(PG8_GCPTR(base) + (unsigned)((u.pm * BM + ai * HALF + wr * 64 + (mp + mm) * 16 + fr) * DM + col0 + bj * HALF) * 2u);
; #pragma unroll
;             for (int mm = 0; mm < 2; ++mm) {
;                 const int m = mp + mm;
;                 const int row = u.pm * BM + ai * HALF + wr * 64 + m * 16 + fr; float q = 0.f;
; #pragma unroll
;                 for (int bj = 0; bj < 2; ++bj) {
;                     const unsigned offb = (unsigned)(row * DM + col0 + bj * HALF) * 2u;
;                     const u32x4 bw = bv[mm][bj];
;                     const f32x4 b0 = (f32x4){__uint_as_float(bw.x << 16), __uint_as_float(bw.x & 0xffff0000u), __uint_as_float(bw.y << 16), __uint_as_float(bw.y & 0xffff0000u)};
;                     const f32x4 b1 = (f32x4){__uint_as_float(bw.z << 16), __uint_as_float(bw.z & 0xffff0000u), __uint_as_float(bw.w << 16), __uint_as_float(bw.w & 0xffff0000u)};
;                     f32x4 a0 = acc[ai][bj][m][0], a1 = acc[ai][bj][m][1]; if constexpr (GN) { a0 *= rc[ai * 4 + m]; a1 *= rc[ai * 4 + m]; }
;                     const f32x4 o0 = b0 + g[bj][0] * a0, o1 = b1 + g[bj][1] * a1;
;                     u32x4 wo; wo.x = cvt_pk_bf16(o0[0], o0[1]); wo.y = cvt_pk_bf16(o0[2], o0[3]); wo.z = cvt_pk_bf16(o1[0], o1[1]); wo.w = cvt_pk_bf16(o1[2], o1[3]);
;                     *(gs_u32x4*)(PG8_GPTR(out) + offb) = wo;
;                     if (xg) {
;                         const f32x4 h0 = o0 * cf[bj][0], h1 = o1 * cf[bj][1];
;                         u32x4 w; w.x = cvt_pk_bf16(h0[0], h0[1]); w.y = cvt_pk_bf16(h0[2], h0[3]); w.z = cvt_pk_bf16(h1[0], h1[1]); w.w = cvt_pk_bf16(h1[2], h1[3]);
;                         *(gs_u32x4*)(PG8_GPTR(xg) + offb) = w;
.LBB0_1260:
	v_add_u32_e32 v118, 0x10000, v240
	global_load_dwordx4 v[132:135], v118, s[20:21] nt
	global_load_dwordx4 v[126:129], v118, s[20:21] offset:1024 nt
	v_add_u32_e32 v118, 0x18000, v240
	global_load_dwordx4 v[122:125], v118, s[20:21] nt
	s_waitcnt lgkmcnt(0)
	global_load_dwordx4 v[118:121], v118, s[20:21] offset:1024 nt
	s_mov_b32 s2, 0x10000
	v_add3_u32 v130, v217, v218, s2
	v_add_u32_e32 v241, s2, v240
	v_add_u32_e32 v243, s2, v242
	v_mov_b32_e32 v131, v1
	s_and_b64 vcc, exec, s[8:9]
	s_waitcnt vmcnt(0)
	v_lshlrev_b32_e32 v136, 16, v132
	v_and_b32_e32 v137, 0xffff0000, v132
	v_lshlrev_b32_e32 v132, 16, v133
	v_and_b32_e32 v133, 0xffff0000, v133
	v_lshlrev_b32_e32 v138, 16, v134
	v_and_b32_e32 v139, 0xffff0000, v134
	v_lshlrev_b32_e32 v134, 16, v135
	v_and_b32_e32 v135, 0xffff0000, v135
	v_pk_fma_f32 v[116:117], v[116:117], v[76:77], v[132:133]
	v_pk_fma_f32 v[114:115], v[114:115], v[74:75], v[136:137]
	v_pk_fma_f32 v[112:113], v[112:113], v[72:73], v[134:135]
	v_cvt_pk_bf16_f32 v132, v114, v115
	v_cvt_pk_bf16_f32 v133, v116, v117
	v_pk_fma_f32 v[110:111], v[110:111], v[70:71], v[138:139]
	s_nop 0
	v_cvt_pk_bf16_f32 v134, v110, v111
	v_cvt_pk_bf16_f32 v135, v112, v113
	global_store_dwordx4 v241, v[132:135], s[22:23] nt
	s_nop 1
	v_lshl_add_u64 v[132:133], s[12:13], 0, v[130:131]
	s_cbranch_vccnz .LBB0_1262
	v_pk_mul_f32 v[134:135], v[212:213], v[114:115]
	v_pk_mul_f32 v[136:137], v[210:211], v[116:117]
	v_cvt_pk_bf16_f32 v134, v134, v135
	v_pk_mul_f32 v[116:117], v[116:117], v[116:117]
	v_cvt_pk_bf16_f32 v135, v136, v137
	v_pk_mul_f32 v[114:115], v[114:115], v[114:115]
	v_pk_mul_f32 v[138:139], v[206:207], v[112:113]
	v_pk_mul_f32 v[140:141], v[208:209], v[110:111]
	v_pk_mul_f32 v[112:113], v[112:113], v[112:113]
	v_cvt_pk_bf16_f32 v136, v140, v141
	v_cvt_pk_bf16_f32 v137, v138, v139
	global_store_dwordx4 v243, v[134:137], s[12:13] offset:-4096
	v_pk_mul_f32 v[110:111], v[110:111], v[110:111]
	s_nop 0
	v_mov_b32_e32 v134, v114
	v_mov_b32_e32 v135, v117
	v_pk_mov_b32 v[114:115], v[114:115], v[116:117] op_sel:[1,0]
	v_mov_b32_e32 v116, v112
	v_pk_add_f32 v[114:115], v[114:115], v[134:135]
	v_mov_b32_e32 v117, v110
	v_mov_b32_e32 v110, v113
	v_pk_add_f32 v[110:111], v[116:117], v[110:111]
	v_add_f32_e32 v112, v114, v115
	v_add_f32_e32 v111, v111, v112
	v_add_f32_e32 v110, v110, v111
	s_branch .LBB0_1263

; __device__ __forceinline__ unsigned cvt_pk_bf16(float lo, float hi) { unsigned r; asm volatile("v_cvt_pk_bf16_f32 %0, %1, %2" : "=v"(r) : "v"(lo), "v"(hi)); return r; }
; #define PG8_GPTR(p) ((__attribute__((address_space(1))) char*)(p))
;     __device__ __forceinline__ void operator()(const f32x4 (&acc)[2][2][4][2], const Unit& u, int wr, int wc, int fr, int fq) const {
;     ...
;             for (int mm = 0; mm < 2; ++mm) {
;                 const int m = mp + mm;
;                 const int row = u.pm * BM + ai * HALF + wr * 64 + m * 16 + fr; float q = 0.f;
; #pragma unroll
;                 for (int bj = 0; bj < 2; ++bj) {
;                     const unsigned offb = (unsigned)(row * DM + col0 + bj * HALF) * 2u;
;                     const u32x4 bw = bv[mm][bj];
;                     const f32x4 b0 = (f32x4){__uint_as_float(bw.x << 16), __uint_as_float(bw.x & 0xffff0000u), __uint_as_float(bw.y << 16), __uint_as_float(bw.y & 0xffff0000u)};
;                     const f32x4 b1 = (f32x4){__uint_as_float(bw.z << 16), __uint_as_float(bw.z & 0xffff0000u), __uint_as_float(bw.w << 16), __uint_as_float(bw.w & 0xffff0000u)};
;                     f32x4 a0 = acc[ai][bj][m][0], a1 = acc[ai][bj][m][1]; if constexpr (GN) { a0 *= rc[ai * 4 + m]; a1 *= rc[ai * 4 + m]; }
;                     const f32x4 o0 = b0 + g[bj][0] * a0, o1 = b1 + g[bj][1] * a1;
;                     u32x4 wo; wo.x = cvt_pk_bf16(o0[0], o0[1]); wo.y = cvt_pk_bf16(o0[2], o0[3]); wo.z = cvt_pk_bf16(o1[0], o1[1]); wo.w = cvt_pk_bf16(o1[2], o1[3]);
;                     *(gs_u32x4*)(PG8_GPTR(out) + offb) = wo;
;                     if (xg) {
;                         const f32x4 h0 = o0 * cf[bj][0], h1 = o1 * cf[bj][1];
;                         u32x4 w; w.x = cvt_pk_bf16(h0[0], h0[1]); w.y = cvt_pk_bf16(h0[2], h0[3]); w.z = cvt_pk_bf16(h1[0], h1[1]); w.w = cvt_pk_bf16(h1[2], h1[3]);
;                         *(gs_u32x4*)(PG8_GPTR(xg) + offb) = w;
;                         q += (o0[0] * o0[0] + o0[1] * o0[1]) + (o0[2] * o0[2] + o0[3] * o0[3]) + (o1[0] * o1[0] + o1[1] * o1[1]) + (o1[2] * o1[2] + o1[3] * o1[3]);
;                     }
;                 }
;                 if (xg) ssq_put(ssq, row, q, fr, fq);
.LBB0_1263:
	v_lshlrev_b32_e32 v112, 16, v126
	v_and_b32_e32 v113, 0xffff0000, v126
	v_lshlrev_b32_e32 v114, 16, v127
	v_and_b32_e32 v115, 0xffff0000, v127
	v_lshlrev_b32_e32 v126, 16, v128
	v_and_b32_e32 v127, 0xffff0000, v128
	v_lshlrev_b32_e32 v128, 16, v129
	v_and_b32_e32 v129, 0xffff0000, v129
	v_lshl_add_u64 v[116:117], s[22:23], 0, v[130:131]
	v_pk_fma_f32 v[108:109], v[108:109], v[68:69], v[114:115]
	v_pk_fma_f32 v[106:107], v[106:107], v[66:67], v[112:113]
	v_pk_fma_f32 v[104:105], v[104:105], v[64:65], v[128:129]
	v_pk_fma_f32 v[102:103], v[102:103], v[62:63], v[126:127]
	s_and_b64 vcc, exec, s[8:9]
	v_cvt_pk_bf16_f32 v112, v106, v107
	v_cvt_pk_bf16_f32 v113, v108, v109
	v_cvt_pk_bf16_f32 v114, v102, v103
	v_cvt_pk_bf16_f32 v115, v104, v105
	global_store_dwordx4 v241, v[112:115], s[22:23] offset:1024 nt
	s_cbranch_vccnz .LBB0_1267
	s_nop 0
	v_pk_mul_f32 v[112:113], v[148:149], v[108:109]
	v_mul_f32_e32 v115, v107, v107
	v_mul_f32_e32 v109, v109, v109
	v_mul_f32_e32 v114, v103, v103
	v_fmac_f32_e32 v115, v106, v106
	v_fmac_f32_e32 v109, v108, v108
	v_mul_f32_e32 v111, v105, v105
	v_fmac_f32_e32 v114, v102, v102
	v_add_f32_e32 v108, v115, v109
	v_fmac_f32_e32 v111, v104, v104
	v_add_f32_e32 v108, v114, v108
	v_add_f32_e32 v108, v111, v108
	v_add_f32_e32 v114, v108, v110
	ds_bpermute_b32 v115, v159, v114
	v_pk_mul_f32 v[110:111], v[146:147], v[102:103]
	v_pk_mul_f32 v[106:107], v[142:143], v[106:107]
	v_pk_mul_f32 v[108:109], v[144:145], v[104:105]
	v_cvt_pk_bf16_f32 v104, v106, v107
	s_waitcnt lgkmcnt(0)
	v_add_f32_e32 v102, v114, v115
	ds_bpermute_b32 v103, v158, v102
	v_cvt_pk_bf16_f32 v105, v112, v113
	v_cvt_pk_bf16_f32 v106, v110, v111
	v_cvt_pk_bf16_f32 v107, v108, v109
	global_store_dwordx4 v243, v[104:107], s[12:13]
	s_and_saveexec_b64 s[2:3], s[10:11]
	s_cbranch_execz .LBB0_1266
	s_waitcnt lgkmcnt(0)
	v_add_f32_e32 v102, v102, v103
	v_mul_f32_e32 v102, 0x4b800000, v102
	v_trunc_f32_e32 v102, v102
	v_mul_f32_e32 v103, 0x2f800000, v102
	v_floor_f32_e32 v103, v103
	v_fmac_f32_e32 v102, 0xcf800000, v103
	v_cvt_u32_f32_e32 v102, v102
	v_cvt_u32_f32_e32 v103, v103
	v_ashrrev_i32_e32 v205, 31, v204
	v_lshl_add_u64 v[104:105], v[204:205], 3, s[16:17]
	global_atomic_add_x2 v[104:105], v[102:103], off offset:256

; __device__ __forceinline__ unsigned cvt_pk_bf16(float lo, float hi) { unsigned r; asm volatile("v_cvt_pk_bf16_f32 %0, %1, %2" : "=v"(r) : "v"(lo), "v"(hi)); return r; }
; #define PG8_GPTR(p) ((__attribute__((address_space(1))) char*)(p))
;     __device__ __forceinline__ void operator()(const f32x4 (&acc)[2][2][4][2], const Unit& u, int wr, int wc, int fr, int fq) const {
;     ...
;             for (int mm = 0; mm < 2; ++mm) {
;                 const int m = mp + mm;
;                 const int row = u.pm * BM + ai * HALF + wr * 64 + m * 16 + fr; float q = 0.f;
; #pragma unroll
;                 for (int bj = 0; bj < 2; ++bj) {
;                     const unsigned offb = (unsigned)(row * DM + col0 + bj * HALF) * 2u;
;                     const u32x4 bw = bv[mm][bj];
;                     const f32x4 b0 = (f32x4){__uint_as_float(bw.x << 16), __uint_as_float(bw.x & 0xffff0000u), __uint_as_float(bw.y << 16), __uint_as_float(bw.y & 0xffff0000u)};
;                     const f32x4 b1 = (f32x4){__uint_as_float(bw.z << 16), __uint_as_float(bw.z & 0xffff0000u), __uint_as_float(bw.w << 16), __uint_as_float(bw.w & 0xffff0000u)};
;                     f32x4 a0 = acc[ai][bj][m][0], a1 = acc[ai][bj][m][1]; if constexpr (GN) { a0 *= rc[ai * 4 + m]; a1 *= rc[ai * 4 + m]; }
;                     const f32x4 o0 = b0 + g[bj][0] * a0, o1 = b1 + g[bj][1] * a1;
;                     u32x4 wo; wo.x = cvt_pk_bf16(o0[0], o0[1]); wo.y = cvt_pk_bf16(o0[2], o0[3]); wo.z = cvt_pk_bf16(o1[0], o1[1]); wo.w = cvt_pk_bf16(o1[2], o1[3]);
;                     *(gs_u32x4*)(PG8_GPTR(out) + offb) = wo;
;                     if (xg) {
;                         const f32x4 h0 = o0 * cf[bj][0], h1 = o1 * cf[bj][1];
;                         u32x4 w; w.x = cvt_pk_bf16(h0[0], h0[1]); w.y = cvt_pk_bf16(h0[2], h0[3]); w.z = cvt_pk_bf16(h1[0], h1[1]); w.w = cvt_pk_bf16(h1[2], h1[3]);
;                         *(gs_u32x4*)(PG8_GPTR(xg) + offb) = w;
.LBB0_1267:
	s_mov_b32 s2, 0x18000
	v_add3_u32 v102, v217, v218, s2
	v_add_u32_e32 v241, s2, v240
	v_add_u32_e32 v243, s2, v242
	v_lshlrev_b32_e32 v104, 16, v122
	v_and_b32_e32 v105, 0xffff0000, v122
	v_lshlrev_b32_e32 v106, 16, v123
	v_and_b32_e32 v107, 0xffff0000, v123
	v_lshlrev_b32_e32 v108, 16, v124
	v_and_b32_e32 v109, 0xffff0000, v124
	v_lshlrev_b32_e32 v110, 16, v125
	v_and_b32_e32 v111, 0xffff0000, v125
	s_waitcnt lgkmcnt(0)
	v_mov_b32_e32 v103, v1
	v_pk_fma_f32 v[100:101], v[100:101], v[76:77], v[106:107]
	v_pk_fma_f32 v[98:99], v[98:99], v[74:75], v[104:105]
	v_pk_fma_f32 v[96:97], v[96:97], v[72:73], v[110:111]
	v_pk_fma_f32 v[104:105], v[94:95], v[70:71], v[108:109]
	s_and_b64 vcc, exec, s[8:9]
	v_lshl_add_u64 v[94:95], s[12:13], 0, v[102:103]
	v_cvt_pk_bf16_f32 v106, v98, v99
	v_cvt_pk_bf16_f32 v107, v100, v101
	v_cvt_pk_bf16_f32 v108, v104, v105
	v_cvt_pk_bf16_f32 v109, v96, v97
	global_store_dwordx4 v241, v[106:109], s[22:23] nt
	s_cbranch_vccnz .LBB0_1269
	s_nop 0
	v_pk_mul_f32 v[106:107], v[212:213], v[98:99]
	v_pk_mul_f32 v[108:109], v[210:211], v[100:101]
	v_cvt_pk_bf16_f32 v106, v106, v107
	v_pk_mul_f32 v[100:101], v[100:101], v[100:101]
	v_cvt_pk_bf16_f32 v107, v108, v109
	v_pk_mul_f32 v[98:99], v[98:99], v[98:99]
	v_pk_mul_f32 v[110:111], v[206:207], v[96:97]
	v_pk_mul_f32 v[112:113], v[208:209], v[104:105]
	v_pk_mul_f32 v[96:97], v[96:97], v[96:97]
	v_cvt_pk_bf16_f32 v108, v112, v113
	v_cvt_pk_bf16_f32 v109, v110, v111
	global_store_dwordx4 v243, v[106:109], s[12:13] offset:-4096
	s_nop 1
	v_mov_b32_e32 v106, v98
	v_mov_b32_e32 v107, v101
	v_pk_mov_b32 v[98:99], v[98:99], v[100:101] op_sel:[1,0]
	v_pk_mul_f32 v[100:101], v[104:105], v[104:105]
	v_pk_add_f32 v[98:99], v[98:99], v[106:107]
	v_mov_b32_e32 v104, v96
	v_mov_b32_e32 v105, v100
	v_mov_b32_e32 v100, v97
	v_pk_add_f32 v[96:97], v[104:105], v[100:101]
	v_add_f32_e32 v98, v98, v99
	v_add_f32_e32 v97, v97, v98
	v_add_f32_e32 v96, v96, v97
	s_branch .LBB0_1270

; __device__ __forceinline__ unsigned cvt_pk_bf16(float lo, float hi) { unsigned r; asm volatile("v_cvt_pk_bf16_f32 %0, %1, %2" : "=v"(r) : "v"(lo), "v"(hi)); return r; }
; #define PG8_GPTR(p) ((__attribute__((address_space(1))) char*)(p))
;     __device__ __forceinline__ void operator()(const f32x4 (&acc)[2][2][4][2], const Unit& u, int wr, int wc, int fr, int fq) const {
;     ...
;             for (int mm = 0; mm < 2; ++mm) {
;                 const int m = mp + mm;
;                 const int row = u.pm * BM + ai * HALF + wr * 64 + m * 16 + fr; float q = 0.f;
; #pragma unroll
;                 for (int bj = 0; bj < 2; ++bj) {
;                     const unsigned offb = (unsigned)(row * DM + col0 + bj * HALF) * 2u;
;                     const u32x4 bw = bv[mm][bj];
;                     const f32x4 b0 = (f32x4){__uint_as_float(bw.x << 16), __uint_as_float(bw.x & 0xffff0000u), __uint_as_float(bw.y << 16), __uint_as_float(bw.y & 0xffff0000u)};
;                     const f32x4 b1 = (f32x4){__uint_as_float(bw.z << 16), __uint_as_float(bw.z & 0xffff0000u), __uint_as_float(bw.w << 16), __uint_as_float(bw.w & 0xffff0000u)};
;                     f32x4 a0 = acc[ai][bj][m][0], a1 = acc[ai][bj][m][1]; if constexpr (GN) { a0 *= rc[ai * 4 + m]; a1 *= rc[ai * 4 + m]; }
;                     const f32x4 o0 = b0 + g[bj][0] * a0, o1 = b1 + g[bj][1] * a1;
;                     u32x4 wo; wo.x = cvt_pk_bf16(o0[0], o0[1]); wo.y = cvt_pk_bf16(o0[2], o0[3]); wo.z = cvt_pk_bf16(o1[0], o1[1]); wo.w = cvt_pk_bf16(o1[2], o1[3]);
;                     *(gs_u32x4*)(PG8_GPTR(out) + offb) = wo;
;                     if (xg) {
;                         const f32x4 h0 = o0 * cf[bj][0], h1 = o1 * cf[bj][1];
;                         u32x4 w; w.x = cvt_pk_bf16(h0[0], h0[1]); w.y = cvt_pk_bf16(h0[2], h0[3]); w.z = cvt_pk_bf16(h1[0], h1[1]); w.w = cvt_pk_bf16(h1[2], h1[3]);
;                         *(gs_u32x4*)(PG8_GPTR(xg) + offb) = w;
;                         q += (o0[0] * o0[0] + o0[1] * o0[1]) + (o0[2] * o0[2] + o0[3] * o0[3]) + (o1[0] * o1[0] + o1[1] * o1[1]) + (o1[2] * o1[2] + o1[3] * o1[3]);
;                     }
;                 }
;                 if (xg) ssq_put(ssq, row, q, fr, fq);
.LBB0_1270:
	v_lshlrev_b32_e32 v98, 16, v118
	v_and_b32_e32 v99, 0xffff0000, v118
	v_lshlrev_b32_e32 v100, 16, v119
	v_and_b32_e32 v101, 0xffff0000, v119
	v_lshlrev_b32_e32 v104, 16, v120
	v_and_b32_e32 v105, 0xffff0000, v120
	v_lshlrev_b32_e32 v106, 16, v121
	v_and_b32_e32 v107, 0xffff0000, v121
	v_lshl_add_u64 v[102:103], s[22:23], 0, v[102:103]
	v_pk_fma_f32 v[92:93], v[92:93], v[68:69], v[100:101]
	v_pk_fma_f32 v[90:91], v[90:91], v[66:67], v[98:99]
	v_pk_fma_f32 v[88:89], v[88:89], v[64:65], v[106:107]
	v_pk_fma_f32 v[86:87], v[86:87], v[62:63], v[104:105]
	s_and_b64 vcc, exec, s[8:9]
	v_cvt_pk_bf16_f32 v98, v90, v91
	v_cvt_pk_bf16_f32 v99, v92, v93
	v_cvt_pk_bf16_f32 v100, v86, v87
	v_cvt_pk_bf16_f32 v101, v88, v89
	global_store_dwordx4 v241, v[98:101], s[22:23] offset:1024 nt
	s_cbranch_vccnz .LBB0_1274
	s_nop 0
	v_pk_mul_f32 v[98:99], v[148:149], v[92:93]
	v_mul_f32_e32 v101, v91, v91
	v_mul_f32_e32 v93, v93, v93
	v_mul_f32_e32 v100, v87, v87
	v_fmac_f32_e32 v101, v90, v90
	v_fmac_f32_e32 v93, v92, v92
	v_mul_f32_e32 v97, v89, v89
	v_fmac_f32_e32 v100, v86, v86
	v_add_f32_e32 v92, v101, v93
	v_fmac_f32_e32 v97, v88, v88
	v_add_f32_e32 v92, v100, v92
	v_add_f32_e32 v92, v97, v92
	v_add_f32_e32 v100, v92, v96
	ds_bpermute_b32 v101, v159, v100
	v_pk_mul_f32 v[96:97], v[146:147], v[86:87]
	v_pk_mul_f32 v[90:91], v[142:143], v[90:91]
	v_pk_mul_f32 v[92:93], v[144:145], v[88:89]
	v_cvt_pk_bf16_f32 v88, v90, v91
	s_waitcnt lgkmcnt(0)
	v_add_f32_e32 v86, v100, v101
	ds_bpermute_b32 v87, v158, v86
	v_cvt_pk_bf16_f32 v89, v98, v99
	v_cvt_pk_bf16_f32 v90, v96, v97
	v_cvt_pk_bf16_f32 v91, v92, v93
	global_store_dwordx4 v243, v[88:91], s[12:13]
	s_and_saveexec_b64 s[2:3], s[10:11]
	s_cbranch_execz .LBB0_1273
	s_waitcnt lgkmcnt(0)
	v_add_f32_e32 v86, v86, v87
	v_mul_f32_e32 v86, 0x4b800000, v86
	v_trunc_f32_e32 v86, v86
	v_mul_f32_e32 v87, 0x2f800000, v86
	v_floor_f32_e32 v87, v87
	v_fmac_f32_e32 v86, 0xcf800000, v87
	v_cvt_u32_f32_e32 v86, v86
	v_cvt_u32_f32_e32 v87, v87
	v_ashrrev_i32_e32 v205, 31, v204
	v_lshl_add_u64 v[88:89], v[204:205], 3, s[16:17]
	global_atomic_add_x2 v[88:89], v[86:87], off offset:384

; __device__ __forceinline__ unsigned cvt_pk_bf16(float lo, float hi) { unsigned r; asm volatile("v_cvt_pk_bf16_f32 %0, %1, %2" : "=v"(r) : "v"(lo), "v"(hi)); return r; }
; #define PG8_GPTR(p) ((__attribute__((address_space(1))) char*)(p))
; #define PG8_GCPTR(p) ((__attribute__((address_space(1))) const char*)(p))
;     __device__ __forceinline__ void operator()(const f32x4 (&acc)[2][2][4][2], const Unit& u, int wr, int wc, int fr, int fq) const {
;     ...
;                     bv[mm][bj] = *(gl_u32x4*)(PG8_GCPTR(base) + (unsigned)((u.pm * BM + ai * HALF + wr * 64 + (mp + mm) * 16 + fr) * DM + col0 + bj * HALF) * 2u);
; #pragma unroll
;             for (int mm = 0; mm < 2; ++mm) {
;                 const int m = mp + mm;
;                 const int row = u.pm * BM + ai * HALF + wr * 64 + m * 16 + fr; float q = 0.f;
; #pragma unroll
;                 for (int bj = 0; bj < 2; ++bj) {
;                     const unsigned offb = (unsigned)(row * DM + col0 + bj * HALF) * 2u;
;                     const u32x4 bw = bv[mm][bj];
;                     const f32x4 b0 = (f32x4){__uint_as_float(bw.x << 16), __uint_as_float(bw.x & 0xffff0000u), __uint_as_float(bw.y << 16), __uint_as_float(bw.y & 0xffff0000u)};
;                     const f32x4 b1 = (f32x4){__uint_as_float(bw.z << 16), __uint_as_float(bw.z & 0xffff0000u), __uint_as_float(bw.w << 16), __uint_as_float(bw.w & 0xffff0000u)};
;                     f32x4 a0 = acc[ai][bj][m][0], a1 = acc[ai][bj][m][1]; if constexpr (GN) { a0 *= rc[ai * 4 + m]; a1 *= rc[ai * 4 + m]; }
;                     const f32x4 o0 = b0 + g[bj][0] * a0, o1 = b1 + g[bj][1] * a1;
;                     u32x4 wo; wo.x = cvt_pk_bf16(o0[0], o0[1]); wo.y = cvt_pk_bf16(o0[2], o0[3]); wo.z = cvt_pk_bf16(o1[0], o1[1]); wo.w = cvt_pk_bf16(o1[2], o1[3]);
;                     *(gs_u32x4*)(PG8_GPTR(out) + offb) = wo;
;                     if (xg) {
;                         const f32x4 h0 = o0 * cf[bj][0], h1 = o1 * cf[bj][1];
;                         u32x4 w; w.x = cvt_pk_bf16(h0[0], h0[1]); w.y = cvt_pk_bf16(h0[2], h0[3]); w.z = cvt_pk_bf16(h1[0], h1[1]); w.w = cvt_pk_bf16(h1[2], h1[3]);
;                         *(gs_u32x4*)(PG8_GPTR(xg) + offb) = w;
.LBB0_1274:
	v_add_u32_e32 v86, 0x40000, v240
	global_load_dwordx4 v[100:103], v86, s[20:21] nt
	global_load_dwordx4 v[94:97], v86, s[20:21] offset:1024 nt
	v_add_u32_e32 v86, 0x48000, v240
	global_load_dwordx4 v[90:93], v86, s[20:21] nt
	s_waitcnt lgkmcnt(0)
	global_load_dwordx4 v[86:89], v86, s[20:21] offset:1024 nt
	s_mov_b32 s2, 0x40000
	v_add3_u32 v98, v218, v217, s2
	v_add_u32_e32 v241, s2, v240
	v_add_u32_e32 v243, s2, v242
	v_mov_b32_e32 v99, v1
	s_and_b64 vcc, exec, s[8:9]
	s_waitcnt vmcnt(0)
	v_lshlrev_b32_e32 v104, 16, v100
	v_and_b32_e32 v105, 0xffff0000, v100
	v_lshlrev_b32_e32 v100, 16, v101
	v_and_b32_e32 v101, 0xffff0000, v101
	v_lshlrev_b32_e32 v106, 16, v102
	v_and_b32_e32 v107, 0xffff0000, v102
	v_lshlrev_b32_e32 v102, 16, v103
	v_and_b32_e32 v103, 0xffff0000, v103
	v_pk_fma_f32 v[84:85], v[84:85], v[76:77], v[100:101]
	v_pk_fma_f32 v[82:83], v[82:83], v[74:75], v[104:105]
	v_pk_fma_f32 v[80:81], v[80:81], v[72:73], v[102:103]
	v_cvt_pk_bf16_f32 v100, v82, v83
	v_cvt_pk_bf16_f32 v101, v84, v85
	v_pk_fma_f32 v[78:79], v[78:79], v[70:71], v[106:107]
	s_nop 0
	v_cvt_pk_bf16_f32 v102, v78, v79
	v_cvt_pk_bf16_f32 v103, v80, v81
	global_store_dwordx4 v241, v[100:103], s[22:23] nt
	s_nop 1
	v_lshl_add_u64 v[100:101], s[12:13], 0, v[98:99]
	s_cbranch_vccnz .LBB0_1276
	v_pk_mul_f32 v[102:103], v[212:213], v[82:83]
	v_pk_mul_f32 v[104:105], v[210:211], v[84:85]
	v_cvt_pk_bf16_f32 v102, v102, v103
	v_pk_mul_f32 v[84:85], v[84:85], v[84:85]
	v_cvt_pk_bf16_f32 v103, v104, v105
	v_pk_mul_f32 v[82:83], v[82:83], v[82:83]
	v_pk_mul_f32 v[106:107], v[206:207], v[80:81]
	v_pk_mul_f32 v[108:109], v[208:209], v[78:79]
	v_pk_mul_f32 v[80:81], v[80:81], v[80:81]
	v_cvt_pk_bf16_f32 v104, v108, v109
	v_cvt_pk_bf16_f32 v105, v106, v107
	global_store_dwordx4 v243, v[102:105], s[12:13] offset:-4096
	v_pk_mul_f32 v[78:79], v[78:79], v[78:79]
	s_nop 0
	v_mov_b32_e32 v102, v82
	v_mov_b32_e32 v103, v85
	v_pk_mov_b32 v[82:83], v[82:83], v[84:85] op_sel:[1,0]
	v_mov_b32_e32 v84, v80
	v_pk_add_f32 v[82:83], v[82:83], v[102:103]
	v_mov_b32_e32 v85, v78
	v_mov_b32_e32 v78, v81
	v_pk_add_f32 v[78:79], v[84:85], v[78:79]
	v_add_f32_e32 v80, v82, v83
	v_add_f32_e32 v79, v79, v80
	v_add_f32_e32 v78, v78, v79
	s_branch .LBB0_1277

; __device__ __forceinline__ unsigned cvt_pk_bf16(float lo, float hi) { unsigned r; asm volatile("v_cvt_pk_bf16_f32 %0, %1, %2" : "=v"(r) : "v"(lo), "v"(hi)); return r; }
; #define PG8_GPTR(p) ((__attribute__((address_space(1))) char*)(p))
;     __device__ __forceinline__ void operator()(const f32x4 (&acc)[2][2][4][2], const Unit& u, int wr, int wc, int fr, int fq) const {
;     ...
;             for (int mm = 0; mm < 2; ++mm) {
;                 const int m = mp + mm;
;                 const int row = u.pm * BM + ai * HALF + wr * 64 + m * 16 + fr; float q = 0.f;
; #pragma unroll
;                 for (int bj = 0; bj < 2; ++bj) {
;                     const unsigned offb = (unsigned)(row * DM + col0 + bj * HALF) * 2u;
;                     const u32x4 bw = bv[mm][bj];
;                     const f32x4 b0 = (f32x4){__uint_as_float(bw.x << 16), __uint_as_float(bw.x & 0xffff0000u), __uint_as_float(bw.y << 16), __uint_as_float(bw.y & 0xffff0000u)};
;                     const f32x4 b1 = (f32x4){__uint_as_float(bw.z << 16), __uint_as_float(bw.z & 0xffff0000u), __uint_as_float(bw.w << 16), __uint_as_float(bw.w & 0xffff0000u)};
;                     f32x4 a0 = acc[ai][bj][m][0], a1 = acc[ai][bj][m][1]; if constexpr (GN) { a0 *= rc[ai * 4 + m]; a1 *= rc[ai * 4 + m]; }
;                     const f32x4 o0 = b0 + g[bj][0] * a0, o1 = b1 + g[bj][1] * a1;
;                     u32x4 wo; wo.x = cvt_pk_bf16(o0[0], o0[1]); wo.y = cvt_pk_bf16(o0[2], o0[3]); wo.z = cvt_pk_bf16(o1[0], o1[1]); wo.w = cvt_pk_bf16(o1[2], o1[3]);
;                     *(gs_u32x4*)(PG8_GPTR(out) + offb) = wo;
;                     if (xg) {
;                         const f32x4 h0 = o0 * cf[bj][0], h1 = o1 * cf[bj][1];
;                         u32x4 w; w.x = cvt_pk_bf16(h0[0], h0[1]); w.y = cvt_pk_bf16(h0[2], h0[3]); w.z = cvt_pk_bf16(h1[0], h1[1]); w.w = cvt_pk_bf16(h1[2], h1[3]);
;                         *(gs_u32x4*)(PG8_GPTR(xg) + offb) = w;
;                         q += (o0[0] * o0[0] + o0[1] * o0[1]) + (o0[2] * o0[2] + o0[3] * o0[3]) + (o1[0] * o1[0] + o1[1] * o1[1]) + (o1[2] * o1[2] + o1[3] * o1[3]);
;                     }
;                 }
;                 if (xg) ssq_put(ssq, row, q, fr, fq);
.LBB0_1277:
	v_lshlrev_b32_e32 v80, 16, v94
	v_and_b32_e32 v81, 0xffff0000, v94
	v_lshlrev_b32_e32 v82, 16, v95
	v_and_b32_e32 v83, 0xffff0000, v95
	v_lshlrev_b32_e32 v94, 16, v96
	v_and_b32_e32 v95, 0xffff0000, v96
	v_lshlrev_b32_e32 v96, 16, v97
	v_and_b32_e32 v97, 0xffff0000, v97
	v_lshl_add_u64 v[84:85], s[22:23], 0, v[98:99]
	v_pk_fma_f32 v[60:61], v[60:61], v[68:69], v[82:83]
	v_pk_fma_f32 v[58:59], v[58:59], v[66:67], v[80:81]
	v_pk_fma_f32 v[56:57], v[56:57], v[64:65], v[96:97]
	v_pk_fma_f32 v[54:55], v[54:55], v[62:63], v[94:95]
	s_and_b64 vcc, exec, s[8:9]
	v_cvt_pk_bf16_f32 v80, v58, v59
	v_cvt_pk_bf16_f32 v81, v60, v61
	v_cvt_pk_bf16_f32 v82, v54, v55
	v_cvt_pk_bf16_f32 v83, v56, v57
	global_store_dwordx4 v241, v[80:83], s[22:23] offset:1024 nt
	s_cbranch_vccnz .LBB0_1281
	s_nop 0
	v_pk_mul_f32 v[80:81], v[148:149], v[60:61]
	v_mul_f32_e32 v83, v59, v59
	v_mul_f32_e32 v61, v61, v61
	v_mul_f32_e32 v82, v55, v55
	v_fmac_f32_e32 v83, v58, v58
	v_fmac_f32_e32 v61, v60, v60
	v_mul_f32_e32 v79, v57, v57
	v_fmac_f32_e32 v82, v54, v54
	v_add_f32_e32 v60, v83, v61
	v_fmac_f32_e32 v79, v56, v56
	v_add_f32_e32 v60, v82, v60
	v_add_f32_e32 v60, v79, v60
	v_add_f32_e32 v82, v60, v78
	ds_bpermute_b32 v83, v159, v82
	v_pk_mul_f32 v[78:79], v[146:147], v[54:55]
	v_pk_mul_f32 v[58:59], v[142:143], v[58:59]
	v_pk_mul_f32 v[60:61], v[144:145], v[56:57]
	v_cvt_pk_bf16_f32 v56, v58, v59
	s_waitcnt lgkmcnt(0)
	v_add_f32_e32 v54, v82, v83
	ds_bpermute_b32 v55, v158, v54
	v_cvt_pk_bf16_f32 v57, v80, v81
	v_cvt_pk_bf16_f32 v58, v78, v79
	v_cvt_pk_bf16_f32 v59, v60, v61
	global_store_dwordx4 v243, v[56:59], s[12:13]
	s_and_saveexec_b64 s[2:3], s[10:11]
	s_cbranch_execz .LBB0_1280
	s_waitcnt lgkmcnt(0)
	v_add_f32_e32 v54, v54, v55
	v_mul_f32_e32 v54, 0x4b800000, v54
	v_trunc_f32_e32 v54, v54
	v_mul_f32_e32 v55, 0x2f800000, v54
	v_floor_f32_e32 v55, v55
	v_fmac_f32_e32 v54, 0xcf800000, v55
	v_cvt_u32_f32_e32 v54, v54
	v_cvt_u32_f32_e32 v55, v55
	v_ashrrev_i32_e32 v205, 31, v204
	v_lshl_add_u64 v[56:57], v[204:205], 3, s[16:17]
	global_atomic_add_x2 v[56:57], v[54:55], off offset:1024

; __device__ __forceinline__ unsigned cvt_pk_bf16(float lo, float hi) { unsigned r; asm volatile("v_cvt_pk_bf16_f32 %0, %1, %2" : "=v"(r) : "v"(lo), "v"(hi)); return r; }
; #define PG8_GPTR(p) ((__attribute__((address_space(1))) char*)(p))
;     __device__ __forceinline__ void operator()(const f32x4 (&acc)[2][2][4][2], const Unit& u, int wr, int wc, int fr, int fq) const {
;     ...
;             for (int mm = 0; mm < 2; ++mm) {
;                 const int m = mp + mm;
;                 const int row = u.pm * BM + ai * HALF + wr * 64 + m * 16 + fr; float q = 0.f;
; #pragma unroll
;                 for (int bj = 0; bj < 2; ++bj) {
;                     const unsigned offb = (unsigned)(row * DM + col0 + bj * HALF) * 2u;
;                     const u32x4 bw = bv[mm][bj];
;                     const f32x4 b0 = (f32x4){__uint_as_float(bw.x << 16), __uint_as_float(bw.x & 0xffff0000u), __uint_as_float(bw.y << 16), __uint_as_float(bw.y & 0xffff0000u)};
;                     const f32x4 b1 = (f32x4){__uint_as_float(bw.z << 16), __uint_as_float(bw.z & 0xffff0000u), __uint_as_float(bw.w << 16), __uint_as_float(bw.w & 0xffff0000u)};
;                     f32x4 a0 = acc[ai][bj][m][0], a1 = acc[ai][bj][m][1]; if constexpr (GN) { a0 *= rc[ai * 4 + m]; a1 *= rc[ai * 4 + m]; }
;                     const f32x4 o0 = b0 + g[bj][0] * a0, o1 = b1 + g[bj][1] * a1;
;                     u32x4 wo; wo.x = cvt_pk_bf16(o0[0], o0[1]); wo.y = cvt_pk_bf16(o0[2], o0[3]); wo.z = cvt_pk_bf16(o1[0], o1[1]); wo.w = cvt_pk_bf16(o1[2], o1[3]);
;                     *(gs_u32x4*)(PG8_GPTR(out) + offb) = wo;
;                     if (xg) {
;                         const f32x4 h0 = o0 * cf[bj][0], h1 = o1 * cf[bj][1];
;                         u32x4 w; w.x = cvt_pk_bf16(h0[0], h0[1]); w.y = cvt_pk_bf16(h0[2], h0[3]); w.z = cvt_pk_bf16(h1[0], h1[1]); w.w = cvt_pk_bf16(h1[2], h1[3]);
;                         *(gs_u32x4*)(PG8_GPTR(xg) + offb) = w;
.LBB0_1281:
	s_mov_b32 s2, 0x48000
	v_add3_u32 v54, v218, v217, s2
	v_add_u32_e32 v241, s2, v240
	v_add_u32_e32 v243, s2, v242
	v_lshlrev_b32_e32 v56, 16, v90
	v_and_b32_e32 v57, 0xffff0000, v90
	v_lshlrev_b32_e32 v58, 16, v91
	v_and_b32_e32 v59, 0xffff0000, v91
	v_lshlrev_b32_e32 v60, 16, v92
	v_and_b32_e32 v61, 0xffff0000, v92
	v_lshlrev_b32_e32 v78, 16, v93
	v_and_b32_e32 v79, 0xffff0000, v93
	s_waitcnt lgkmcnt(0)
	v_mov_b32_e32 v55, v1
	v_pk_fma_f32 v[52:53], v[52:53], v[76:77], v[58:59]
	v_pk_fma_f32 v[50:51], v[50:51], v[74:75], v[56:57]
	v_pk_fma_f32 v[48:49], v[48:49], v[72:73], v[78:79]
	v_pk_fma_f32 v[56:57], v[46:47], v[70:71], v[60:61]
	s_and_b64 vcc, exec, s[8:9]
	v_lshl_add_u64 v[46:47], s[12:13], 0, v[54:55]
	v_cvt_pk_bf16_f32 v58, v50, v51
	v_cvt_pk_bf16_f32 v59, v52, v53
	v_cvt_pk_bf16_f32 v60, v56, v57
	v_cvt_pk_bf16_f32 v61, v48, v49
	global_store_dwordx4 v241, v[58:61], s[22:23] nt
	s_cbranch_vccnz .LBB0_1283
	s_nop 0
	v_pk_mul_f32 v[58:59], v[212:213], v[50:51]
	v_pk_mul_f32 v[60:61], v[210:211], v[52:53]
	v_cvt_pk_bf16_f32 v58, v58, v59
	v_pk_mul_f32 v[52:53], v[52:53], v[52:53]
	v_cvt_pk_bf16_f32 v59, v60, v61
	v_pk_mul_f32 v[50:51], v[50:51], v[50:51]
	v_pk_mul_f32 v[78:79], v[206:207], v[48:49]
	v_pk_mul_f32 v[80:81], v[208:209], v[56:57]
	v_pk_mul_f32 v[48:49], v[48:49], v[48:49]
	v_cvt_pk_bf16_f32 v60, v80, v81
	v_cvt_pk_bf16_f32 v61, v78, v79
	global_store_dwordx4 v243, v[58:61], s[12:13] offset:-4096
	s_nop 1
	v_mov_b32_e32 v58, v50
	v_mov_b32_e32 v59, v53
	v_pk_mov_b32 v[50:51], v[50:51], v[52:53] op_sel:[1,0]
	v_pk_mul_f32 v[52:53], v[56:57], v[56:57]
	v_pk_add_f32 v[50:51], v[50:51], v[58:59]
	v_mov_b32_e32 v56, v48
	v_mov_b32_e32 v57, v52
	v_mov_b32_e32 v52, v49
	v_pk_add_f32 v[48:49], v[56:57], v[52:53]
	v_add_f32_e32 v50, v50, v51
	v_add_f32_e32 v49, v49, v50
	v_add_f32_e32 v48, v48, v49
	s_branch .LBB0_1284

; __device__ __forceinline__ unsigned cvt_pk_bf16(float lo, float hi) { unsigned r; asm volatile("v_cvt_pk_bf16_f32 %0, %1, %2" : "=v"(r) : "v"(lo), "v"(hi)); return r; }
; #define PG8_GPTR(p) ((__attribute__((address_space(1))) char*)(p))
;     __device__ __forceinline__ void operator()(const f32x4 (&acc)[2][2][4][2], const Unit& u, int wr, int wc, int fr, int fq) const {
;     ...
;             for (int mm = 0; mm < 2; ++mm) {
;                 const int m = mp + mm;
;                 const int row = u.pm * BM + ai * HALF + wr * 64 + m * 16 + fr; float q = 0.f;
; #pragma unroll
;                 for (int bj = 0; bj < 2; ++bj) {
;                     const unsigned offb = (unsigned)(row * DM + col0 + bj * HALF) * 2u;
;                     const u32x4 bw = bv[mm][bj];
;                     const f32x4 b0 = (f32x4){__uint_as_float(bw.x << 16), __uint_as_float(bw.x & 0xffff0000u), __uint_as_float(bw.y << 16), __uint_as_float(bw.y & 0xffff0000u)};
;                     const f32x4 b1 = (f32x4){__uint_as_float(bw.z << 16), __uint_as_float(bw.z & 0xffff0000u), __uint_as_float(bw.w << 16), __uint_as_float(bw.w & 0xffff0000u)};
;                     f32x4 a0 = acc[ai][bj][m][0], a1 = acc[ai][bj][m][1]; if constexpr (GN) { a0 *= rc[ai * 4 + m]; a1 *= rc[ai * 4 + m]; }
;                     const f32x4 o0 = b0 + g[bj][0] * a0, o1 = b1 + g[bj][1] * a1;
;                     u32x4 wo; wo.x = cvt_pk_bf16(o0[0], o0[1]); wo.y = cvt_pk_bf16(o0[2], o0[3]); wo.z = cvt_pk_bf16(o1[0], o1[1]); wo.w = cvt_pk_bf16(o1[2], o1[3]);
;                     *(gs_u32x4*)(PG8_GPTR(out) + offb) = wo;
;                     if (xg) {
;                         const f32x4 h0 = o0 * cf[bj][0], h1 = o1 * cf[bj][1];
;                         u32x4 w; w.x = cvt_pk_bf16(h0[0], h0[1]); w.y = cvt_pk_bf16(h0[2], h0[3]); w.z = cvt_pk_bf16(h1[0], h1[1]); w.w = cvt_pk_bf16(h1[2], h1[3]);
;                         *(gs_u32x4*)(PG8_GPTR(xg) + offb) = w;
;                         q += (o0[0] * o0[0] + o0[1] * o0[1]) + (o0[2] * o0[2] + o0[3] * o0[3]) + (o1[0] * o1[0] + o1[1] * o1[1]) + (o1[2] * o1[2] + o1[3] * o1[3]);
;                     }
;                 }
;                 if (xg) ssq_put(ssq, row, q, fr, fq);
.LBB0_1284:
	v_lshlrev_b32_e32 v50, 16, v86
	v_and_b32_e32 v51, 0xffff0000, v86
	v_lshlrev_b32_e32 v52, 16, v87
	v_and_b32_e32 v53, 0xffff0000, v87
	v_lshlrev_b32_e32 v56, 16, v88
	v_and_b32_e32 v57, 0xffff0000, v88
	v_lshlrev_b32_e32 v58, 16, v89
	v_and_b32_e32 v59, 0xffff0000, v89
	v_lshl_add_u64 v[54:55], s[22:23], 0, v[54:55]
	v_pk_fma_f32 v[44:45], v[44:45], v[68:69], v[52:53]
	v_pk_fma_f32 v[42:43], v[42:43], v[66:67], v[50:51]
	v_pk_fma_f32 v[40:41], v[40:41], v[64:65], v[58:59]
	v_pk_fma_f32 v[38:39], v[38:39], v[62:63], v[56:57]
	s_and_b64 vcc, exec, s[8:9]
	v_cvt_pk_bf16_f32 v50, v42, v43
	v_cvt_pk_bf16_f32 v51, v44, v45
	v_cvt_pk_bf16_f32 v52, v38, v39
	v_cvt_pk_bf16_f32 v53, v40, v41
	global_store_dwordx4 v241, v[50:53], s[22:23] offset:1024 nt
	s_cbranch_vccnz .LBB0_1288
	s_nop 0
	v_pk_mul_f32 v[50:51], v[148:149], v[44:45]
	v_mul_f32_e32 v53, v43, v43
	v_mul_f32_e32 v45, v45, v45
	v_mul_f32_e32 v52, v39, v39
	v_fmac_f32_e32 v53, v42, v42
	v_fmac_f32_e32 v45, v44, v44
	v_mul_f32_e32 v49, v41, v41
	v_fmac_f32_e32 v52, v38, v38
	v_add_f32_e32 v44, v53, v45
	v_fmac_f32_e32 v49, v40, v40
	v_add_f32_e32 v44, v52, v44
	v_add_f32_e32 v44, v49, v44
	v_add_f32_e32 v52, v44, v48
	ds_bpermute_b32 v53, v159, v52
	v_pk_mul_f32 v[48:49], v[146:147], v[38:39]
	v_pk_mul_f32 v[42:43], v[142:143], v[42:43]
	v_pk_mul_f32 v[44:45], v[144:145], v[40:41]
	v_cvt_pk_bf16_f32 v40, v42, v43
	s_waitcnt lgkmcnt(0)
	v_add_f32_e32 v38, v52, v53
	ds_bpermute_b32 v39, v158, v38
	v_cvt_pk_bf16_f32 v41, v50, v51
	v_cvt_pk_bf16_f32 v42, v48, v49
	v_cvt_pk_bf16_f32 v43, v44, v45
	global_store_dwordx4 v243, v[40:43], s[12:13]
	s_and_saveexec_b64 s[2:3], s[10:11]
	s_cbranch_execz .LBB0_1287
	s_waitcnt lgkmcnt(0)
	v_add_f32_e32 v38, v38, v39
	v_mul_f32_e32 v38, 0x4b800000, v38
	v_trunc_f32_e32 v38, v38
	v_mul_f32_e32 v39, 0x2f800000, v38
	v_floor_f32_e32 v39, v39
	v_fmac_f32_e32 v38, 0xcf800000, v39
	v_cvt_u32_f32_e32 v38, v38
	v_cvt_u32_f32_e32 v39, v39
	v_ashrrev_i32_e32 v205, 31, v204
	v_lshl_add_u64 v[40:41], v[204:205], 3, s[16:17]
	global_atomic_add_x2 v[40:41], v[38:39], off offset:1152

; __device__ __forceinline__ unsigned cvt_pk_bf16(float lo, float hi) { unsigned r; asm volatile("v_cvt_pk_bf16_f32 %0, %1, %2" : "=v"(r) : "v"(lo), "v"(hi)); return r; }
; #define PG8_GPTR(p) ((__attribute__((address_space(1))) char*)(p))
; #define PG8_GCPTR(p) ((__attribute__((address_space(1))) const char*)(p))
;     __device__ __forceinline__ void operator()(const f32x4 (&acc)[2][2][4][2], const Unit& u, int wr, int wc, int fr, int fq) const {
;     ...
;                     bv[mm][bj] = *(gl_u32x4*)(PG8_GCPTR(base) + (unsigned)((u.pm * BM + ai * HALF + wr * 64 + (mp + mm) * 16 + fr) * DM + col0 + bj * HALF) * 2u);
; #pragma unroll
;             for (int mm = 0; mm < 2; ++mm) {
;                 const int m = mp + mm;
;                 const int row = u.pm * BM + ai * HALF + wr * 64 + m * 16 + fr; float q = 0.f;
; #pragma unroll
;                 for (int bj = 0; bj < 2; ++bj) {
;                     const unsigned offb = (unsigned)(row * DM + col0 + bj * HALF) * 2u;
;                     const u32x4 bw = bv[mm][bj];
;                     const f32x4 b0 = (f32x4){__uint_as_float(bw.x << 16), __uint_as_float(bw.x & 0xffff0000u), __uint_as_float(bw.y << 16), __uint_as_float(bw.y & 0xffff0000u)};
;                     const f32x4 b1 = (f32x4){__uint_as_float(bw.z << 16), __uint_as_float(bw.z & 0xffff0000u), __uint_as_float(bw.w << 16), __uint_as_float(bw.w & 0xffff0000u)};
;                     f32x4 a0 = acc[ai][bj][m][0], a1 = acc[ai][bj][m][1]; if constexpr (GN) { a0 *= rc[ai * 4 + m]; a1 *= rc[ai * 4 + m]; }
;                     const f32x4 o0 = b0 + g[bj][0] * a0, o1 = b1 + g[bj][1] * a1;
;                     u32x4 wo; wo.x = cvt_pk_bf16(o0[0], o0[1]); wo.y = cvt_pk_bf16(o0[2], o0[3]); wo.z = cvt_pk_bf16(o1[0], o1[1]); wo.w = cvt_pk_bf16(o1[2], o1[3]);
;                     *(gs_u32x4*)(PG8_GPTR(out) + offb) = wo;
;                     if (xg) {
;                         const f32x4 h0 = o0 * cf[bj][0], h1 = o1 * cf[bj][1];
;                         u32x4 w; w.x = cvt_pk_bf16(h0[0], h0[1]); w.y = cvt_pk_bf16(h0[2], h0[3]); w.z = cvt_pk_bf16(h1[0], h1[1]); w.w = cvt_pk_bf16(h1[2], h1[3]);
;                         *(gs_u32x4*)(PG8_GPTR(xg) + offb) = w;
.LBB0_1288:
	v_add_u32_e32 v38, 0x50000, v240
	global_load_dwordx4 v[50:53], v38, s[20:21] nt
	v_add_u32_e32 v0, 0x58000, v240
	global_load_dwordx4 v[46:49], v38, s[20:21] offset:1024 nt
	global_load_dwordx4 v[42:45], v0, s[20:21] nt
	s_waitcnt lgkmcnt(0)
	global_load_dwordx4 v[38:41], v0, s[20:21] offset:1024 nt
	s_mov_b32 s2, 0x50000
	v_add3_u32 v0, v218, v217, s2
	v_add_u32_e32 v241, s2, v240
	v_add_u32_e32 v243, s2, v242
	s_and_b64 vcc, exec, s[8:9]
	s_waitcnt vmcnt(0)
	v_lshlrev_b32_e32 v54, 16, v50
	v_and_b32_e32 v55, 0xffff0000, v50
	v_lshlrev_b32_e32 v50, 16, v51
	v_and_b32_e32 v51, 0xffff0000, v51
	v_lshlrev_b32_e32 v56, 16, v52
	v_and_b32_e32 v57, 0xffff0000, v52
	v_lshlrev_b32_e32 v52, 16, v53
	v_and_b32_e32 v53, 0xffff0000, v53
	v_pk_fma_f32 v[36:37], v[36:37], v[76:77], v[50:51]
	v_pk_fma_f32 v[50:51], v[34:35], v[74:75], v[54:55]
	v_pk_fma_f32 v[32:33], v[32:33], v[72:73], v[52:53]
	v_pk_fma_f32 v[34:35], v[30:31], v[70:71], v[56:57]
	v_lshl_add_u64 v[30:31], s[12:13], 0, v[0:1]
	v_cvt_pk_bf16_f32 v52, v50, v51
	v_cvt_pk_bf16_f32 v53, v36, v37
	v_cvt_pk_bf16_f32 v54, v34, v35
	v_cvt_pk_bf16_f32 v55, v32, v33
	global_store_dwordx4 v241, v[52:55], s[22:23] nt
	s_cbranch_vccnz .LBB0_1290
	s_nop 0
	v_pk_mul_f32 v[52:53], v[212:213], v[50:51]
	v_pk_mul_f32 v[54:55], v[210:211], v[36:37]
	v_cvt_pk_bf16_f32 v52, v52, v53
	v_pk_mul_f32 v[36:37], v[36:37], v[36:37]
	v_cvt_pk_bf16_f32 v53, v54, v55
	v_pk_mul_f32 v[50:51], v[50:51], v[50:51]
	v_pk_mul_f32 v[56:57], v[206:207], v[32:33]
	v_pk_mul_f32 v[58:59], v[208:209], v[34:35]
	v_pk_mul_f32 v[32:33], v[32:33], v[32:33]
	v_cvt_pk_bf16_f32 v54, v58, v59
	v_cvt_pk_bf16_f32 v55, v56, v57
	global_store_dwordx4 v243, v[52:55], s[12:13] offset:-4096
	v_pk_mul_f32 v[34:35], v[34:35], v[34:35]
	s_nop 0
	v_mov_b32_e32 v52, v50
	v_mov_b32_e32 v53, v37
	v_pk_mov_b32 v[36:37], v[50:51], v[36:37] op_sel:[1,0]
	v_mov_b32_e32 v50, v32
	v_pk_add_f32 v[36:37], v[36:37], v[52:53]
	v_mov_b32_e32 v51, v34
	v_mov_b32_e32 v34, v33
	v_pk_add_f32 v[32:33], v[50:51], v[34:35]
	v_add_f32_e32 v34, v36, v37
	v_add_f32_e32 v33, v33, v34
	v_add_f32_e32 v32, v32, v33
	s_branch .LBB0_1291

; __device__ __forceinline__ unsigned cvt_pk_bf16(float lo, float hi) { unsigned r; asm volatile("v_cvt_pk_bf16_f32 %0, %1, %2" : "=v"(r) : "v"(lo), "v"(hi)); return r; }
; #define PG8_GPTR(p) ((__attribute__((address_space(1))) char*)(p))
;     __device__ __forceinline__ void operator()(const f32x4 (&acc)[2][2][4][2], const Unit& u, int wr, int wc, int fr, int fq) const {
;     ...
;             for (int mm = 0; mm < 2; ++mm) {
;                 const int m = mp + mm;
;                 const int row = u.pm * BM + ai * HALF + wr * 64 + m * 16 + fr; float q = 0.f;
; #pragma unroll
;                 for (int bj = 0; bj < 2; ++bj) {
;                     const unsigned offb = (unsigned)(row * DM + col0 + bj * HALF) * 2u;
;                     const u32x4 bw = bv[mm][bj];
;                     const f32x4 b0 = (f32x4){__uint_as_float(bw.x << 16), __uint_as_float(bw.x & 0xffff0000u), __uint_as_float(bw.y << 16), __uint_as_float(bw.y & 0xffff0000u)};
;                     const f32x4 b1 = (f32x4){__uint_as_float(bw.z << 16), __uint_as_float(bw.z & 0xffff0000u), __uint_as_float(bw.w << 16), __uint_as_float(bw.w & 0xffff0000u)};
;                     f32x4 a0 = acc[ai][bj][m][0], a1 = acc[ai][bj][m][1]; if constexpr (GN) { a0 *= rc[ai * 4 + m]; a1 *= rc[ai * 4 + m]; }
;                     const f32x4 o0 = b0 + g[bj][0] * a0, o1 = b1 + g[bj][1] * a1;
;                     u32x4 wo; wo.x = cvt_pk_bf16(o0[0], o0[1]); wo.y = cvt_pk_bf16(o0[2], o0[3]); wo.z = cvt_pk_bf16(o1[0], o1[1]); wo.w = cvt_pk_bf16(o1[2], o1[3]);
;                     *(gs_u32x4*)(PG8_GPTR(out) + offb) = wo;
;                     if (xg) {
;                         const f32x4 h0 = o0 * cf[bj][0], h1 = o1 * cf[bj][1];
;                         u32x4 w; w.x = cvt_pk_bf16(h0[0], h0[1]); w.y = cvt_pk_bf16(h0[2], h0[3]); w.z = cvt_pk_bf16(h1[0], h1[1]); w.w = cvt_pk_bf16(h1[2], h1[3]);
;                         *(gs_u32x4*)(PG8_GPTR(xg) + offb) = w;
;                         q += (o0[0] * o0[0] + o0[1] * o0[1]) + (o0[2] * o0[2] + o0[3] * o0[3]) + (o1[0] * o1[0] + o1[1] * o1[1]) + (o1[2] * o1[2] + o1[3] * o1[3]);
;                     }
;                 }
;                 if (xg) ssq_put(ssq, row, q, fr, fq);
.LBB0_1291:
	v_lshlrev_b32_e32 v34, 16, v46
	v_and_b32_e32 v35, 0xffff0000, v46
	v_lshlrev_b32_e32 v36, 16, v47
	v_and_b32_e32 v37, 0xffff0000, v47
	v_lshlrev_b32_e32 v46, 16, v48
	v_and_b32_e32 v47, 0xffff0000, v48
	v_lshlrev_b32_e32 v48, 16, v49
	v_and_b32_e32 v49, 0xffff0000, v49
	v_lshl_add_u64 v[50:51], s[22:23], 0, v[0:1]
	v_pk_fma_f32 v[28:29], v[28:29], v[68:69], v[36:37]
	v_pk_fma_f32 v[26:27], v[26:27], v[66:67], v[34:35]
	v_pk_fma_f32 v[24:25], v[24:25], v[64:65], v[48:49]
	v_pk_fma_f32 v[22:23], v[22:23], v[62:63], v[46:47]
	s_and_b64 vcc, exec, s[8:9]
	v_cvt_pk_bf16_f32 v34, v26, v27
	v_cvt_pk_bf16_f32 v35, v28, v29
	v_cvt_pk_bf16_f32 v36, v22, v23
	v_cvt_pk_bf16_f32 v37, v24, v25
	global_store_dwordx4 v241, v[34:37], s[22:23] offset:1024 nt
	s_cbranch_vccnz .LBB0_1295
	s_nop 0
	v_pk_mul_f32 v[34:35], v[148:149], v[28:29]
	v_mul_f32_e32 v36, v27, v27
	v_mul_f32_e32 v29, v29, v29
	v_mul_f32_e32 v33, v23, v23
	v_fmac_f32_e32 v36, v26, v26
	v_fmac_f32_e32 v29, v28, v28
	v_mul_f32_e32 v0, v25, v25
	v_fmac_f32_e32 v33, v22, v22
	v_add_f32_e32 v28, v36, v29
	v_fmac_f32_e32 v0, v24, v24
	v_add_f32_e32 v28, v33, v28
	v_add_f32_e32 v0, v0, v28
	v_add_f32_e32 v0, v0, v32
	ds_bpermute_b32 v36, v159, v0
	v_pk_mul_f32 v[32:33], v[146:147], v[22:23]
	v_pk_mul_f32 v[26:27], v[142:143], v[26:27]
	v_pk_mul_f32 v[28:29], v[144:145], v[24:25]
	v_cvt_pk_bf16_f32 v24, v26, v27
	s_waitcnt lgkmcnt(0)
	v_add_f32_e32 v0, v0, v36
	ds_bpermute_b32 v22, v158, v0
	v_cvt_pk_bf16_f32 v25, v34, v35
	v_cvt_pk_bf16_f32 v26, v32, v33
	v_cvt_pk_bf16_f32 v27, v28, v29
	global_store_dwordx4 v243, v[24:27], s[12:13]
	s_and_saveexec_b64 s[2:3], s[10:11]
	s_cbranch_execz .LBB0_1294
	s_waitcnt lgkmcnt(0)
	v_add_f32_e32 v0, v0, v22
	v_mul_f32_e32 v0, 0x4b800000, v0
	v_trunc_f32_e32 v0, v0
	v_mul_f32_e32 v22, 0x2f800000, v0
	v_floor_f32_e32 v23, v22
	v_fmac_f32_e32 v0, 0xcf800000, v23
	v_cvt_u32_f32_e32 v22, v0
	v_cvt_u32_f32_e32 v23, v23
	v_ashrrev_i32_e32 v205, 31, v204
	v_lshl_add_u64 v[24:25], v[204:205], 3, s[16:17]
	global_atomic_add_x2 v[24:25], v[22:23], off offset:1280

; __device__ __forceinline__ unsigned cvt_pk_bf16(float lo, float hi) { unsigned r; asm volatile("v_cvt_pk_bf16_f32 %0, %1, %2" : "=v"(r) : "v"(lo), "v"(hi)); return r; }
; #define PG8_GPTR(p) ((__attribute__((address_space(1))) char*)(p))
;     __device__ __forceinline__ void operator()(const f32x4 (&acc)[2][2][4][2], const Unit& u, int wr, int wc, int fr, int fq) const {
;     ...
;             for (int mm = 0; mm < 2; ++mm) {
;                 const int m = mp + mm;
;                 const int row = u.pm * BM + ai * HALF + wr * 64 + m * 16 + fr; float q = 0.f;
; #pragma unroll
;                 for (int bj = 0; bj < 2; ++bj) {
;                     const unsigned offb = (unsigned)(row * DM + col0 + bj * HALF) * 2u;
;                     const u32x4 bw = bv[mm][bj];
;                     const f32x4 b0 = (f32x4){__uint_as_float(bw.x << 16), __uint_as_float(bw.x & 0xffff0000u), __uint_as_float(bw.y << 16), __uint_as_float(bw.y & 0xffff0000u)};
;                     const f32x4 b1 = (f32x4){__uint_as_float(bw.z << 16), __uint_as_float(bw.z & 0xffff0000u), __uint_as_float(bw.w << 16), __uint_as_float(bw.w & 0xffff0000u)};
;                     f32x4 a0 = acc[ai][bj][m][0], a1 = acc[ai][bj][m][1]; if constexpr (GN) { a0 *= rc[ai * 4 + m]; a1 *= rc[ai * 4 + m]; }
;                     const f32x4 o0 = b0 + g[bj][0] * a0, o1 = b1 + g[bj][1] * a1;
;                     u32x4 wo; wo.x = cvt_pk_bf16(o0[0], o0[1]); wo.y = cvt_pk_bf16(o0[2], o0[3]); wo.z = cvt_pk_bf16(o1[0], o1[1]); wo.w = cvt_pk_bf16(o1[2], o1[3]);
;                     *(gs_u32x4*)(PG8_GPTR(out) + offb) = wo;
;                     if (xg) {
;                         const f32x4 h0 = o0 * cf[bj][0], h1 = o1 * cf[bj][1];
;                         u32x4 w; w.x = cvt_pk_bf16(h0[0], h0[1]); w.y = cvt_pk_bf16(h0[2], h0[3]); w.z = cvt_pk_bf16(h1[0], h1[1]); w.w = cvt_pk_bf16(h1[2], h1[3]);
;                         *(gs_u32x4*)(PG8_GPTR(xg) + offb) = w;
.LBB0_1295:
	s_mov_b32 s2, 0x58000
	v_add3_u32 v0, v218, v217, s2
	v_add_u32_e32 v241, s2, v240
	v_add_u32_e32 v243, s2, v242
	s_waitcnt lgkmcnt(0)
	v_lshlrev_b32_e32 v22, 16, v42
	v_and_b32_e32 v23, 0xffff0000, v42
	v_lshlrev_b32_e32 v24, 16, v43
	v_and_b32_e32 v25, 0xffff0000, v43
	v_lshlrev_b32_e32 v26, 16, v44
	v_and_b32_e32 v27, 0xffff0000, v44
	v_lshlrev_b32_e32 v28, 16, v45
	v_and_b32_e32 v29, 0xffff0000, v45
	v_pk_fma_f32 v[20:21], v[20:21], v[76:77], v[24:25]
	v_pk_fma_f32 v[18:19], v[18:19], v[74:75], v[22:23]
	v_pk_fma_f32 v[12:13], v[12:13], v[72:73], v[28:29]
	v_pk_fma_f32 v[22:23], v[10:11], v[70:71], v[26:27]
	s_and_b64 vcc, exec, s[8:9]
	v_lshl_add_u64 v[10:11], s[12:13], 0, v[0:1]
	v_cvt_pk_bf16_f32 v24, v18, v19
	v_cvt_pk_bf16_f32 v25, v20, v21
	v_cvt_pk_bf16_f32 v26, v22, v23
	v_cvt_pk_bf16_f32 v27, v12, v13
	global_store_dwordx4 v241, v[24:27], s[22:23] nt
	s_cbranch_vccnz .LBB0_1297
	s_nop 0
	v_pk_mul_f32 v[24:25], v[212:213], v[18:19]
	v_pk_mul_f32 v[26:27], v[210:211], v[20:21]
	v_cvt_pk_bf16_f32 v24, v24, v25
	v_pk_mul_f32 v[20:21], v[20:21], v[20:21]
	v_cvt_pk_bf16_f32 v25, v26, v27
	v_pk_mul_f32 v[18:19], v[18:19], v[18:19]
	v_pk_mul_f32 v[28:29], v[206:207], v[12:13]
	v_pk_mul_f32 v[30:31], v[208:209], v[22:23]
	v_pk_mul_f32 v[12:13], v[12:13], v[12:13]
	v_cvt_pk_bf16_f32 v26, v30, v31
	v_cvt_pk_bf16_f32 v27, v28, v29
	global_store_dwordx4 v243, v[24:27], s[12:13] offset:-4096
	s_nop 1
	v_mov_b32_e32 v24, v18
	v_mov_b32_e32 v25, v21
	v_pk_mov_b32 v[18:19], v[18:19], v[20:21] op_sel:[1,0]
	v_pk_mul_f32 v[20:21], v[22:23], v[22:23]
	v_pk_add_f32 v[18:19], v[18:19], v[24:25]
	v_mov_b32_e32 v22, v12
	v_mov_b32_e32 v23, v20
	v_mov_b32_e32 v20, v13
	v_pk_add_f32 v[12:13], v[22:23], v[20:21]
	v_add_f32_e32 v18, v18, v19
	v_add_f32_e32 v13, v13, v18
	v_add_f32_e32 v12, v12, v13
	s_branch .LBB0_1298

; __device__ __forceinline__ unsigned cvt_pk_bf16(float lo, float hi) { unsigned r; asm volatile("v_cvt_pk_bf16_f32 %0, %1, %2" : "=v"(r) : "v"(lo), "v"(hi)); return r; }
; #define PG8_GPTR(p) ((__attribute__((address_space(1))) char*)(p))
;     __device__ __forceinline__ void operator()(const f32x4 (&acc)[2][2][4][2], const Unit& u, int wr, int wc, int fr, int fq) const {
;     ...
;             for (int mm = 0; mm < 2; ++mm) {
;                 const int m = mp + mm;
;                 const int row = u.pm * BM + ai * HALF + wr * 64 + m * 16 + fr; float q = 0.f;
; #pragma unroll
;                 for (int bj = 0; bj < 2; ++bj) {
;                     const unsigned offb = (unsigned)(row * DM + col0 + bj * HALF) * 2u;
;                     const u32x4 bw = bv[mm][bj];
;                     const f32x4 b0 = (f32x4){__uint_as_float(bw.x << 16), __uint_as_float(bw.x & 0xffff0000u), __uint_as_float(bw.y << 16), __uint_as_float(bw.y & 0xffff0000u)};
;                     const f32x4 b1 = (f32x4){__uint_as_float(bw.z << 16), __uint_as_float(bw.z & 0xffff0000u), __uint_as_float(bw.w << 16), __uint_as_float(bw.w & 0xffff0000u)};
;                     f32x4 a0 = acc[ai][bj][m][0], a1 = acc[ai][bj][m][1]; if constexpr (GN) { a0 *= rc[ai * 4 + m]; a1 *= rc[ai * 4 + m]; }
;                     const f32x4 o0 = b0 + g[bj][0] * a0, o1 = b1 + g[bj][1] * a1;
;                     u32x4 wo; wo.x = cvt_pk_bf16(o0[0], o0[1]); wo.y = cvt_pk_bf16(o0[2], o0[3]); wo.z = cvt_pk_bf16(o1[0], o1[1]); wo.w = cvt_pk_bf16(o1[2], o1[3]);
;                     *(gs_u32x4*)(PG8_GPTR(out) + offb) = wo;
;                     if (xg) {
;                         const f32x4 h0 = o0 * cf[bj][0], h1 = o1 * cf[bj][1];
;                         u32x4 w; w.x = cvt_pk_bf16(h0[0], h0[1]); w.y = cvt_pk_bf16(h0[2], h0[3]); w.z = cvt_pk_bf16(h1[0], h1[1]); w.w = cvt_pk_bf16(h1[2], h1[3]);
;                         *(gs_u32x4*)(PG8_GPTR(xg) + offb) = w;
;                         q += (o0[0] * o0[0] + o0[1] * o0[1]) + (o0[2] * o0[2] + o0[3] * o0[3]) + (o1[0] * o1[0] + o1[1] * o1[1]) + (o1[2] * o1[2] + o1[3] * o1[3]);
;                     }
;                 }
;                 if (xg) ssq_put(ssq, row, q, fr, fq);
.LBB0_1298:
	v_lshlrev_b32_e32 v18, 16, v38
	v_and_b32_e32 v19, 0xffff0000, v38
	v_lshlrev_b32_e32 v20, 16, v39
	v_and_b32_e32 v21, 0xffff0000, v39
	v_lshlrev_b32_e32 v24, 16, v40
	v_and_b32_e32 v25, 0xffff0000, v40
	v_lshlrev_b32_e32 v26, 16, v41
	v_and_b32_e32 v27, 0xffff0000, v41
	v_lshl_add_u64 v[22:23], s[22:23], 0, v[0:1]
	v_pk_fma_f32 v[8:9], v[8:9], v[68:69], v[20:21]
	v_pk_fma_f32 v[6:7], v[6:7], v[66:67], v[18:19]
	v_pk_fma_f32 v[4:5], v[4:5], v[64:65], v[26:27]
	v_pk_fma_f32 v[2:3], v[2:3], v[62:63], v[24:25]
	s_and_b64 vcc, exec, s[8:9]
	v_cvt_pk_bf16_f32 v18, v6, v7
	v_cvt_pk_bf16_f32 v19, v8, v9
	v_cvt_pk_bf16_f32 v20, v2, v3
	v_cvt_pk_bf16_f32 v21, v4, v5
	global_store_dwordx4 v241, v[18:21], s[22:23] offset:1024 nt
	s_cbranch_vccnz .LBB0_1302
	s_nop 0
	v_pk_mul_f32 v[18:19], v[148:149], v[8:9]
	v_mul_f32_e32 v20, v7, v7
	v_mul_f32_e32 v9, v9, v9
	v_mul_f32_e32 v13, v3, v3
	v_fmac_f32_e32 v20, v6, v6
	v_fmac_f32_e32 v9, v8, v8
	v_mul_f32_e32 v0, v5, v5
	v_fmac_f32_e32 v13, v2, v2
	v_add_f32_e32 v8, v20, v9
	v_fmac_f32_e32 v0, v4, v4
	v_add_f32_e32 v8, v13, v8
	v_add_f32_e32 v0, v0, v8
	v_add_f32_e32 v0, v0, v12
	ds_bpermute_b32 v20, v159, v0
	v_pk_mul_f32 v[12:13], v[146:147], v[2:3]
	v_pk_mul_f32 v[6:7], v[142:143], v[6:7]
	v_pk_mul_f32 v[8:9], v[144:145], v[4:5]
	v_cvt_pk_bf16_f32 v4, v6, v7
	s_waitcnt lgkmcnt(0)
	v_add_f32_e32 v0, v0, v20
	ds_bpermute_b32 v2, v158, v0
	v_cvt_pk_bf16_f32 v5, v18, v19
	v_cvt_pk_bf16_f32 v6, v12, v13
	v_cvt_pk_bf16_f32 v7, v8, v9
	global_store_dwordx4 v243, v[4:7], s[12:13]
	s_and_saveexec_b64 s[2:3], s[10:11]
	s_cbranch_execz .LBB0_1301
	s_waitcnt lgkmcnt(0)
	v_add_f32_e32 v0, v0, v2
	v_mul_f32_e32 v0, 0x4b800000, v0
	v_trunc_f32_e32 v0, v0
	v_mul_f32_e32 v2, 0x2f800000, v0
	v_floor_f32_e32 v3, v2
	v_fmac_f32_e32 v0, 0xcf800000, v3
	v_cvt_u32_f32_e32 v2, v0
	v_cvt_u32_f32_e32 v3, v3
	v_ashrrev_i32_e32 v205, 31, v204
	v_lshl_add_u64 v[4:5], v[204:205], 3, s[16:17]
	global_atomic_add_x2 v[4:5], v[2:3], off offset:1408
